# pool mixer tile body rewritten by hand (all row loads issued up front, window rows kept in registers, same arithmetic order); AQKV V^T epilogue staged through wave-private LDS with dwordx4 row stores
# speedup vs baseline: 1.0286x; 1.0037x over previous
.LBB0_1218:
	s_lshl_b32 s0, s12, 5
	s_and_b32 s14, s0, 0xfe0
	s_barrier
	v_readfirstlane_b32 s26, v12
	v_readlane_b32 s22, v250, 9
	v_readlane_b32 s23, v250, 10
	v_lshlrev_b32_e32 v220, 4, v214
	s_add_i32 s28, s13, s26
	s_sub_i32 s28, s28, 15
	s_ashr_i32 s29, s28, 31
	s_lshl_b64 s[24:25], s[28:29], 12
	s_add_u32 s24, s22, s24
	s_addc_u32 s25, s23, s25
	v_xor_b32_e32 v244, 32, v214
	v_lshlrev_b32_e32 v244, 2, v244
	v_xor_b32_e32 v245, 16, v214
	v_lshlrev_b32_e32 v245, 2, v245
	v_xor_b32_e32 v246, 8, v214
	v_lshlrev_b32_e32 v246, 2, v246
	v_xor_b32_e32 v247, 4, v214
	v_lshlrev_b32_e32 v247, 2, v247
	v_xor_b32_e32 v248, 2, v214
	v_lshlrev_b32_e32 v248, 2, v248
	v_xor_b32_e32 v249, 1, v214
	v_lshlrev_b32_e32 v249, 2, v249
	s_add_i32 s36, s28, 0
	s_cmp_lt_i32 s36, 0
	s_cbranch_scc1 .Lpool_p1skip_0
	global_load_dwordx4 v[20:23], v220, s[24:25] offset:0
	global_load_dwordx4 v[24:27], v220, s[24:25] offset:1024
	global_load_dwordx4 v[28:31], v220, s[24:25] offset:2048
	global_load_dwordx4 v[32:35], v220, s[24:25] offset:3072
.Lpool_p1skip_0:
	s_add_u32 s24, s24, 0x4000
	s_addc_u32 s25, s25, 0
	s_add_i32 s36, s28, 4
	s_cmp_lt_i32 s36, 0
	s_cbranch_scc1 .Lpool_p1skip_1
	global_load_dwordx4 v[36:39], v220, s[24:25] offset:0
	global_load_dwordx4 v[40:43], v220, s[24:25] offset:1024
	global_load_dwordx4 v[44:47], v220, s[24:25] offset:2048
	global_load_dwordx4 v[48:51], v220, s[24:25] offset:3072
.Lpool_p1skip_1:
	s_add_u32 s24, s24, 0x4000
	s_addc_u32 s25, s25, 0
	s_add_i32 s36, s28, 8
	s_cmp_lt_i32 s36, 0
	s_cbranch_scc1 .Lpool_p1skip_2
	global_load_dwordx4 v[52:55], v220, s[24:25] offset:0
	global_load_dwordx4 v[56:59], v220, s[24:25] offset:1024
	global_load_dwordx4 v[60:63], v220, s[24:25] offset:2048
	global_load_dwordx4 v[64:67], v220, s[24:25] offset:3072
.Lpool_p1skip_2:
	s_add_u32 s24, s24, 0x4000
	s_addc_u32 s25, s25, 0
	s_add_i32 s36, s28, 12
	s_cmp_lt_i32 s36, 0
	s_cbranch_scc1 .Lpool_p1skip_3
	global_load_dwordx4 v[68:71], v220, s[24:25] offset:0
	global_load_dwordx4 v[72:75], v220, s[24:25] offset:1024
	global_load_dwordx4 v[76:79], v220, s[24:25] offset:2048
	global_load_dwordx4 v[80:83], v220, s[24:25] offset:3072
.Lpool_p1skip_3:
	s_add_u32 s24, s24, 0x4000
	s_addc_u32 s25, s25, 0
	s_add_i32 s36, s28, 16
	s_cmp_lt_i32 s36, 0
	s_cbranch_scc1 .Lpool_p1skip_4
	global_load_dwordx4 v[84:87], v220, s[24:25] offset:0
	global_load_dwordx4 v[88:91], v220, s[24:25] offset:1024
	global_load_dwordx4 v[92:95], v220, s[24:25] offset:2048
	global_load_dwordx4 v[96:99], v220, s[24:25] offset:3072
.Lpool_p1skip_4:
	s_add_u32 s24, s24, 0x4000
	s_addc_u32 s25, s25, 0
	s_add_i32 s36, s28, 20
	s_cmp_lt_i32 s36, 0
	s_cbranch_scc1 .Lpool_p1skip_5
	global_load_dwordx4 v[100:103], v220, s[24:25] offset:0
	global_load_dwordx4 v[104:107], v220, s[24:25] offset:1024
	global_load_dwordx4 v[108:111], v220, s[24:25] offset:2048
	global_load_dwordx4 v[112:115], v220, s[24:25] offset:3072
.Lpool_p1skip_5:
	s_add_u32 s24, s24, 0x4000
	s_addc_u32 s25, s25, 0
	s_add_i32 s36, s28, 24
	s_cmp_lt_i32 s36, 0
	s_cbranch_scc1 .Lpool_p1skip_6
	global_load_dwordx4 v[116:119], v220, s[24:25] offset:0
	global_load_dwordx4 v[120:123], v220, s[24:25] offset:1024
	global_load_dwordx4 v[124:127], v220, s[24:25] offset:2048
	global_load_dwordx4 v[128:131], v220, s[24:25] offset:3072
.Lpool_p1skip_6:
	s_add_u32 s24, s24, 0x4000
	s_addc_u32 s25, s25, 0
	s_add_i32 s36, s28, 28
	s_cmp_lt_i32 s36, 0
	s_cbranch_scc1 .Lpool_p1skip_7
	global_load_dwordx4 v[132:135], v220, s[24:25] offset:0
	global_load_dwordx4 v[136:139], v220, s[24:25] offset:1024
	global_load_dwordx4 v[140:143], v220, s[24:25] offset:2048
	global_load_dwordx4 v[144:147], v220, s[24:25] offset:3072
.Lpool_p1skip_7:
	s_add_u32 s24, s24, 0x4000
	s_addc_u32 s25, s25, 0
	s_add_i32 s36, s28, 32
	s_cmp_lt_i32 s36, 0
	s_cbranch_scc1 .Lpool_p1skip_8
	global_load_dwordx4 v[148:151], v220, s[24:25] offset:0
	global_load_dwordx4 v[152:155], v220, s[24:25] offset:1024
	global_load_dwordx4 v[156:159], v220, s[24:25] offset:2048
	global_load_dwordx4 v[160:163], v220, s[24:25] offset:3072
.Lpool_p1skip_8:
	s_add_u32 s24, s24, 0x4000
	s_addc_u32 s25, s25, 0
	s_add_i32 s36, s28, 36
	s_cmp_lt_i32 s36, 0
	s_cbranch_scc1 .Lpool_p1skip_9
	global_load_dwordx4 v[164:167], v220, s[24:25] offset:0
	global_load_dwordx4 v[168:171], v220, s[24:25] offset:1024
	global_load_dwordx4 v[172:175], v220, s[24:25] offset:2048
	global_load_dwordx4 v[176:179], v220, s[24:25] offset:3072
.Lpool_p1skip_9:
	s_add_u32 s24, s24, 0x4000
	s_addc_u32 s25, s25, 0
	s_add_i32 s36, s28, 40
	s_cmp_lt_i32 s36, 0
	s_cbranch_scc1 .Lpool_p1skip_10
	global_load_dwordx4 v[180:183], v220, s[24:25] offset:0
	global_load_dwordx4 v[184:187], v220, s[24:25] offset:1024
	global_load_dwordx4 v[188:191], v220, s[24:25] offset:2048
	global_load_dwordx4 v[192:195], v220, s[24:25] offset:3072
.Lpool_p1skip_10:
	s_add_u32 s24, s24, 0x4000
	s_addc_u32 s25, s25, 0
	s_add_i32 s36, s28, 44
	s_cmp_lt_i32 s36, 0
	s_cbranch_scc1 .Lpool_p1skip_11
	s_cmp_gt_u32 s26, 2
	s_cbranch_scc1 .Lpool_p1skip_11
	global_load_dwordx4 v[196:199], v220, s[24:25] offset:0
	global_load_dwordx4 v[200:203], v220, s[24:25] offset:1024
	global_load_dwordx4 v[216:219], v220, s[24:25] offset:2048
	global_load_dwordx4 v[224:227], v220, s[24:25] offset:3072
.Lpool_p1skip_11:
	s_waitcnt vmcnt(0)
	v_mul_f32_e32 v232, v21, v21
	v_fmac_f32_e32 v232, v20, v20
	v_fmac_f32_e32 v232, v22, v22
	v_fmac_f32_e32 v232, v23, v23
	v_mul_f32_e32 v0, v25, v25
	v_fmac_f32_e32 v0, v24, v24
	v_fmac_f32_e32 v0, v26, v26
	v_fmac_f32_e32 v0, v27, v27
	v_add_f32_e32 v232, v232, v0
	v_mul_f32_e32 v0, v29, v29
	v_fmac_f32_e32 v0, v28, v28
	v_fmac_f32_e32 v0, v30, v30
	v_fmac_f32_e32 v0, v31, v31
	v_add_f32_e32 v232, v232, v0
	v_mul_f32_e32 v0, v33, v33
	v_fmac_f32_e32 v0, v32, v32
	v_fmac_f32_e32 v0, v34, v34
	v_fmac_f32_e32 v0, v35, v35
	v_add_f32_e32 v232, v232, v0
	v_mul_f32_e32 v233, v37, v37
	v_fmac_f32_e32 v233, v36, v36
	v_fmac_f32_e32 v233, v38, v38
	v_fmac_f32_e32 v233, v39, v39
	v_mul_f32_e32 v0, v41, v41
	v_fmac_f32_e32 v0, v40, v40
	v_fmac_f32_e32 v0, v42, v42
	v_fmac_f32_e32 v0, v43, v43
	v_add_f32_e32 v233, v233, v0
	v_mul_f32_e32 v0, v45, v45
	v_fmac_f32_e32 v0, v44, v44
	v_fmac_f32_e32 v0, v46, v46
	v_fmac_f32_e32 v0, v47, v47
	v_add_f32_e32 v233, v233, v0
	v_mul_f32_e32 v0, v49, v49
	v_fmac_f32_e32 v0, v48, v48
	v_fmac_f32_e32 v0, v50, v50
	v_fmac_f32_e32 v0, v51, v51
	v_add_f32_e32 v233, v233, v0
	v_mul_f32_e32 v234, v53, v53
	v_fmac_f32_e32 v234, v52, v52
	v_fmac_f32_e32 v234, v54, v54
	v_fmac_f32_e32 v234, v55, v55
	v_mul_f32_e32 v0, v57, v57
	v_fmac_f32_e32 v0, v56, v56
	v_fmac_f32_e32 v0, v58, v58
	v_fmac_f32_e32 v0, v59, v59
	v_add_f32_e32 v234, v234, v0
	v_mul_f32_e32 v0, v61, v61
	v_fmac_f32_e32 v0, v60, v60
	v_fmac_f32_e32 v0, v62, v62
	v_fmac_f32_e32 v0, v63, v63
	v_add_f32_e32 v234, v234, v0
	v_mul_f32_e32 v0, v65, v65
	v_fmac_f32_e32 v0, v64, v64
	v_fmac_f32_e32 v0, v66, v66
	v_fmac_f32_e32 v0, v67, v67
	v_add_f32_e32 v234, v234, v0
	v_mul_f32_e32 v235, v69, v69
	v_fmac_f32_e32 v235, v68, v68
	v_fmac_f32_e32 v235, v70, v70
	v_fmac_f32_e32 v235, v71, v71
	v_mul_f32_e32 v0, v73, v73
	v_fmac_f32_e32 v0, v72, v72
	v_fmac_f32_e32 v0, v74, v74
	v_fmac_f32_e32 v0, v75, v75
	v_add_f32_e32 v235, v235, v0
	v_mul_f32_e32 v0, v77, v77
	v_fmac_f32_e32 v0, v76, v76
	v_fmac_f32_e32 v0, v78, v78
	v_fmac_f32_e32 v0, v79, v79
	v_add_f32_e32 v235, v235, v0
	v_mul_f32_e32 v0, v81, v81
	v_fmac_f32_e32 v0, v80, v80
	v_fmac_f32_e32 v0, v82, v82
	v_fmac_f32_e32 v0, v83, v83
	v_add_f32_e32 v235, v235, v0
	v_mul_f32_e32 v236, v85, v85
	v_fmac_f32_e32 v236, v84, v84
	v_fmac_f32_e32 v236, v86, v86
	v_fmac_f32_e32 v236, v87, v87
	v_mul_f32_e32 v0, v89, v89
	v_fmac_f32_e32 v0, v88, v88
	v_fmac_f32_e32 v0, v90, v90
	v_fmac_f32_e32 v0, v91, v91
	v_add_f32_e32 v236, v236, v0
	v_mul_f32_e32 v0, v93, v93
	v_fmac_f32_e32 v0, v92, v92
	v_fmac_f32_e32 v0, v94, v94
	v_fmac_f32_e32 v0, v95, v95
	v_add_f32_e32 v236, v236, v0
	v_mul_f32_e32 v0, v97, v97
	v_fmac_f32_e32 v0, v96, v96
	v_fmac_f32_e32 v0, v98, v98
	v_fmac_f32_e32 v0, v99, v99
	v_add_f32_e32 v236, v236, v0
	v_mul_f32_e32 v237, v101, v101
	v_fmac_f32_e32 v237, v100, v100
	v_fmac_f32_e32 v237, v102, v102
	v_fmac_f32_e32 v237, v103, v103
	v_mul_f32_e32 v0, v105, v105
	v_fmac_f32_e32 v0, v104, v104
	v_fmac_f32_e32 v0, v106, v106
	v_fmac_f32_e32 v0, v107, v107
	v_add_f32_e32 v237, v237, v0
	v_mul_f32_e32 v0, v109, v109
	v_fmac_f32_e32 v0, v108, v108
	v_fmac_f32_e32 v0, v110, v110
	v_fmac_f32_e32 v0, v111, v111
	v_add_f32_e32 v237, v237, v0
	v_mul_f32_e32 v0, v113, v113
	v_fmac_f32_e32 v0, v112, v112
	v_fmac_f32_e32 v0, v114, v114
	v_fmac_f32_e32 v0, v115, v115
	v_add_f32_e32 v237, v237, v0
	v_mul_f32_e32 v238, v117, v117
	v_fmac_f32_e32 v238, v116, v116
	v_fmac_f32_e32 v238, v118, v118
	v_fmac_f32_e32 v238, v119, v119
	v_mul_f32_e32 v0, v121, v121
	v_fmac_f32_e32 v0, v120, v120
	v_fmac_f32_e32 v0, v122, v122
	v_fmac_f32_e32 v0, v123, v123
	v_add_f32_e32 v238, v238, v0
	v_mul_f32_e32 v0, v125, v125
	v_fmac_f32_e32 v0, v124, v124
	v_fmac_f32_e32 v0, v126, v126
	v_fmac_f32_e32 v0, v127, v127
	v_add_f32_e32 v238, v238, v0
	v_mul_f32_e32 v0, v129, v129
	v_fmac_f32_e32 v0, v128, v128
	v_fmac_f32_e32 v0, v130, v130
	v_fmac_f32_e32 v0, v131, v131
	v_add_f32_e32 v238, v238, v0
	v_mul_f32_e32 v239, v133, v133
	v_fmac_f32_e32 v239, v132, v132
	v_fmac_f32_e32 v239, v134, v134
	v_fmac_f32_e32 v239, v135, v135
	v_mul_f32_e32 v0, v137, v137
	v_fmac_f32_e32 v0, v136, v136
	v_fmac_f32_e32 v0, v138, v138
	v_fmac_f32_e32 v0, v139, v139
	v_add_f32_e32 v239, v239, v0
	v_mul_f32_e32 v0, v141, v141
	v_fmac_f32_e32 v0, v140, v140
	v_fmac_f32_e32 v0, v142, v142
	v_fmac_f32_e32 v0, v143, v143
	v_add_f32_e32 v239, v239, v0
	v_mul_f32_e32 v0, v145, v145
	v_fmac_f32_e32 v0, v144, v144
	v_fmac_f32_e32 v0, v146, v146
	v_fmac_f32_e32 v0, v147, v147
	v_add_f32_e32 v239, v239, v0
	v_mul_f32_e32 v240, v149, v149
	v_fmac_f32_e32 v240, v148, v148
	v_fmac_f32_e32 v240, v150, v150
	v_fmac_f32_e32 v240, v151, v151
	v_mul_f32_e32 v0, v153, v153
	v_fmac_f32_e32 v0, v152, v152
	v_fmac_f32_e32 v0, v154, v154
	v_fmac_f32_e32 v0, v155, v155
	v_add_f32_e32 v240, v240, v0
	v_mul_f32_e32 v0, v157, v157
	v_fmac_f32_e32 v0, v156, v156
	v_fmac_f32_e32 v0, v158, v158
	v_fmac_f32_e32 v0, v159, v159
	v_add_f32_e32 v240, v240, v0
	v_mul_f32_e32 v0, v161, v161
	v_fmac_f32_e32 v0, v160, v160
	v_fmac_f32_e32 v0, v162, v162
	v_fmac_f32_e32 v0, v163, v163
	v_add_f32_e32 v240, v240, v0
	v_mul_f32_e32 v241, v165, v165
	v_fmac_f32_e32 v241, v164, v164
	v_fmac_f32_e32 v241, v166, v166
	v_fmac_f32_e32 v241, v167, v167
	v_mul_f32_e32 v0, v169, v169
	v_fmac_f32_e32 v0, v168, v168
	v_fmac_f32_e32 v0, v170, v170
	v_fmac_f32_e32 v0, v171, v171
	v_add_f32_e32 v241, v241, v0
	v_mul_f32_e32 v0, v173, v173
	v_fmac_f32_e32 v0, v172, v172
	v_fmac_f32_e32 v0, v174, v174
	v_fmac_f32_e32 v0, v175, v175
	v_add_f32_e32 v241, v241, v0
	v_mul_f32_e32 v0, v177, v177
	v_fmac_f32_e32 v0, v176, v176
	v_fmac_f32_e32 v0, v178, v178
	v_fmac_f32_e32 v0, v179, v179
	v_add_f32_e32 v241, v241, v0
	v_mul_f32_e32 v242, v181, v181
	v_fmac_f32_e32 v242, v180, v180
	v_fmac_f32_e32 v242, v182, v182
	v_fmac_f32_e32 v242, v183, v183
	v_mul_f32_e32 v0, v185, v185
	v_fmac_f32_e32 v0, v184, v184
	v_fmac_f32_e32 v0, v186, v186
	v_fmac_f32_e32 v0, v187, v187
	v_add_f32_e32 v242, v242, v0
	v_mul_f32_e32 v0, v189, v189
	v_fmac_f32_e32 v0, v188, v188
	v_fmac_f32_e32 v0, v190, v190
	v_fmac_f32_e32 v0, v191, v191
	v_add_f32_e32 v242, v242, v0
	v_mul_f32_e32 v0, v193, v193
	v_fmac_f32_e32 v0, v192, v192
	v_fmac_f32_e32 v0, v194, v194
	v_fmac_f32_e32 v0, v195, v195
	v_add_f32_e32 v242, v242, v0
	v_mul_f32_e32 v243, v197, v197
	v_fmac_f32_e32 v243, v196, v196
	v_fmac_f32_e32 v243, v198, v198
	v_fmac_f32_e32 v243, v199, v199
	v_mul_f32_e32 v0, v201, v201
	v_fmac_f32_e32 v0, v200, v200
	v_fmac_f32_e32 v0, v202, v202
	v_fmac_f32_e32 v0, v203, v203
	v_add_f32_e32 v243, v243, v0
	v_mul_f32_e32 v0, v217, v217
	v_fmac_f32_e32 v0, v216, v216
	v_fmac_f32_e32 v0, v218, v218
	v_fmac_f32_e32 v0, v219, v219
	v_add_f32_e32 v243, v243, v0
	v_mul_f32_e32 v0, v225, v225
	v_fmac_f32_e32 v0, v224, v224
	v_fmac_f32_e32 v0, v226, v226
	v_fmac_f32_e32 v0, v227, v227
	v_add_f32_e32 v243, v243, v0
	v_lshlrev_b32_e32 v221, 4, v205
	v_lshlrev_b32_e32 v222, 3, v205
	s_sub_i32 s28, s13, 15
	s_ashr_i32 s29, s28, 31
	s_lshl_b64 s[24:25], s[28:29], 12
	s_add_u32 s24, s22, s24
	s_addc_u32 s25, s23, s25
	v_readfirstlane_b32 s27, v13
	s_sub_i32 s27, 16, s27
	s_cmp_eq_u32 s14, 0
	s_cselect_b32 s27, 15, s27
	s_cmp_gt_u32 s27, 0
	s_cbranch_scc1 .Lpool_ldskip_0
	global_load_dwordx4 v[20:23], v221, s[24:25]
.Lpool_ldskip_0:
	s_add_u32 s24, s24, 0x1000
	s_addc_u32 s25, s25, 0
	s_cmp_gt_u32 s27, 1
	s_cbranch_scc1 .Lpool_ldskip_1
	global_load_dwordx4 v[24:27], v221, s[24:25]
.Lpool_ldskip_1:
	s_add_u32 s24, s24, 0x1000
	s_addc_u32 s25, s25, 0
	s_cmp_gt_u32 s27, 2
	s_cbranch_scc1 .Lpool_ldskip_2
	global_load_dwordx4 v[28:31], v221, s[24:25]
.Lpool_ldskip_2:
	s_add_u32 s24, s24, 0x1000
	s_addc_u32 s25, s25, 0
	s_cmp_gt_u32 s27, 3
	s_cbranch_scc1 .Lpool_ldskip_3
	global_load_dwordx4 v[32:35], v221, s[24:25]
.Lpool_ldskip_3:
	s_add_u32 s24, s24, 0x1000
	s_addc_u32 s25, s25, 0
	s_cmp_gt_u32 s27, 4
	s_cbranch_scc1 .Lpool_ldskip_4
	global_load_dwordx4 v[36:39], v221, s[24:25]
.Lpool_ldskip_4:
	s_add_u32 s24, s24, 0x1000
	s_addc_u32 s25, s25, 0
	s_cmp_gt_u32 s27, 5
	s_cbranch_scc1 .Lpool_ldskip_5
	global_load_dwordx4 v[40:43], v221, s[24:25]
.Lpool_ldskip_5:
	s_add_u32 s24, s24, 0x1000
	s_addc_u32 s25, s25, 0
	s_cmp_gt_u32 s27, 6
	s_cbranch_scc1 .Lpool_ldskip_6
	global_load_dwordx4 v[44:47], v221, s[24:25]
.Lpool_ldskip_6:
	s_add_u32 s24, s24, 0x1000
	s_addc_u32 s25, s25, 0
	s_cmp_gt_u32 s27, 7
	s_cbranch_scc1 .Lpool_ldskip_7
	global_load_dwordx4 v[48:51], v221, s[24:25]
.Lpool_ldskip_7:
	s_add_u32 s24, s24, 0x1000
	s_addc_u32 s25, s25, 0
	s_cmp_gt_u32 s27, 8
	s_cbranch_scc1 .Lpool_ldskip_8
	global_load_dwordx4 v[52:55], v221, s[24:25]
.Lpool_ldskip_8:
	s_add_u32 s24, s24, 0x1000
	s_addc_u32 s25, s25, 0
	s_cmp_gt_u32 s27, 9
	s_cbranch_scc1 .Lpool_ldskip_9
	global_load_dwordx4 v[56:59], v221, s[24:25]
.Lpool_ldskip_9:
	s_add_u32 s24, s24, 0x1000
	s_addc_u32 s25, s25, 0
	s_cmp_gt_u32 s27, 10
	s_cbranch_scc1 .Lpool_ldskip_10
	global_load_dwordx4 v[60:63], v221, s[24:25]
.Lpool_ldskip_10:
	s_add_u32 s24, s24, 0x1000
	s_addc_u32 s25, s25, 0
	s_cmp_gt_u32 s27, 11
	s_cbranch_scc1 .Lpool_ldskip_11
	global_load_dwordx4 v[64:67], v221, s[24:25]
.Lpool_ldskip_11:
	s_add_u32 s24, s24, 0x1000
	s_addc_u32 s25, s25, 0
	s_cmp_gt_u32 s27, 12
	s_cbranch_scc1 .Lpool_ldskip_12
	global_load_dwordx4 v[68:71], v221, s[24:25]
.Lpool_ldskip_12:
	s_add_u32 s24, s24, 0x1000
	s_addc_u32 s25, s25, 0
	s_cmp_gt_u32 s27, 13
	s_cbranch_scc1 .Lpool_ldskip_13
	global_load_dwordx4 v[72:75], v221, s[24:25]
.Lpool_ldskip_13:
	s_add_u32 s24, s24, 0x1000
	s_addc_u32 s25, s25, 0
	s_cmp_gt_u32 s27, 14
	s_cbranch_scc1 .Lpool_ldskip_14
	global_load_dwordx4 v[76:79], v221, s[24:25]
.Lpool_ldskip_14:
	s_add_u32 s24, s24, 0x1000
	s_addc_u32 s25, s25, 0
	global_load_dwordx4 v[80:83], v221, s[24:25]
	s_add_u32 s24, s24, 0x1000
	s_addc_u32 s25, s25, 0
	global_load_dwordx4 v[84:87], v221, s[24:25]
	s_add_u32 s24, s24, 0x1000
	s_addc_u32 s25, s25, 0
	global_load_dwordx4 v[88:91], v221, s[24:25]
	s_add_u32 s24, s24, 0x1000
	s_addc_u32 s25, s25, 0
	global_load_dwordx4 v[92:95], v221, s[24:25]
	s_add_u32 s24, s24, 0x1000
	s_addc_u32 s25, s25, 0
	global_load_dwordx4 v[96:99], v221, s[24:25]
	s_add_u32 s24, s24, 0x1000
	s_addc_u32 s25, s25, 0
	global_load_dwordx4 v[100:103], v221, s[24:25]
	s_add_u32 s24, s24, 0x1000
	s_addc_u32 s25, s25, 0
	global_load_dwordx4 v[104:107], v221, s[24:25]
	s_add_u32 s24, s24, 0x1000
	s_addc_u32 s25, s25, 0
	global_load_dwordx4 v[108:111], v221, s[24:25]
	s_add_u32 s24, s24, 0x1000
	s_addc_u32 s25, s25, 0
	global_load_dwordx4 v[112:115], v221, s[24:25]
	s_add_u32 s24, s24, 0x1000
	s_addc_u32 s25, s25, 0
	global_load_dwordx4 v[116:119], v221, s[24:25]
	s_add_u32 s24, s24, 0x1000
	s_addc_u32 s25, s25, 0
	global_load_dwordx4 v[120:123], v221, s[24:25]
	s_add_u32 s24, s24, 0x1000
	s_addc_u32 s25, s25, 0
	global_load_dwordx4 v[124:127], v221, s[24:25]
	s_add_u32 s24, s24, 0x1000
	s_addc_u32 s25, s25, 0
	global_load_dwordx4 v[128:131], v221, s[24:25]
	s_add_u32 s24, s24, 0x1000
	s_addc_u32 s25, s25, 0
	global_load_dwordx4 v[132:135], v221, s[24:25]
	s_add_u32 s24, s24, 0x1000
	s_addc_u32 s25, s25, 0
	global_load_dwordx4 v[136:139], v221, s[24:25]
	s_add_u32 s24, s24, 0x1000
	s_addc_u32 s25, s25, 0
	global_load_dwordx4 v[140:143], v221, s[24:25]
	s_add_u32 s24, s24, 0x1000
	s_addc_u32 s25, s25, 0
	global_load_dwordx4 v[144:147], v221, s[24:25]
	s_add_u32 s24, s24, 0x1000
	s_addc_u32 s25, s25, 0
	global_load_dwordx4 v[148:151], v221, s[24:25]
	s_add_u32 s24, s24, 0x1000
	s_addc_u32 s25, s25, 0
	global_load_dwordx4 v[152:155], v221, s[24:25]
	s_add_u32 s24, s24, 0x1000
	s_addc_u32 s25, s25, 0
	global_load_dwordx4 v[156:159], v221, s[24:25]
	s_add_u32 s24, s24, 0x1000
	s_addc_u32 s25, s25, 0
	global_load_dwordx4 v[160:163], v221, s[24:25]
	s_add_u32 s24, s24, 0x1000
	s_addc_u32 s25, s25, 0
	global_load_dwordx4 v[164:167], v221, s[24:25]
	s_add_u32 s24, s24, 0x1000
	s_addc_u32 s25, s25, 0
	global_load_dwordx4 v[168:171], v221, s[24:25]
	s_add_u32 s24, s24, 0x1000
	s_addc_u32 s25, s25, 0
	global_load_dwordx4 v[172:175], v221, s[24:25]
	s_add_u32 s24, s24, 0x1000
	s_addc_u32 s25, s25, 0
	global_load_dwordx4 v[176:179], v221, s[24:25]
	s_add_u32 s24, s24, 0x1000
	s_addc_u32 s25, s25, 0
	global_load_dwordx4 v[180:183], v221, s[24:25]
	s_add_u32 s24, s24, 0x1000
	s_addc_u32 s25, s25, 0
	global_load_dwordx4 v[184:187], v221, s[24:25]
	s_add_u32 s24, s24, 0x1000
	s_addc_u32 s25, s25, 0
	global_load_dwordx4 v[188:191], v221, s[24:25]
	s_add_u32 s24, s24, 0x1000
	s_addc_u32 s25, s25, 0
	global_load_dwordx4 v[192:195], v221, s[24:25]
	s_add_u32 s24, s24, 0x1000
	s_addc_u32 s25, s25, 0
	global_load_dwordx4 v[196:199], v221, s[24:25]
	s_add_u32 s24, s24, 0x1000
	s_addc_u32 s25, s25, 0
	global_load_dwordx4 v[200:203], v221, s[24:25]
	s_add_u32 s24, s24, 0x1000
	s_addc_u32 s25, s25, 0
	global_load_dwordx4 v[216:219], v221, s[24:25]
	ds_bpermute_b32 v224, v244, v232
	ds_bpermute_b32 v225, v244, v233
	ds_bpermute_b32 v226, v244, v234
	ds_bpermute_b32 v227, v244, v235
	ds_bpermute_b32 v228, v244, v236
	ds_bpermute_b32 v229, v244, v237
	ds_bpermute_b32 v230, v244, v238
	ds_bpermute_b32 v231, v244, v239
	ds_bpermute_b32 v2, v244, v240
	ds_bpermute_b32 v3, v244, v241
	ds_bpermute_b32 v4, v244, v242
	ds_bpermute_b32 v5, v244, v243
	s_waitcnt lgkmcnt(11)
	v_add_f32_e32 v232, v232, v224
	s_waitcnt lgkmcnt(10)
	v_add_f32_e32 v233, v233, v225
	s_waitcnt lgkmcnt(9)
	v_add_f32_e32 v234, v234, v226
	s_waitcnt lgkmcnt(8)
	v_add_f32_e32 v235, v235, v227
	s_waitcnt lgkmcnt(7)
	v_add_f32_e32 v236, v236, v228
	s_waitcnt lgkmcnt(6)
	v_add_f32_e32 v237, v237, v229
	s_waitcnt lgkmcnt(5)
	v_add_f32_e32 v238, v238, v230
	s_waitcnt lgkmcnt(4)
	v_add_f32_e32 v239, v239, v231
	s_waitcnt lgkmcnt(3)
	v_add_f32_e32 v240, v240, v2
	s_waitcnt lgkmcnt(2)
	v_add_f32_e32 v241, v241, v3
	s_waitcnt lgkmcnt(1)
	v_add_f32_e32 v242, v242, v4
	s_waitcnt lgkmcnt(0)
	v_add_f32_e32 v243, v243, v5
	ds_bpermute_b32 v224, v245, v232
	ds_bpermute_b32 v225, v245, v233
	ds_bpermute_b32 v226, v245, v234
	ds_bpermute_b32 v227, v245, v235
	ds_bpermute_b32 v228, v245, v236
	ds_bpermute_b32 v229, v245, v237
	ds_bpermute_b32 v230, v245, v238
	ds_bpermute_b32 v231, v245, v239
	ds_bpermute_b32 v2, v245, v240
	ds_bpermute_b32 v3, v245, v241
	ds_bpermute_b32 v4, v245, v242
	ds_bpermute_b32 v5, v245, v243
	s_waitcnt lgkmcnt(11)
	v_add_f32_e32 v232, v232, v224
	s_waitcnt lgkmcnt(10)
	v_add_f32_e32 v233, v233, v225
	s_waitcnt lgkmcnt(9)
	v_add_f32_e32 v234, v234, v226
	s_waitcnt lgkmcnt(8)
	v_add_f32_e32 v235, v235, v227
	s_waitcnt lgkmcnt(7)
	v_add_f32_e32 v236, v236, v228
	s_waitcnt lgkmcnt(6)
	v_add_f32_e32 v237, v237, v229
	s_waitcnt lgkmcnt(5)
	v_add_f32_e32 v238, v238, v230
	s_waitcnt lgkmcnt(4)
	v_add_f32_e32 v239, v239, v231
	s_waitcnt lgkmcnt(3)
	v_add_f32_e32 v240, v240, v2
	s_waitcnt lgkmcnt(2)
	v_add_f32_e32 v241, v241, v3
	s_waitcnt lgkmcnt(1)
	v_add_f32_e32 v242, v242, v4
	s_waitcnt lgkmcnt(0)
	v_add_f32_e32 v243, v243, v5
	ds_bpermute_b32 v224, v246, v232
	ds_bpermute_b32 v225, v246, v233
	ds_bpermute_b32 v226, v246, v234
	ds_bpermute_b32 v227, v246, v235
	ds_bpermute_b32 v228, v246, v236
	ds_bpermute_b32 v229, v246, v237
	ds_bpermute_b32 v230, v246, v238
	ds_bpermute_b32 v231, v246, v239
	ds_bpermute_b32 v2, v246, v240
	ds_bpermute_b32 v3, v246, v241
	ds_bpermute_b32 v4, v246, v242
	ds_bpermute_b32 v5, v246, v243
	s_waitcnt lgkmcnt(11)
	v_add_f32_e32 v232, v232, v224
	s_waitcnt lgkmcnt(10)
	v_add_f32_e32 v233, v233, v225
	s_waitcnt lgkmcnt(9)
	v_add_f32_e32 v234, v234, v226
	s_waitcnt lgkmcnt(8)
	v_add_f32_e32 v235, v235, v227
	s_waitcnt lgkmcnt(7)
	v_add_f32_e32 v236, v236, v228
	s_waitcnt lgkmcnt(6)
	v_add_f32_e32 v237, v237, v229
	s_waitcnt lgkmcnt(5)
	v_add_f32_e32 v238, v238, v230
	s_waitcnt lgkmcnt(4)
	v_add_f32_e32 v239, v239, v231
	s_waitcnt lgkmcnt(3)
	v_add_f32_e32 v240, v240, v2
	s_waitcnt lgkmcnt(2)
	v_add_f32_e32 v241, v241, v3
	s_waitcnt lgkmcnt(1)
	v_add_f32_e32 v242, v242, v4
	s_waitcnt lgkmcnt(0)
	v_add_f32_e32 v243, v243, v5
	ds_bpermute_b32 v224, v247, v232
	ds_bpermute_b32 v225, v247, v233
	ds_bpermute_b32 v226, v247, v234
	ds_bpermute_b32 v227, v247, v235
	ds_bpermute_b32 v228, v247, v236
	ds_bpermute_b32 v229, v247, v237
	ds_bpermute_b32 v230, v247, v238
	ds_bpermute_b32 v231, v247, v239
	ds_bpermute_b32 v2, v247, v240
	ds_bpermute_b32 v3, v247, v241
	ds_bpermute_b32 v4, v247, v242
	ds_bpermute_b32 v5, v247, v243
	s_waitcnt lgkmcnt(11)
	v_add_f32_e32 v232, v232, v224
	s_waitcnt lgkmcnt(10)
	v_add_f32_e32 v233, v233, v225
	s_waitcnt lgkmcnt(9)
	v_add_f32_e32 v234, v234, v226
	s_waitcnt lgkmcnt(8)
	v_add_f32_e32 v235, v235, v227
	s_waitcnt lgkmcnt(7)
	v_add_f32_e32 v236, v236, v228
	s_waitcnt lgkmcnt(6)
	v_add_f32_e32 v237, v237, v229
	s_waitcnt lgkmcnt(5)
	v_add_f32_e32 v238, v238, v230
	s_waitcnt lgkmcnt(4)
	v_add_f32_e32 v239, v239, v231
	s_waitcnt lgkmcnt(3)
	v_add_f32_e32 v240, v240, v2
	s_waitcnt lgkmcnt(2)
	v_add_f32_e32 v241, v241, v3
	s_waitcnt lgkmcnt(1)
	v_add_f32_e32 v242, v242, v4
	s_waitcnt lgkmcnt(0)
	v_add_f32_e32 v243, v243, v5
	ds_bpermute_b32 v224, v248, v232
	ds_bpermute_b32 v225, v248, v233
	ds_bpermute_b32 v226, v248, v234
	ds_bpermute_b32 v227, v248, v235
	ds_bpermute_b32 v228, v248, v236
	ds_bpermute_b32 v229, v248, v237
	ds_bpermute_b32 v230, v248, v238
	ds_bpermute_b32 v231, v248, v239
	ds_bpermute_b32 v2, v248, v240
	ds_bpermute_b32 v3, v248, v241
	ds_bpermute_b32 v4, v248, v242
	ds_bpermute_b32 v5, v248, v243
	s_waitcnt lgkmcnt(11)
	v_add_f32_e32 v232, v232, v224
	s_waitcnt lgkmcnt(10)
	v_add_f32_e32 v233, v233, v225
	s_waitcnt lgkmcnt(9)
	v_add_f32_e32 v234, v234, v226
	s_waitcnt lgkmcnt(8)
	v_add_f32_e32 v235, v235, v227
	s_waitcnt lgkmcnt(7)
	v_add_f32_e32 v236, v236, v228
	s_waitcnt lgkmcnt(6)
	v_add_f32_e32 v237, v237, v229
	s_waitcnt lgkmcnt(5)
	v_add_f32_e32 v238, v238, v230
	s_waitcnt lgkmcnt(4)
	v_add_f32_e32 v239, v239, v231
	s_waitcnt lgkmcnt(3)
	v_add_f32_e32 v240, v240, v2
	s_waitcnt lgkmcnt(2)
	v_add_f32_e32 v241, v241, v3
	s_waitcnt lgkmcnt(1)
	v_add_f32_e32 v242, v242, v4
	s_waitcnt lgkmcnt(0)
	v_add_f32_e32 v243, v243, v5
	ds_bpermute_b32 v224, v249, v232
	ds_bpermute_b32 v225, v249, v233
	ds_bpermute_b32 v226, v249, v234
	ds_bpermute_b32 v227, v249, v235
	ds_bpermute_b32 v228, v249, v236
	ds_bpermute_b32 v229, v249, v237
	ds_bpermute_b32 v230, v249, v238
	ds_bpermute_b32 v231, v249, v239
	ds_bpermute_b32 v2, v249, v240
	ds_bpermute_b32 v3, v249, v241
	ds_bpermute_b32 v4, v249, v242
	ds_bpermute_b32 v5, v249, v243
	s_waitcnt lgkmcnt(11)
	v_add_f32_e32 v232, v232, v224
	s_waitcnt lgkmcnt(10)
	v_add_f32_e32 v233, v233, v225
	s_waitcnt lgkmcnt(9)
	v_add_f32_e32 v234, v234, v226
	s_waitcnt lgkmcnt(8)
	v_add_f32_e32 v235, v235, v227
	s_waitcnt lgkmcnt(7)
	v_add_f32_e32 v236, v236, v228
	s_waitcnt lgkmcnt(6)
	v_add_f32_e32 v237, v237, v229
	s_waitcnt lgkmcnt(5)
	v_add_f32_e32 v238, v238, v230
	s_waitcnt lgkmcnt(4)
	v_add_f32_e32 v239, v239, v231
	s_waitcnt lgkmcnt(3)
	v_add_f32_e32 v240, v240, v2
	s_waitcnt lgkmcnt(2)
	v_add_f32_e32 v241, v241, v3
	s_waitcnt lgkmcnt(1)
	v_add_f32_e32 v242, v242, v4
	s_waitcnt lgkmcnt(0)
	v_add_f32_e32 v243, v243, v5
	v_mov_b32_e32 v223, s80
	v_lshl_add_u32 v0, v12, 2, v223
	v_fmamk_f32 v232, v232, 0x3a800000, v206
	v_mul_f32_e32 v224, 0x4b800000, v232
	v_cmp_gt_f32_e32 vcc, s58, v232
	s_nop 1
	v_cndmask_b32_e32 v232, v232, v224, vcc
	v_rsq_f32_e32 v232, v232
	s_nop 0
	v_mul_f32_e32 v224, 0x45800000, v232
	v_cndmask_b32_e32 v232, v232, v224, vcc
	v_fmamk_f32 v233, v233, 0x3a800000, v206
	v_mul_f32_e32 v225, 0x4b800000, v233
	v_cmp_gt_f32_e32 vcc, s58, v233
	s_nop 1
	v_cndmask_b32_e32 v233, v233, v225, vcc
	v_rsq_f32_e32 v233, v233
	s_nop 0
	v_mul_f32_e32 v225, 0x45800000, v233
	v_cndmask_b32_e32 v233, v233, v225, vcc
	v_fmamk_f32 v234, v234, 0x3a800000, v206
	v_mul_f32_e32 v226, 0x4b800000, v234
	v_cmp_gt_f32_e32 vcc, s58, v234
	s_nop 1
	v_cndmask_b32_e32 v234, v234, v226, vcc
	v_rsq_f32_e32 v234, v234
	s_nop 0
	v_mul_f32_e32 v226, 0x45800000, v234
	v_cndmask_b32_e32 v234, v234, v226, vcc
	v_fmamk_f32 v235, v235, 0x3a800000, v206
	v_mul_f32_e32 v227, 0x4b800000, v235
	v_cmp_gt_f32_e32 vcc, s58, v235
	s_nop 1
	v_cndmask_b32_e32 v235, v235, v227, vcc
	v_rsq_f32_e32 v235, v235
	s_nop 0
	v_mul_f32_e32 v227, 0x45800000, v235
	v_cndmask_b32_e32 v235, v235, v227, vcc
	v_fmamk_f32 v236, v236, 0x3a800000, v206
	v_mul_f32_e32 v228, 0x4b800000, v236
	v_cmp_gt_f32_e32 vcc, s58, v236
	s_nop 1
	v_cndmask_b32_e32 v236, v236, v228, vcc
	v_rsq_f32_e32 v236, v236
	s_nop 0
	v_mul_f32_e32 v228, 0x45800000, v236
	v_cndmask_b32_e32 v236, v236, v228, vcc
	v_fmamk_f32 v237, v237, 0x3a800000, v206
	v_mul_f32_e32 v229, 0x4b800000, v237
	v_cmp_gt_f32_e32 vcc, s58, v237
	s_nop 1
	v_cndmask_b32_e32 v237, v237, v229, vcc
	v_rsq_f32_e32 v237, v237
	s_nop 0
	v_mul_f32_e32 v229, 0x45800000, v237
	v_cndmask_b32_e32 v237, v237, v229, vcc
	v_fmamk_f32 v238, v238, 0x3a800000, v206
	v_mul_f32_e32 v230, 0x4b800000, v238
	v_cmp_gt_f32_e32 vcc, s58, v238
	s_nop 1
	v_cndmask_b32_e32 v238, v238, v230, vcc
	v_rsq_f32_e32 v238, v238
	s_nop 0
	v_mul_f32_e32 v230, 0x45800000, v238
	v_cndmask_b32_e32 v238, v238, v230, vcc
	v_fmamk_f32 v239, v239, 0x3a800000, v206
	v_mul_f32_e32 v231, 0x4b800000, v239
	v_cmp_gt_f32_e32 vcc, s58, v239
	s_nop 1
	v_cndmask_b32_e32 v239, v239, v231, vcc
	v_rsq_f32_e32 v239, v239
	s_nop 0
	v_mul_f32_e32 v231, 0x45800000, v239
	v_cndmask_b32_e32 v239, v239, v231, vcc
	v_fmamk_f32 v240, v240, 0x3a800000, v206
	v_mul_f32_e32 v2, 0x4b800000, v240
	v_cmp_gt_f32_e32 vcc, s58, v240
	s_nop 1
	v_cndmask_b32_e32 v240, v240, v2, vcc
	v_rsq_f32_e32 v240, v240
	s_nop 0
	v_mul_f32_e32 v2, 0x45800000, v240
	v_cndmask_b32_e32 v240, v240, v2, vcc
	v_fmamk_f32 v241, v241, 0x3a800000, v206
	v_mul_f32_e32 v3, 0x4b800000, v241
	v_cmp_gt_f32_e32 vcc, s58, v241
	s_nop 1
	v_cndmask_b32_e32 v241, v241, v3, vcc
	v_rsq_f32_e32 v241, v241
	s_nop 0
	v_mul_f32_e32 v3, 0x45800000, v241
	v_cndmask_b32_e32 v241, v241, v3, vcc
	v_fmamk_f32 v242, v242, 0x3a800000, v206
	v_mul_f32_e32 v4, 0x4b800000, v242
	v_cmp_gt_f32_e32 vcc, s58, v242
	s_nop 1
	v_cndmask_b32_e32 v242, v242, v4, vcc
	v_rsq_f32_e32 v242, v242
	s_nop 0
	v_mul_f32_e32 v4, 0x45800000, v242
	v_cndmask_b32_e32 v242, v242, v4, vcc
	v_fmamk_f32 v243, v243, 0x3a800000, v206
	v_mul_f32_e32 v5, 0x4b800000, v243
	v_cmp_gt_f32_e32 vcc, s58, v243
	s_nop 1
	v_cndmask_b32_e32 v243, v243, v5, vcc
	v_rsq_f32_e32 v243, v243
	s_nop 0
	v_mul_f32_e32 v5, 0x45800000, v243
	v_cndmask_b32_e32 v243, v243, v5, vcc
	s_mov_b64 s[30:31], exec
	s_mov_b64 exec, 1
	s_add_i32 s36, s13, s26
	s_add_i32 s36, s36, -15
	s_cmp_lt_i32 s36, 0
	s_cbranch_scc1 .Lpool_wrskip_0
	ds_write_b32 v0, v232 offset:0
.Lpool_wrskip_0:
	s_add_i32 s36, s13, s26
	s_add_i32 s36, s36, -11
	s_cmp_lt_i32 s36, 0
	s_cbranch_scc1 .Lpool_wrskip_1
	ds_write_b32 v0, v233 offset:16
.Lpool_wrskip_1:
	s_add_i32 s36, s13, s26
	s_add_i32 s36, s36, -7
	s_cmp_lt_i32 s36, 0
	s_cbranch_scc1 .Lpool_wrskip_2
	ds_write_b32 v0, v234 offset:32
.Lpool_wrskip_2:
	s_add_i32 s36, s13, s26
	s_add_i32 s36, s36, -3
	s_cmp_lt_i32 s36, 0
	s_cbranch_scc1 .Lpool_wrskip_3
	ds_write_b32 v0, v235 offset:48
.Lpool_wrskip_3:
	s_add_i32 s36, s13, s26
	s_add_i32 s36, s36, 1
	s_cmp_lt_i32 s36, 0
	s_cbranch_scc1 .Lpool_wrskip_4
	ds_write_b32 v0, v236 offset:64
.Lpool_wrskip_4:
	s_add_i32 s36, s13, s26
	s_add_i32 s36, s36, 5
	s_cmp_lt_i32 s36, 0
	s_cbranch_scc1 .Lpool_wrskip_5
	ds_write_b32 v0, v237 offset:80
.Lpool_wrskip_5:
	s_add_i32 s36, s13, s26
	s_add_i32 s36, s36, 9
	s_cmp_lt_i32 s36, 0
	s_cbranch_scc1 .Lpool_wrskip_6
	ds_write_b32 v0, v238 offset:96
.Lpool_wrskip_6:
	s_add_i32 s36, s13, s26
	s_add_i32 s36, s36, 13
	s_cmp_lt_i32 s36, 0
	s_cbranch_scc1 .Lpool_wrskip_7
	ds_write_b32 v0, v239 offset:112
.Lpool_wrskip_7:
	s_add_i32 s36, s13, s26
	s_add_i32 s36, s36, 17
	s_cmp_lt_i32 s36, 0
	s_cbranch_scc1 .Lpool_wrskip_8
	ds_write_b32 v0, v240 offset:128
.Lpool_wrskip_8:
	s_add_i32 s36, s13, s26
	s_add_i32 s36, s36, 21
	s_cmp_lt_i32 s36, 0
	s_cbranch_scc1 .Lpool_wrskip_9
	ds_write_b32 v0, v241 offset:144
.Lpool_wrskip_9:
	s_add_i32 s36, s13, s26
	s_add_i32 s36, s36, 25
	s_cmp_lt_i32 s36, 0
	s_cbranch_scc1 .Lpool_wrskip_10
	ds_write_b32 v0, v242 offset:160
.Lpool_wrskip_10:
	s_add_i32 s36, s13, s26
	s_add_i32 s36, s36, 29
	s_cmp_lt_i32 s36, 0
	s_cbranch_scc1 .Lpool_wrskip_11
	s_cmp_gt_u32 s26, 2
	s_cbranch_scc1 .Lpool_wrskip_11
	ds_write_b32 v0, v243 offset:176
.Lpool_wrskip_11:
	s_mov_b64 exec, s[30:31]
	s_waitcnt lgkmcnt(0)
	s_barrier
	v_readlane_b32 s34, v250, 48
	v_readlane_b32 s35, v250, 49
	s_ashr_i32 s29, s13, 31
	s_mov_b32 s28, s13
	s_lshl_b64 s[28:29], s[28:29], 11
	s_add_u32 s34, s34, s28
	s_addc_u32 s35, s35, s29
	s_cmp_eq_u32 s26, 0
	s_cbranch_scc1 .Lpool_v0
	s_cmp_eq_u32 s26, 1
	s_cbranch_scc1 .Lpool_v1
	s_cmp_eq_u32 s26, 2
	s_cbranch_scc1 .Lpool_v2
	s_branch .Lpool_v3
.Lpool_v0:
	ds_read_b32 v224, v223 offset:56
	ds_read_b32 v226, v223 offset:60
	ds_read_b32 v228, v223 offset:56
	ds_read_b32 v230, v223 offset:64
	ds_read_b32 v244, v223 offset:60
	ds_read_b32 v246, v223 offset:68
	v_mov_b32_e32 v2, 0
	v_mov_b32_e32 v3, 0
	v_mov_b32_e32 v4, 0
	v_mov_b32_e32 v5, 0
	s_cmp_eq_u32 s14, 0
	s_cbranch_scc1 .Lpool_v0_nopre
	s_waitcnt vmcnt(32)
	s_waitcnt lgkmcnt(5)
	v_pk_fma_f32 v[4:5], v[78:79], v[224:225], v[4:5] op_sel_hi:[1,0,1]
	v_pk_fma_f32 v[2:3], v[76:77], v[224:225], v[2:3] op_sel_hi:[1,0,1]
	ds_read_b32 v248, v223 offset:64
	s_branch .Lpool_v0_main
.Lpool_v0_nopre:
	ds_read_b32 v248, v223 offset:64
.Lpool_v0_main:
	s_waitcnt lgkmcnt(5)
	s_waitcnt vmcnt(31)
	v_pk_mul_f32 v[236:237], v[80:81], v[226:227] op_sel_hi:[1,0]
	v_pk_fma_f32 v[2:3], v[80:81], v[226:227], v[2:3] op_sel_hi:[1,0,1]
	v_pk_mul_f32 v[238:239], v[82:83], v[226:227] op_sel_hi:[1,0]
	v_pk_fma_f32 v[4:5], v[82:83], v[226:227], v[4:5] op_sel_hi:[1,0,1]
	ds_read_b32 v232, v223 offset:72
	s_mov_b32 s36, 0x3f000000
	s_cmp_eq_u32 s14, 0
	s_cselect_b32 s36, 0x3f800000, s36
	v_mov_b32_e32 v240, s36
	v_pk_fma_f32 v[242:243], v[240:241], v[2:3], v[236:237] op_sel_hi:[0,1,1] neg_lo:[0,0,1] neg_hi:[0,0,1]
	v_pk_fma_f32 v[236:237], v[240:241], v[4:5], v[238:239] op_sel_hi:[0,1,1] neg_lo:[0,0,1] neg_hi:[0,0,1]
	v_cvt_pk_bf16_f32 v242, v242, v243
	v_cvt_pk_bf16_f32 v243, v236, v237
	global_store_dwordx2 v222, v[242:243], s[34:35]
	s_add_u32 s34, s34, 0x800
	s_addc_u32 s35, s35, 0
	s_waitcnt lgkmcnt(5)
	s_cmp_eq_u32 s14, 0
	s_cbranch_scc1 .Lpool_v0_ns0
	v_xor_b32_e32 v239, 0x80000000, v79
	v_xor_b32_e32 v238, 0x80000000, v78
	v_pk_fma_f32 v[4:5], v[238:239], v[228:229], v[4:5] op_sel_hi:[1,0,1]
	v_pk_fma_f32 v[2:3], v[76:77], v[228:229], v[2:3] op_sel_hi:[1,0,1] neg_lo:[1,0,0] neg_hi:[1,0,0]
.Lpool_v0_ns0:
	ds_read_b32 v224, v223 offset:68
	s_waitcnt lgkmcnt(5)
	s_waitcnt vmcnt(31)
	v_pk_mul_f32 v[236:237], v[84:85], v[230:231] op_sel_hi:[1,0]
	v_pk_fma_f32 v[2:3], v[84:85], v[230:231], v[2:3] op_sel_hi:[1,0,1]
	v_pk_mul_f32 v[238:239], v[86:87], v[230:231] op_sel_hi:[1,0]
	v_pk_fma_f32 v[4:5], v[86:87], v[230:231], v[4:5] op_sel_hi:[1,0,1]
	ds_read_b32 v226, v223 offset:76
	v_mov_b32_e32 v240, 0x3f000000
	v_pk_fma_f32 v[242:243], v[240:241], v[2:3], v[236:237] op_sel_hi:[0,1,1] neg_lo:[0,0,1] neg_hi:[0,0,1]
	v_pk_fma_f32 v[236:237], v[240:241], v[4:5], v[238:239] op_sel_hi:[0,1,1] neg_lo:[0,0,1] neg_hi:[0,0,1]
	v_cvt_pk_bf16_f32 v242, v242, v243
	v_cvt_pk_bf16_f32 v243, v236, v237
	global_store_dwordx2 v222, v[242:243], s[34:35]
	s_add_u32 s34, s34, 0x800
	s_addc_u32 s35, s35, 0
	s_waitcnt lgkmcnt(5)
	v_xor_b32_e32 v239, 0x80000000, v83
	v_xor_b32_e32 v238, 0x80000000, v82
	v_pk_fma_f32 v[4:5], v[238:239], v[244:245], v[4:5] op_sel_hi:[1,0,1]
	v_pk_fma_f32 v[2:3], v[80:81], v[244:245], v[2:3] op_sel_hi:[1,0,1] neg_lo:[1,0,0] neg_hi:[1,0,0]
	ds_read_b32 v228, v223 offset:72
	s_waitcnt lgkmcnt(5)
	s_waitcnt vmcnt(31)
	v_pk_mul_f32 v[236:237], v[88:89], v[246:247] op_sel_hi:[1,0]
	v_pk_fma_f32 v[2:3], v[88:89], v[246:247], v[2:3] op_sel_hi:[1,0,1]
	v_pk_mul_f32 v[238:239], v[90:91], v[246:247] op_sel_hi:[1,0]
	v_pk_fma_f32 v[4:5], v[90:91], v[246:247], v[4:5] op_sel_hi:[1,0,1]
	ds_read_b32 v230, v223 offset:80
	v_mov_b32_e32 v240, 0x3f000000
	v_pk_fma_f32 v[242:243], v[240:241], v[2:3], v[236:237] op_sel_hi:[0,1,1] neg_lo:[0,0,1] neg_hi:[0,0,1]
	v_pk_fma_f32 v[236:237], v[240:241], v[4:5], v[238:239] op_sel_hi:[0,1,1] neg_lo:[0,0,1] neg_hi:[0,0,1]
	v_cvt_pk_bf16_f32 v242, v242, v243
	v_cvt_pk_bf16_f32 v243, v236, v237
	global_store_dwordx2 v222, v[242:243], s[34:35]
	s_add_u32 s34, s34, 0x800
	s_addc_u32 s35, s35, 0
	s_waitcnt lgkmcnt(5)
	v_xor_b32_e32 v239, 0x80000000, v87
	v_xor_b32_e32 v238, 0x80000000, v86
	v_pk_fma_f32 v[4:5], v[238:239], v[248:249], v[4:5] op_sel_hi:[1,0,1]
	v_pk_fma_f32 v[2:3], v[84:85], v[248:249], v[2:3] op_sel_hi:[1,0,1] neg_lo:[1,0,0] neg_hi:[1,0,0]
	ds_read_b32 v244, v223 offset:76
	s_waitcnt lgkmcnt(5)
	s_waitcnt vmcnt(31)
	v_pk_mul_f32 v[236:237], v[92:93], v[232:233] op_sel_hi:[1,0]
	v_pk_fma_f32 v[2:3], v[92:93], v[232:233], v[2:3] op_sel_hi:[1,0,1]
	v_pk_mul_f32 v[238:239], v[94:95], v[232:233] op_sel_hi:[1,0]
	v_pk_fma_f32 v[4:5], v[94:95], v[232:233], v[4:5] op_sel_hi:[1,0,1]
	ds_read_b32 v246, v223 offset:84
	v_mov_b32_e32 v240, 0x3f000000
	v_pk_fma_f32 v[242:243], v[240:241], v[2:3], v[236:237] op_sel_hi:[0,1,1] neg_lo:[0,0,1] neg_hi:[0,0,1]
	v_pk_fma_f32 v[236:237], v[240:241], v[4:5], v[238:239] op_sel_hi:[0,1,1] neg_lo:[0,0,1] neg_hi:[0,0,1]
	v_cvt_pk_bf16_f32 v242, v242, v243
	v_cvt_pk_bf16_f32 v243, v236, v237
	global_store_dwordx2 v222, v[242:243], s[34:35]
	s_add_u32 s34, s34, 0x800
	s_addc_u32 s35, s35, 0
	s_waitcnt lgkmcnt(5)
	v_xor_b32_e32 v239, 0x80000000, v91
	v_xor_b32_e32 v238, 0x80000000, v90
	v_pk_fma_f32 v[4:5], v[238:239], v[224:225], v[4:5] op_sel_hi:[1,0,1]
	v_pk_fma_f32 v[2:3], v[88:89], v[224:225], v[2:3] op_sel_hi:[1,0,1] neg_lo:[1,0,0] neg_hi:[1,0,0]
	ds_read_b32 v248, v223 offset:80
	s_waitcnt lgkmcnt(5)
	s_waitcnt vmcnt(31)
	v_pk_mul_f32 v[236:237], v[96:97], v[226:227] op_sel_hi:[1,0]
	v_pk_fma_f32 v[2:3], v[96:97], v[226:227], v[2:3] op_sel_hi:[1,0,1]
	v_pk_mul_f32 v[238:239], v[98:99], v[226:227] op_sel_hi:[1,0]
	v_pk_fma_f32 v[4:5], v[98:99], v[226:227], v[4:5] op_sel_hi:[1,0,1]
	ds_read_b32 v232, v223 offset:88
	v_mov_b32_e32 v240, 0x3f000000
	v_pk_fma_f32 v[242:243], v[240:241], v[2:3], v[236:237] op_sel_hi:[0,1,1] neg_lo:[0,0,1] neg_hi:[0,0,1]
	v_pk_fma_f32 v[236:237], v[240:241], v[4:5], v[238:239] op_sel_hi:[0,1,1] neg_lo:[0,0,1] neg_hi:[0,0,1]
	v_cvt_pk_bf16_f32 v242, v242, v243
	v_cvt_pk_bf16_f32 v243, v236, v237
	global_store_dwordx2 v222, v[242:243], s[34:35]
	s_add_u32 s34, s34, 0x800
	s_addc_u32 s35, s35, 0
	s_waitcnt lgkmcnt(5)
	v_xor_b32_e32 v239, 0x80000000, v95
	v_xor_b32_e32 v238, 0x80000000, v94
	v_pk_fma_f32 v[4:5], v[238:239], v[228:229], v[4:5] op_sel_hi:[1,0,1]
	v_pk_fma_f32 v[2:3], v[92:93], v[228:229], v[2:3] op_sel_hi:[1,0,1] neg_lo:[1,0,0] neg_hi:[1,0,0]
	ds_read_b32 v224, v223 offset:84
	s_waitcnt lgkmcnt(5)
	s_waitcnt vmcnt(31)
	v_pk_mul_f32 v[236:237], v[100:101], v[230:231] op_sel_hi:[1,0]
	v_pk_fma_f32 v[2:3], v[100:101], v[230:231], v[2:3] op_sel_hi:[1,0,1]
	v_pk_mul_f32 v[238:239], v[102:103], v[230:231] op_sel_hi:[1,0]
	v_pk_fma_f32 v[4:5], v[102:103], v[230:231], v[4:5] op_sel_hi:[1,0,1]
	ds_read_b32 v226, v223 offset:92
	v_mov_b32_e32 v240, 0x3f000000
	v_pk_fma_f32 v[242:243], v[240:241], v[2:3], v[236:237] op_sel_hi:[0,1,1] neg_lo:[0,0,1] neg_hi:[0,0,1]
	v_pk_fma_f32 v[236:237], v[240:241], v[4:5], v[238:239] op_sel_hi:[0,1,1] neg_lo:[0,0,1] neg_hi:[0,0,1]
	v_cvt_pk_bf16_f32 v242, v242, v243
	v_cvt_pk_bf16_f32 v243, v236, v237
	global_store_dwordx2 v222, v[242:243], s[34:35]
	s_add_u32 s34, s34, 0x800
	s_addc_u32 s35, s35, 0
	s_waitcnt lgkmcnt(5)
	v_xor_b32_e32 v239, 0x80000000, v99
	v_xor_b32_e32 v238, 0x80000000, v98
	v_pk_fma_f32 v[4:5], v[238:239], v[244:245], v[4:5] op_sel_hi:[1,0,1]
	v_pk_fma_f32 v[2:3], v[96:97], v[244:245], v[2:3] op_sel_hi:[1,0,1] neg_lo:[1,0,0] neg_hi:[1,0,0]
	ds_read_b32 v228, v223 offset:88
	s_waitcnt lgkmcnt(5)
	s_waitcnt vmcnt(31)
	v_pk_mul_f32 v[236:237], v[104:105], v[246:247] op_sel_hi:[1,0]
	v_pk_fma_f32 v[2:3], v[104:105], v[246:247], v[2:3] op_sel_hi:[1,0,1]
	v_pk_mul_f32 v[238:239], v[106:107], v[246:247] op_sel_hi:[1,0]
	v_pk_fma_f32 v[4:5], v[106:107], v[246:247], v[4:5] op_sel_hi:[1,0,1]
	ds_read_b32 v230, v223 offset:96
	v_mov_b32_e32 v240, 0x3f000000
	v_pk_fma_f32 v[242:243], v[240:241], v[2:3], v[236:237] op_sel_hi:[0,1,1] neg_lo:[0,0,1] neg_hi:[0,0,1]
	v_pk_fma_f32 v[236:237], v[240:241], v[4:5], v[238:239] op_sel_hi:[0,1,1] neg_lo:[0,0,1] neg_hi:[0,0,1]
	v_cvt_pk_bf16_f32 v242, v242, v243
	v_cvt_pk_bf16_f32 v243, v236, v237
	global_store_dwordx2 v222, v[242:243], s[34:35]
	s_add_u32 s34, s34, 0x800
	s_addc_u32 s35, s35, 0
	s_waitcnt lgkmcnt(5)
	v_xor_b32_e32 v239, 0x80000000, v103
	v_xor_b32_e32 v238, 0x80000000, v102
	v_pk_fma_f32 v[4:5], v[238:239], v[248:249], v[4:5] op_sel_hi:[1,0,1]
	v_pk_fma_f32 v[2:3], v[100:101], v[248:249], v[2:3] op_sel_hi:[1,0,1] neg_lo:[1,0,0] neg_hi:[1,0,0]
	ds_read_b32 v244, v223 offset:92
	s_waitcnt lgkmcnt(5)
	s_waitcnt vmcnt(31)
	v_pk_mul_f32 v[236:237], v[108:109], v[232:233] op_sel_hi:[1,0]
	v_pk_fma_f32 v[2:3], v[108:109], v[232:233], v[2:3] op_sel_hi:[1,0,1]
	v_pk_mul_f32 v[238:239], v[110:111], v[232:233] op_sel_hi:[1,0]
	v_pk_fma_f32 v[4:5], v[110:111], v[232:233], v[4:5] op_sel_hi:[1,0,1]
	ds_read_b32 v246, v223 offset:100
	v_mov_b32_e32 v240, 0x3f000000
	v_pk_fma_f32 v[242:243], v[240:241], v[2:3], v[236:237] op_sel_hi:[0,1,1] neg_lo:[0,0,1] neg_hi:[0,0,1]
	v_pk_fma_f32 v[236:237], v[240:241], v[4:5], v[238:239] op_sel_hi:[0,1,1] neg_lo:[0,0,1] neg_hi:[0,0,1]
	v_cvt_pk_bf16_f32 v242, v242, v243
	v_cvt_pk_bf16_f32 v243, v236, v237
	global_store_dwordx2 v222, v[242:243], s[34:35]
	s_add_u32 s34, s34, 0x800
	s_addc_u32 s35, s35, 0
	s_waitcnt lgkmcnt(5)
	v_xor_b32_e32 v239, 0x80000000, v107
	v_xor_b32_e32 v238, 0x80000000, v106
	v_pk_fma_f32 v[4:5], v[238:239], v[224:225], v[4:5] op_sel_hi:[1,0,1]
	v_pk_fma_f32 v[2:3], v[104:105], v[224:225], v[2:3] op_sel_hi:[1,0,1] neg_lo:[1,0,0] neg_hi:[1,0,0]
	ds_read_b32 v248, v223 offset:96
	s_waitcnt lgkmcnt(5)
	s_waitcnt vmcnt(31)
	v_pk_mul_f32 v[236:237], v[112:113], v[226:227] op_sel_hi:[1,0]
	v_pk_fma_f32 v[2:3], v[112:113], v[226:227], v[2:3] op_sel_hi:[1,0,1]
	v_pk_mul_f32 v[238:239], v[114:115], v[226:227] op_sel_hi:[1,0]
	v_pk_fma_f32 v[4:5], v[114:115], v[226:227], v[4:5] op_sel_hi:[1,0,1]
	ds_read_b32 v232, v223 offset:104
	v_mov_b32_e32 v240, 0x3f000000
	v_pk_fma_f32 v[242:243], v[240:241], v[2:3], v[236:237] op_sel_hi:[0,1,1] neg_lo:[0,0,1] neg_hi:[0,0,1]
	v_pk_fma_f32 v[236:237], v[240:241], v[4:5], v[238:239] op_sel_hi:[0,1,1] neg_lo:[0,0,1] neg_hi:[0,0,1]
	v_cvt_pk_bf16_f32 v242, v242, v243
	v_cvt_pk_bf16_f32 v243, v236, v237
	global_store_dwordx2 v222, v[242:243], s[34:35]
	s_add_u32 s34, s34, 0x800
	s_addc_u32 s35, s35, 0
	s_waitcnt lgkmcnt(5)
	v_xor_b32_e32 v239, 0x80000000, v111
	v_xor_b32_e32 v238, 0x80000000, v110
	v_pk_fma_f32 v[4:5], v[238:239], v[228:229], v[4:5] op_sel_hi:[1,0,1]
	v_pk_fma_f32 v[2:3], v[108:109], v[228:229], v[2:3] op_sel_hi:[1,0,1] neg_lo:[1,0,0] neg_hi:[1,0,0]
	ds_read_b32 v224, v223 offset:100
	s_waitcnt lgkmcnt(5)
	s_waitcnt vmcnt(31)
	v_pk_mul_f32 v[236:237], v[116:117], v[230:231] op_sel_hi:[1,0]
	v_pk_fma_f32 v[2:3], v[116:117], v[230:231], v[2:3] op_sel_hi:[1,0,1]
	v_pk_mul_f32 v[238:239], v[118:119], v[230:231] op_sel_hi:[1,0]
	v_pk_fma_f32 v[4:5], v[118:119], v[230:231], v[4:5] op_sel_hi:[1,0,1]
	ds_read_b32 v226, v223 offset:108
	v_mov_b32_e32 v240, 0x3f000000
	v_pk_fma_f32 v[242:243], v[240:241], v[2:3], v[236:237] op_sel_hi:[0,1,1] neg_lo:[0,0,1] neg_hi:[0,0,1]
	v_pk_fma_f32 v[236:237], v[240:241], v[4:5], v[238:239] op_sel_hi:[0,1,1] neg_lo:[0,0,1] neg_hi:[0,0,1]
	v_cvt_pk_bf16_f32 v242, v242, v243
	v_cvt_pk_bf16_f32 v243, v236, v237
	global_store_dwordx2 v222, v[242:243], s[34:35]
	s_add_u32 s34, s34, 0x800
	s_addc_u32 s35, s35, 0
	s_waitcnt lgkmcnt(5)
	v_xor_b32_e32 v239, 0x80000000, v115
	v_xor_b32_e32 v238, 0x80000000, v114
	v_pk_fma_f32 v[4:5], v[238:239], v[244:245], v[4:5] op_sel_hi:[1,0,1]
	v_pk_fma_f32 v[2:3], v[112:113], v[244:245], v[2:3] op_sel_hi:[1,0,1] neg_lo:[1,0,0] neg_hi:[1,0,0]
	ds_read_b32 v228, v223 offset:104
	s_waitcnt lgkmcnt(5)
	s_waitcnt vmcnt(31)
	v_pk_mul_f32 v[236:237], v[120:121], v[246:247] op_sel_hi:[1,0]
	v_pk_fma_f32 v[2:3], v[120:121], v[246:247], v[2:3] op_sel_hi:[1,0,1]
	v_pk_mul_f32 v[238:239], v[122:123], v[246:247] op_sel_hi:[1,0]
	v_pk_fma_f32 v[4:5], v[122:123], v[246:247], v[4:5] op_sel_hi:[1,0,1]
	ds_read_b32 v230, v223 offset:112
	v_mov_b32_e32 v240, 0x3f000000
	v_pk_fma_f32 v[242:243], v[240:241], v[2:3], v[236:237] op_sel_hi:[0,1,1] neg_lo:[0,0,1] neg_hi:[0,0,1]
	v_pk_fma_f32 v[236:237], v[240:241], v[4:5], v[238:239] op_sel_hi:[0,1,1] neg_lo:[0,0,1] neg_hi:[0,0,1]
	v_cvt_pk_bf16_f32 v242, v242, v243
	v_cvt_pk_bf16_f32 v243, v236, v237
	global_store_dwordx2 v222, v[242:243], s[34:35]
	s_add_u32 s34, s34, 0x800
	s_addc_u32 s35, s35, 0
	s_waitcnt lgkmcnt(5)
	v_xor_b32_e32 v239, 0x80000000, v119
	v_xor_b32_e32 v238, 0x80000000, v118
	v_pk_fma_f32 v[4:5], v[238:239], v[248:249], v[4:5] op_sel_hi:[1,0,1]
	v_pk_fma_f32 v[2:3], v[116:117], v[248:249], v[2:3] op_sel_hi:[1,0,1] neg_lo:[1,0,0] neg_hi:[1,0,0]
	ds_read_b32 v244, v223 offset:108
	s_waitcnt lgkmcnt(5)
	s_waitcnt vmcnt(31)
	v_pk_mul_f32 v[236:237], v[124:125], v[232:233] op_sel_hi:[1,0]
	v_pk_fma_f32 v[2:3], v[124:125], v[232:233], v[2:3] op_sel_hi:[1,0,1]
	v_pk_mul_f32 v[238:239], v[126:127], v[232:233] op_sel_hi:[1,0]
	v_pk_fma_f32 v[4:5], v[126:127], v[232:233], v[4:5] op_sel_hi:[1,0,1]
	ds_read_b32 v246, v223 offset:116
	v_mov_b32_e32 v240, 0x3f000000
	v_pk_fma_f32 v[242:243], v[240:241], v[2:3], v[236:237] op_sel_hi:[0,1,1] neg_lo:[0,0,1] neg_hi:[0,0,1]
	v_pk_fma_f32 v[236:237], v[240:241], v[4:5], v[238:239] op_sel_hi:[0,1,1] neg_lo:[0,0,1] neg_hi:[0,0,1]
	v_cvt_pk_bf16_f32 v242, v242, v243
	v_cvt_pk_bf16_f32 v243, v236, v237
	global_store_dwordx2 v222, v[242:243], s[34:35]
	s_add_u32 s34, s34, 0x800
	s_addc_u32 s35, s35, 0
	s_waitcnt lgkmcnt(5)
	v_xor_b32_e32 v239, 0x80000000, v123
	v_xor_b32_e32 v238, 0x80000000, v122
	v_pk_fma_f32 v[4:5], v[238:239], v[224:225], v[4:5] op_sel_hi:[1,0,1]
	v_pk_fma_f32 v[2:3], v[120:121], v[224:225], v[2:3] op_sel_hi:[1,0,1] neg_lo:[1,0,0] neg_hi:[1,0,0]
	ds_read_b32 v248, v223 offset:112
	s_waitcnt lgkmcnt(5)
	s_waitcnt vmcnt(31)
	v_pk_mul_f32 v[236:237], v[128:129], v[226:227] op_sel_hi:[1,0]
	v_pk_fma_f32 v[2:3], v[128:129], v[226:227], v[2:3] op_sel_hi:[1,0,1]
	v_pk_mul_f32 v[238:239], v[130:131], v[226:227] op_sel_hi:[1,0]
	v_pk_fma_f32 v[4:5], v[130:131], v[226:227], v[4:5] op_sel_hi:[1,0,1]
	ds_read_b32 v232, v223 offset:120
	v_mov_b32_e32 v240, 0x3f000000
	v_pk_fma_f32 v[242:243], v[240:241], v[2:3], v[236:237] op_sel_hi:[0,1,1] neg_lo:[0,0,1] neg_hi:[0,0,1]
	v_pk_fma_f32 v[236:237], v[240:241], v[4:5], v[238:239] op_sel_hi:[0,1,1] neg_lo:[0,0,1] neg_hi:[0,0,1]
	v_cvt_pk_bf16_f32 v242, v242, v243
	v_cvt_pk_bf16_f32 v243, v236, v237
	global_store_dwordx2 v222, v[242:243], s[34:35]
	s_add_u32 s34, s34, 0x800
	s_addc_u32 s35, s35, 0
	s_waitcnt lgkmcnt(5)
	v_xor_b32_e32 v239, 0x80000000, v127
	v_xor_b32_e32 v238, 0x80000000, v126
	v_pk_fma_f32 v[4:5], v[238:239], v[228:229], v[4:5] op_sel_hi:[1,0,1]
	v_pk_fma_f32 v[2:3], v[124:125], v[228:229], v[2:3] op_sel_hi:[1,0,1] neg_lo:[1,0,0] neg_hi:[1,0,0]
	ds_read_b32 v224, v223 offset:116
	s_waitcnt lgkmcnt(5)
	s_waitcnt vmcnt(31)
	v_pk_mul_f32 v[236:237], v[132:133], v[230:231] op_sel_hi:[1,0]
	v_pk_fma_f32 v[2:3], v[132:133], v[230:231], v[2:3] op_sel_hi:[1,0,1]
	v_pk_mul_f32 v[238:239], v[134:135], v[230:231] op_sel_hi:[1,0]
	v_pk_fma_f32 v[4:5], v[134:135], v[230:231], v[4:5] op_sel_hi:[1,0,1]
	ds_read_b32 v226, v223 offset:124
	v_mov_b32_e32 v240, 0x3f000000
	v_pk_fma_f32 v[242:243], v[240:241], v[2:3], v[236:237] op_sel_hi:[0,1,1] neg_lo:[0,0,1] neg_hi:[0,0,1]
	v_pk_fma_f32 v[236:237], v[240:241], v[4:5], v[238:239] op_sel_hi:[0,1,1] neg_lo:[0,0,1] neg_hi:[0,0,1]
	v_cvt_pk_bf16_f32 v242, v242, v243
	v_cvt_pk_bf16_f32 v243, v236, v237
	global_store_dwordx2 v222, v[242:243], s[34:35]
	s_add_u32 s34, s34, 0x800
	s_addc_u32 s35, s35, 0
	s_waitcnt lgkmcnt(5)
	v_xor_b32_e32 v239, 0x80000000, v131
	v_xor_b32_e32 v238, 0x80000000, v130
	v_pk_fma_f32 v[4:5], v[238:239], v[244:245], v[4:5] op_sel_hi:[1,0,1]
	v_pk_fma_f32 v[2:3], v[128:129], v[244:245], v[2:3] op_sel_hi:[1,0,1] neg_lo:[1,0,0] neg_hi:[1,0,0]
	ds_read_b32 v228, v223 offset:120
	s_waitcnt lgkmcnt(5)
	s_waitcnt vmcnt(31)
	v_pk_mul_f32 v[236:237], v[136:137], v[246:247] op_sel_hi:[1,0]
	v_pk_fma_f32 v[2:3], v[136:137], v[246:247], v[2:3] op_sel_hi:[1,0,1]
	v_pk_mul_f32 v[238:239], v[138:139], v[246:247] op_sel_hi:[1,0]
	v_pk_fma_f32 v[4:5], v[138:139], v[246:247], v[4:5] op_sel_hi:[1,0,1]
	ds_read_b32 v230, v223 offset:128
	v_mov_b32_e32 v240, 0x3f000000
	v_pk_fma_f32 v[242:243], v[240:241], v[2:3], v[236:237] op_sel_hi:[0,1,1] neg_lo:[0,0,1] neg_hi:[0,0,1]
	v_pk_fma_f32 v[236:237], v[240:241], v[4:5], v[238:239] op_sel_hi:[0,1,1] neg_lo:[0,0,1] neg_hi:[0,0,1]
	v_cvt_pk_bf16_f32 v242, v242, v243
	v_cvt_pk_bf16_f32 v243, v236, v237
	global_store_dwordx2 v222, v[242:243], s[34:35]
	s_add_u32 s34, s34, 0x800
	s_addc_u32 s35, s35, 0
	s_waitcnt lgkmcnt(5)
	v_xor_b32_e32 v239, 0x80000000, v135
	v_xor_b32_e32 v238, 0x80000000, v134
	v_pk_fma_f32 v[4:5], v[238:239], v[248:249], v[4:5] op_sel_hi:[1,0,1]
	v_pk_fma_f32 v[2:3], v[132:133], v[248:249], v[2:3] op_sel_hi:[1,0,1] neg_lo:[1,0,0] neg_hi:[1,0,0]
	ds_read_b32 v244, v223 offset:124
	s_waitcnt lgkmcnt(5)
	s_waitcnt vmcnt(31)
	v_pk_mul_f32 v[236:237], v[140:141], v[232:233] op_sel_hi:[1,0]
	v_pk_fma_f32 v[2:3], v[140:141], v[232:233], v[2:3] op_sel_hi:[1,0,1]
	v_pk_mul_f32 v[238:239], v[142:143], v[232:233] op_sel_hi:[1,0]
	v_pk_fma_f32 v[4:5], v[142:143], v[232:233], v[4:5] op_sel_hi:[1,0,1]
	ds_read_b32 v246, v223 offset:132
	v_mov_b32_e32 v240, 0x3f000000
	v_pk_fma_f32 v[242:243], v[240:241], v[2:3], v[236:237] op_sel_hi:[0,1,1] neg_lo:[0,0,1] neg_hi:[0,0,1]
	v_pk_fma_f32 v[236:237], v[240:241], v[4:5], v[238:239] op_sel_hi:[0,1,1] neg_lo:[0,0,1] neg_hi:[0,0,1]
	v_cvt_pk_bf16_f32 v242, v242, v243
	v_cvt_pk_bf16_f32 v243, v236, v237
	global_store_dwordx2 v222, v[242:243], s[34:35]
	s_add_u32 s34, s34, 0x800
	s_addc_u32 s35, s35, 0
	s_waitcnt lgkmcnt(5)
	v_xor_b32_e32 v239, 0x80000000, v139
	v_xor_b32_e32 v238, 0x80000000, v138
	v_pk_fma_f32 v[4:5], v[238:239], v[224:225], v[4:5] op_sel_hi:[1,0,1]
	v_pk_fma_f32 v[2:3], v[136:137], v[224:225], v[2:3] op_sel_hi:[1,0,1] neg_lo:[1,0,0] neg_hi:[1,0,0]
	ds_read_b32 v248, v223 offset:128
	s_waitcnt lgkmcnt(5)
	s_waitcnt vmcnt(31)
	v_pk_mul_f32 v[236:237], v[144:145], v[226:227] op_sel_hi:[1,0]
	v_pk_fma_f32 v[2:3], v[144:145], v[226:227], v[2:3] op_sel_hi:[1,0,1]
	v_pk_mul_f32 v[238:239], v[146:147], v[226:227] op_sel_hi:[1,0]
	v_pk_fma_f32 v[4:5], v[146:147], v[226:227], v[4:5] op_sel_hi:[1,0,1]
	ds_read_b32 v232, v223 offset:136
	v_mov_b32_e32 v240, 0x3f000000
	v_pk_fma_f32 v[242:243], v[240:241], v[2:3], v[236:237] op_sel_hi:[0,1,1] neg_lo:[0,0,1] neg_hi:[0,0,1]
	v_pk_fma_f32 v[236:237], v[240:241], v[4:5], v[238:239] op_sel_hi:[0,1,1] neg_lo:[0,0,1] neg_hi:[0,0,1]
	v_cvt_pk_bf16_f32 v242, v242, v243
	v_cvt_pk_bf16_f32 v243, v236, v237
	global_store_dwordx2 v222, v[242:243], s[34:35]
	s_add_u32 s34, s34, 0x800
	s_addc_u32 s35, s35, 0
	s_waitcnt lgkmcnt(5)
	v_xor_b32_e32 v239, 0x80000000, v143
	v_xor_b32_e32 v238, 0x80000000, v142
	v_pk_fma_f32 v[4:5], v[238:239], v[228:229], v[4:5] op_sel_hi:[1,0,1]
	v_pk_fma_f32 v[2:3], v[140:141], v[228:229], v[2:3] op_sel_hi:[1,0,1] neg_lo:[1,0,0] neg_hi:[1,0,0]
	ds_read_b32 v224, v223 offset:132
	s_waitcnt lgkmcnt(5)
	s_waitcnt vmcnt(31)
	v_pk_mul_f32 v[236:237], v[148:149], v[230:231] op_sel_hi:[1,0]
	v_pk_fma_f32 v[2:3], v[148:149], v[230:231], v[2:3] op_sel_hi:[1,0,1]
	v_pk_mul_f32 v[238:239], v[150:151], v[230:231] op_sel_hi:[1,0]
	v_pk_fma_f32 v[4:5], v[150:151], v[230:231], v[4:5] op_sel_hi:[1,0,1]
	ds_read_b32 v226, v223 offset:140
	v_mov_b32_e32 v240, 0x3f000000
	v_pk_fma_f32 v[242:243], v[240:241], v[2:3], v[236:237] op_sel_hi:[0,1,1] neg_lo:[0,0,1] neg_hi:[0,0,1]
	v_pk_fma_f32 v[236:237], v[240:241], v[4:5], v[238:239] op_sel_hi:[0,1,1] neg_lo:[0,0,1] neg_hi:[0,0,1]
	v_cvt_pk_bf16_f32 v242, v242, v243
	v_cvt_pk_bf16_f32 v243, v236, v237
	global_store_dwordx2 v222, v[242:243], s[34:35]
	s_add_u32 s34, s34, 0x800
	s_addc_u32 s35, s35, 0
	s_waitcnt lgkmcnt(5)
	v_xor_b32_e32 v239, 0x80000000, v147
	v_xor_b32_e32 v238, 0x80000000, v146
	v_pk_fma_f32 v[4:5], v[238:239], v[244:245], v[4:5] op_sel_hi:[1,0,1]
	v_pk_fma_f32 v[2:3], v[144:145], v[244:245], v[2:3] op_sel_hi:[1,0,1] neg_lo:[1,0,0] neg_hi:[1,0,0]
	ds_read_b32 v228, v223 offset:136
	s_waitcnt lgkmcnt(5)
	s_waitcnt vmcnt(31)
	v_pk_mul_f32 v[236:237], v[152:153], v[246:247] op_sel_hi:[1,0]
	v_pk_fma_f32 v[2:3], v[152:153], v[246:247], v[2:3] op_sel_hi:[1,0,1]
	v_pk_mul_f32 v[238:239], v[154:155], v[246:247] op_sel_hi:[1,0]
	v_pk_fma_f32 v[4:5], v[154:155], v[246:247], v[4:5] op_sel_hi:[1,0,1]
	ds_read_b32 v230, v223 offset:144
	v_mov_b32_e32 v240, 0x3f000000
	v_pk_fma_f32 v[242:243], v[240:241], v[2:3], v[236:237] op_sel_hi:[0,1,1] neg_lo:[0,0,1] neg_hi:[0,0,1]
	v_pk_fma_f32 v[236:237], v[240:241], v[4:5], v[238:239] op_sel_hi:[0,1,1] neg_lo:[0,0,1] neg_hi:[0,0,1]
	v_cvt_pk_bf16_f32 v242, v242, v243
	v_cvt_pk_bf16_f32 v243, v236, v237
	global_store_dwordx2 v222, v[242:243], s[34:35]
	s_add_u32 s34, s34, 0x800
	s_addc_u32 s35, s35, 0
	s_waitcnt lgkmcnt(5)
	v_xor_b32_e32 v239, 0x80000000, v151
	v_xor_b32_e32 v238, 0x80000000, v150
	v_pk_fma_f32 v[4:5], v[238:239], v[248:249], v[4:5] op_sel_hi:[1,0,1]
	v_pk_fma_f32 v[2:3], v[148:149], v[248:249], v[2:3] op_sel_hi:[1,0,1] neg_lo:[1,0,0] neg_hi:[1,0,0]
	ds_read_b32 v244, v223 offset:140
	s_waitcnt lgkmcnt(5)
	s_waitcnt vmcnt(31)
	v_pk_mul_f32 v[236:237], v[156:157], v[232:233] op_sel_hi:[1,0]
	v_pk_fma_f32 v[2:3], v[156:157], v[232:233], v[2:3] op_sel_hi:[1,0,1]
	v_pk_mul_f32 v[238:239], v[158:159], v[232:233] op_sel_hi:[1,0]
	v_pk_fma_f32 v[4:5], v[158:159], v[232:233], v[4:5] op_sel_hi:[1,0,1]
	ds_read_b32 v246, v223 offset:148
	v_mov_b32_e32 v240, 0x3f000000
	v_pk_fma_f32 v[242:243], v[240:241], v[2:3], v[236:237] op_sel_hi:[0,1,1] neg_lo:[0,0,1] neg_hi:[0,0,1]
	v_pk_fma_f32 v[236:237], v[240:241], v[4:5], v[238:239] op_sel_hi:[0,1,1] neg_lo:[0,0,1] neg_hi:[0,0,1]
	v_cvt_pk_bf16_f32 v242, v242, v243
	v_cvt_pk_bf16_f32 v243, v236, v237
	global_store_dwordx2 v222, v[242:243], s[34:35]
	s_add_u32 s34, s34, 0x800
	s_addc_u32 s35, s35, 0
	s_waitcnt lgkmcnt(5)
	v_xor_b32_e32 v239, 0x80000000, v155
	v_xor_b32_e32 v238, 0x80000000, v154
	v_pk_fma_f32 v[4:5], v[238:239], v[224:225], v[4:5] op_sel_hi:[1,0,1]
	v_pk_fma_f32 v[2:3], v[152:153], v[224:225], v[2:3] op_sel_hi:[1,0,1] neg_lo:[1,0,0] neg_hi:[1,0,0]
	ds_read_b32 v248, v223 offset:144
	s_waitcnt lgkmcnt(5)
	s_waitcnt vmcnt(31)
	v_pk_mul_f32 v[236:237], v[160:161], v[226:227] op_sel_hi:[1,0]
	v_pk_fma_f32 v[2:3], v[160:161], v[226:227], v[2:3] op_sel_hi:[1,0,1]
	v_pk_mul_f32 v[238:239], v[162:163], v[226:227] op_sel_hi:[1,0]
	v_pk_fma_f32 v[4:5], v[162:163], v[226:227], v[4:5] op_sel_hi:[1,0,1]
	ds_read_b32 v232, v223 offset:152
	v_mov_b32_e32 v240, 0x3f000000
	v_pk_fma_f32 v[242:243], v[240:241], v[2:3], v[236:237] op_sel_hi:[0,1,1] neg_lo:[0,0,1] neg_hi:[0,0,1]
	v_pk_fma_f32 v[236:237], v[240:241], v[4:5], v[238:239] op_sel_hi:[0,1,1] neg_lo:[0,0,1] neg_hi:[0,0,1]
	v_cvt_pk_bf16_f32 v242, v242, v243
	v_cvt_pk_bf16_f32 v243, v236, v237
	global_store_dwordx2 v222, v[242:243], s[34:35]
	s_add_u32 s34, s34, 0x800
	s_addc_u32 s35, s35, 0
	s_waitcnt lgkmcnt(5)
	v_xor_b32_e32 v239, 0x80000000, v159
	v_xor_b32_e32 v238, 0x80000000, v158
	v_pk_fma_f32 v[4:5], v[238:239], v[228:229], v[4:5] op_sel_hi:[1,0,1]
	v_pk_fma_f32 v[2:3], v[156:157], v[228:229], v[2:3] op_sel_hi:[1,0,1] neg_lo:[1,0,0] neg_hi:[1,0,0]
	ds_read_b32 v224, v223 offset:148
	s_waitcnt lgkmcnt(5)
	s_waitcnt vmcnt(31)
	v_pk_mul_f32 v[236:237], v[164:165], v[230:231] op_sel_hi:[1,0]
	v_pk_fma_f32 v[2:3], v[164:165], v[230:231], v[2:3] op_sel_hi:[1,0,1]
	v_pk_mul_f32 v[238:239], v[166:167], v[230:231] op_sel_hi:[1,0]
	v_pk_fma_f32 v[4:5], v[166:167], v[230:231], v[4:5] op_sel_hi:[1,0,1]
	ds_read_b32 v226, v223 offset:156
	v_mov_b32_e32 v240, 0x3f000000
	v_pk_fma_f32 v[242:243], v[240:241], v[2:3], v[236:237] op_sel_hi:[0,1,1] neg_lo:[0,0,1] neg_hi:[0,0,1]
	v_pk_fma_f32 v[236:237], v[240:241], v[4:5], v[238:239] op_sel_hi:[0,1,1] neg_lo:[0,0,1] neg_hi:[0,0,1]
	v_cvt_pk_bf16_f32 v242, v242, v243
	v_cvt_pk_bf16_f32 v243, v236, v237
	global_store_dwordx2 v222, v[242:243], s[34:35]
	s_add_u32 s34, s34, 0x800
	s_addc_u32 s35, s35, 0
	s_waitcnt lgkmcnt(5)
	v_xor_b32_e32 v239, 0x80000000, v163
	v_xor_b32_e32 v238, 0x80000000, v162
	v_pk_fma_f32 v[4:5], v[238:239], v[244:245], v[4:5] op_sel_hi:[1,0,1]
	v_pk_fma_f32 v[2:3], v[160:161], v[244:245], v[2:3] op_sel_hi:[1,0,1] neg_lo:[1,0,0] neg_hi:[1,0,0]
	ds_read_b32 v228, v223 offset:152
	s_waitcnt lgkmcnt(5)
	s_waitcnt vmcnt(31)
	v_pk_mul_f32 v[236:237], v[168:169], v[246:247] op_sel_hi:[1,0]
	v_pk_fma_f32 v[2:3], v[168:169], v[246:247], v[2:3] op_sel_hi:[1,0,1]
	v_pk_mul_f32 v[238:239], v[170:171], v[246:247] op_sel_hi:[1,0]
	v_pk_fma_f32 v[4:5], v[170:171], v[246:247], v[4:5] op_sel_hi:[1,0,1]
	ds_read_b32 v230, v223 offset:160
	v_mov_b32_e32 v240, 0x3f000000
	v_pk_fma_f32 v[242:243], v[240:241], v[2:3], v[236:237] op_sel_hi:[0,1,1] neg_lo:[0,0,1] neg_hi:[0,0,1]
	v_pk_fma_f32 v[236:237], v[240:241], v[4:5], v[238:239] op_sel_hi:[0,1,1] neg_lo:[0,0,1] neg_hi:[0,0,1]
	v_cvt_pk_bf16_f32 v242, v242, v243
	v_cvt_pk_bf16_f32 v243, v236, v237
	global_store_dwordx2 v222, v[242:243], s[34:35]
	s_add_u32 s34, s34, 0x800
	s_addc_u32 s35, s35, 0
	s_waitcnt lgkmcnt(5)
	v_xor_b32_e32 v239, 0x80000000, v167
	v_xor_b32_e32 v238, 0x80000000, v166
	v_pk_fma_f32 v[4:5], v[238:239], v[248:249], v[4:5] op_sel_hi:[1,0,1]
	v_pk_fma_f32 v[2:3], v[164:165], v[248:249], v[2:3] op_sel_hi:[1,0,1] neg_lo:[1,0,0] neg_hi:[1,0,0]
	ds_read_b32 v244, v223 offset:156
	s_waitcnt lgkmcnt(5)
	s_waitcnt vmcnt(31)
	v_pk_mul_f32 v[236:237], v[172:173], v[232:233] op_sel_hi:[1,0]
	v_pk_fma_f32 v[2:3], v[172:173], v[232:233], v[2:3] op_sel_hi:[1,0,1]
	v_pk_mul_f32 v[238:239], v[174:175], v[232:233] op_sel_hi:[1,0]
	v_pk_fma_f32 v[4:5], v[174:175], v[232:233], v[4:5] op_sel_hi:[1,0,1]
	ds_read_b32 v246, v223 offset:164
	v_mov_b32_e32 v240, 0x3f000000
	v_pk_fma_f32 v[242:243], v[240:241], v[2:3], v[236:237] op_sel_hi:[0,1,1] neg_lo:[0,0,1] neg_hi:[0,0,1]
	v_pk_fma_f32 v[236:237], v[240:241], v[4:5], v[238:239] op_sel_hi:[0,1,1] neg_lo:[0,0,1] neg_hi:[0,0,1]
	v_cvt_pk_bf16_f32 v242, v242, v243
	v_cvt_pk_bf16_f32 v243, v236, v237
	global_store_dwordx2 v222, v[242:243], s[34:35]
	s_add_u32 s34, s34, 0x800
	s_addc_u32 s35, s35, 0
	s_waitcnt lgkmcnt(5)
	v_xor_b32_e32 v239, 0x80000000, v171
	v_xor_b32_e32 v238, 0x80000000, v170
	v_pk_fma_f32 v[4:5], v[238:239], v[224:225], v[4:5] op_sel_hi:[1,0,1]
	v_pk_fma_f32 v[2:3], v[168:169], v[224:225], v[2:3] op_sel_hi:[1,0,1] neg_lo:[1,0,0] neg_hi:[1,0,0]
	ds_read_b32 v248, v223 offset:160
	s_waitcnt lgkmcnt(5)
	s_waitcnt vmcnt(31)
	v_pk_mul_f32 v[236:237], v[176:177], v[226:227] op_sel_hi:[1,0]
	v_pk_fma_f32 v[2:3], v[176:177], v[226:227], v[2:3] op_sel_hi:[1,0,1]
	v_pk_mul_f32 v[238:239], v[178:179], v[226:227] op_sel_hi:[1,0]
	v_pk_fma_f32 v[4:5], v[178:179], v[226:227], v[4:5] op_sel_hi:[1,0,1]
	ds_read_b32 v232, v223 offset:168
	v_mov_b32_e32 v240, 0x3f000000
	v_pk_fma_f32 v[242:243], v[240:241], v[2:3], v[236:237] op_sel_hi:[0,1,1] neg_lo:[0,0,1] neg_hi:[0,0,1]
	v_pk_fma_f32 v[236:237], v[240:241], v[4:5], v[238:239] op_sel_hi:[0,1,1] neg_lo:[0,0,1] neg_hi:[0,0,1]
	v_cvt_pk_bf16_f32 v242, v242, v243
	v_cvt_pk_bf16_f32 v243, v236, v237
	global_store_dwordx2 v222, v[242:243], s[34:35]
	s_add_u32 s34, s34, 0x800
	s_addc_u32 s35, s35, 0
	s_waitcnt lgkmcnt(5)
	v_xor_b32_e32 v239, 0x80000000, v175
	v_xor_b32_e32 v238, 0x80000000, v174
	v_pk_fma_f32 v[4:5], v[238:239], v[228:229], v[4:5] op_sel_hi:[1,0,1]
	v_pk_fma_f32 v[2:3], v[172:173], v[228:229], v[2:3] op_sel_hi:[1,0,1] neg_lo:[1,0,0] neg_hi:[1,0,0]
	ds_read_b32 v224, v223 offset:164
	s_waitcnt lgkmcnt(5)
	s_waitcnt vmcnt(31)
	v_pk_mul_f32 v[236:237], v[180:181], v[230:231] op_sel_hi:[1,0]
	v_pk_fma_f32 v[2:3], v[180:181], v[230:231], v[2:3] op_sel_hi:[1,0,1]
	v_pk_mul_f32 v[238:239], v[182:183], v[230:231] op_sel_hi:[1,0]
	v_pk_fma_f32 v[4:5], v[182:183], v[230:231], v[4:5] op_sel_hi:[1,0,1]
	ds_read_b32 v226, v223 offset:172
	v_mov_b32_e32 v240, 0x3f000000
	v_pk_fma_f32 v[242:243], v[240:241], v[2:3], v[236:237] op_sel_hi:[0,1,1] neg_lo:[0,0,1] neg_hi:[0,0,1]
	v_pk_fma_f32 v[236:237], v[240:241], v[4:5], v[238:239] op_sel_hi:[0,1,1] neg_lo:[0,0,1] neg_hi:[0,0,1]
	v_cvt_pk_bf16_f32 v242, v242, v243
	v_cvt_pk_bf16_f32 v243, v236, v237
	global_store_dwordx2 v222, v[242:243], s[34:35]
	s_add_u32 s34, s34, 0x800
	s_addc_u32 s35, s35, 0
	s_waitcnt lgkmcnt(5)
	v_xor_b32_e32 v239, 0x80000000, v179
	v_xor_b32_e32 v238, 0x80000000, v178
	v_pk_fma_f32 v[4:5], v[238:239], v[244:245], v[4:5] op_sel_hi:[1,0,1]
	v_pk_fma_f32 v[2:3], v[176:177], v[244:245], v[2:3] op_sel_hi:[1,0,1] neg_lo:[1,0,0] neg_hi:[1,0,0]
	ds_read_b32 v228, v223 offset:168
	s_waitcnt lgkmcnt(5)
	s_waitcnt vmcnt(31)
	v_pk_mul_f32 v[236:237], v[184:185], v[246:247] op_sel_hi:[1,0]
	v_pk_fma_f32 v[2:3], v[184:185], v[246:247], v[2:3] op_sel_hi:[1,0,1]
	v_pk_mul_f32 v[238:239], v[186:187], v[246:247] op_sel_hi:[1,0]
	v_pk_fma_f32 v[4:5], v[186:187], v[246:247], v[4:5] op_sel_hi:[1,0,1]
	ds_read_b32 v230, v223 offset:176
	v_mov_b32_e32 v240, 0x3f000000
	v_pk_fma_f32 v[242:243], v[240:241], v[2:3], v[236:237] op_sel_hi:[0,1,1] neg_lo:[0,0,1] neg_hi:[0,0,1]
	v_pk_fma_f32 v[236:237], v[240:241], v[4:5], v[238:239] op_sel_hi:[0,1,1] neg_lo:[0,0,1] neg_hi:[0,0,1]
	v_cvt_pk_bf16_f32 v242, v242, v243
	v_cvt_pk_bf16_f32 v243, v236, v237
	global_store_dwordx2 v222, v[242:243], s[34:35]
	s_add_u32 s34, s34, 0x800
	s_addc_u32 s35, s35, 0
	s_waitcnt lgkmcnt(5)
	v_xor_b32_e32 v239, 0x80000000, v183
	v_xor_b32_e32 v238, 0x80000000, v182
	v_pk_fma_f32 v[4:5], v[238:239], v[248:249], v[4:5] op_sel_hi:[1,0,1]
	v_pk_fma_f32 v[2:3], v[180:181], v[248:249], v[2:3] op_sel_hi:[1,0,1] neg_lo:[1,0,0] neg_hi:[1,0,0]
	ds_read_b32 v244, v223 offset:172
	s_waitcnt lgkmcnt(5)
	s_waitcnt vmcnt(31)
	v_pk_mul_f32 v[236:237], v[188:189], v[232:233] op_sel_hi:[1,0]
	v_pk_fma_f32 v[2:3], v[188:189], v[232:233], v[2:3] op_sel_hi:[1,0,1]
	v_pk_mul_f32 v[238:239], v[190:191], v[232:233] op_sel_hi:[1,0]
	v_pk_fma_f32 v[4:5], v[190:191], v[232:233], v[4:5] op_sel_hi:[1,0,1]
	ds_read_b32 v246, v223 offset:180
	v_mov_b32_e32 v240, 0x3f000000
	v_pk_fma_f32 v[242:243], v[240:241], v[2:3], v[236:237] op_sel_hi:[0,1,1] neg_lo:[0,0,1] neg_hi:[0,0,1]
	v_pk_fma_f32 v[236:237], v[240:241], v[4:5], v[238:239] op_sel_hi:[0,1,1] neg_lo:[0,0,1] neg_hi:[0,0,1]
	v_cvt_pk_bf16_f32 v242, v242, v243
	v_cvt_pk_bf16_f32 v243, v236, v237
	global_store_dwordx2 v222, v[242:243], s[34:35]
	s_add_u32 s34, s34, 0x800
	s_addc_u32 s35, s35, 0
	s_waitcnt lgkmcnt(5)
	v_xor_b32_e32 v239, 0x80000000, v187
	v_xor_b32_e32 v238, 0x80000000, v186
	v_pk_fma_f32 v[4:5], v[238:239], v[224:225], v[4:5] op_sel_hi:[1,0,1]
	v_pk_fma_f32 v[2:3], v[184:185], v[224:225], v[2:3] op_sel_hi:[1,0,1] neg_lo:[1,0,0] neg_hi:[1,0,0]
	ds_read_b32 v248, v223 offset:176
	s_waitcnt lgkmcnt(5)
	s_waitcnt vmcnt(31)
	v_pk_mul_f32 v[236:237], v[192:193], v[226:227] op_sel_hi:[1,0]
	v_pk_fma_f32 v[2:3], v[192:193], v[226:227], v[2:3] op_sel_hi:[1,0,1]
	v_pk_mul_f32 v[238:239], v[194:195], v[226:227] op_sel_hi:[1,0]
	v_pk_fma_f32 v[4:5], v[194:195], v[226:227], v[4:5] op_sel_hi:[1,0,1]
	ds_read_b32 v232, v223 offset:184
	v_mov_b32_e32 v240, 0x3f000000
	v_pk_fma_f32 v[242:243], v[240:241], v[2:3], v[236:237] op_sel_hi:[0,1,1] neg_lo:[0,0,1] neg_hi:[0,0,1]
	v_pk_fma_f32 v[236:237], v[240:241], v[4:5], v[238:239] op_sel_hi:[0,1,1] neg_lo:[0,0,1] neg_hi:[0,0,1]
	v_cvt_pk_bf16_f32 v242, v242, v243
	v_cvt_pk_bf16_f32 v243, v236, v237
	global_store_dwordx2 v222, v[242:243], s[34:35]
	s_add_u32 s34, s34, 0x800
	s_addc_u32 s35, s35, 0
	s_waitcnt lgkmcnt(5)
	v_xor_b32_e32 v239, 0x80000000, v191
	v_xor_b32_e32 v238, 0x80000000, v190
	v_pk_fma_f32 v[4:5], v[238:239], v[228:229], v[4:5] op_sel_hi:[1,0,1]
	v_pk_fma_f32 v[2:3], v[188:189], v[228:229], v[2:3] op_sel_hi:[1,0,1] neg_lo:[1,0,0] neg_hi:[1,0,0]
	ds_read_b32 v224, v223 offset:180
	s_waitcnt lgkmcnt(5)
	s_waitcnt vmcnt(31)
	v_pk_mul_f32 v[236:237], v[196:197], v[230:231] op_sel_hi:[1,0]
	v_pk_fma_f32 v[2:3], v[196:197], v[230:231], v[2:3] op_sel_hi:[1,0,1]
	v_pk_mul_f32 v[238:239], v[198:199], v[230:231] op_sel_hi:[1,0]
	v_pk_fma_f32 v[4:5], v[198:199], v[230:231], v[4:5] op_sel_hi:[1,0,1]
	v_mov_b32_e32 v240, 0x3f000000
	v_pk_fma_f32 v[242:243], v[240:241], v[2:3], v[236:237] op_sel_hi:[0,1,1] neg_lo:[0,0,1] neg_hi:[0,0,1]
	v_pk_fma_f32 v[236:237], v[240:241], v[4:5], v[238:239] op_sel_hi:[0,1,1] neg_lo:[0,0,1] neg_hi:[0,0,1]
	v_cvt_pk_bf16_f32 v242, v242, v243
	v_cvt_pk_bf16_f32 v243, v236, v237
	global_store_dwordx2 v222, v[242:243], s[34:35]
	s_add_u32 s34, s34, 0x800
	s_addc_u32 s35, s35, 0
	s_waitcnt lgkmcnt(4)
	v_xor_b32_e32 v239, 0x80000000, v195
	v_xor_b32_e32 v238, 0x80000000, v194
	v_pk_fma_f32 v[4:5], v[238:239], v[244:245], v[4:5] op_sel_hi:[1,0,1]
	v_pk_fma_f32 v[2:3], v[192:193], v[244:245], v[2:3] op_sel_hi:[1,0,1] neg_lo:[1,0,0] neg_hi:[1,0,0]
	s_waitcnt lgkmcnt(3)
	s_waitcnt vmcnt(31)
	v_pk_mul_f32 v[236:237], v[200:201], v[246:247] op_sel_hi:[1,0]
	v_pk_fma_f32 v[2:3], v[200:201], v[246:247], v[2:3] op_sel_hi:[1,0,1]
	v_pk_mul_f32 v[238:239], v[202:203], v[246:247] op_sel_hi:[1,0]
	v_pk_fma_f32 v[4:5], v[202:203], v[246:247], v[4:5] op_sel_hi:[1,0,1]
	v_mov_b32_e32 v240, 0x3f000000
	v_pk_fma_f32 v[242:243], v[240:241], v[2:3], v[236:237] op_sel_hi:[0,1,1] neg_lo:[0,0,1] neg_hi:[0,0,1]
	v_pk_fma_f32 v[236:237], v[240:241], v[4:5], v[238:239] op_sel_hi:[0,1,1] neg_lo:[0,0,1] neg_hi:[0,0,1]
	v_cvt_pk_bf16_f32 v242, v242, v243
	v_cvt_pk_bf16_f32 v243, v236, v237
	global_store_dwordx2 v222, v[242:243], s[34:35]
	s_add_u32 s34, s34, 0x800
	s_addc_u32 s35, s35, 0
	s_waitcnt lgkmcnt(2)
	v_xor_b32_e32 v239, 0x80000000, v199
	v_xor_b32_e32 v238, 0x80000000, v198
	v_pk_fma_f32 v[4:5], v[238:239], v[248:249], v[4:5] op_sel_hi:[1,0,1]
	v_pk_fma_f32 v[2:3], v[196:197], v[248:249], v[2:3] op_sel_hi:[1,0,1] neg_lo:[1,0,0] neg_hi:[1,0,0]
	s_waitcnt lgkmcnt(1)
	s_waitcnt vmcnt(31)
	v_pk_mul_f32 v[236:237], v[216:217], v[232:233] op_sel_hi:[1,0]
	v_pk_fma_f32 v[2:3], v[216:217], v[232:233], v[2:3] op_sel_hi:[1,0,1]
	v_pk_mul_f32 v[238:239], v[218:219], v[232:233] op_sel_hi:[1,0]
	v_pk_fma_f32 v[4:5], v[218:219], v[232:233], v[4:5] op_sel_hi:[1,0,1]
	v_mov_b32_e32 v240, 0x3f000000
	v_pk_fma_f32 v[242:243], v[240:241], v[2:3], v[236:237] op_sel_hi:[0,1,1] neg_lo:[0,0,1] neg_hi:[0,0,1]
	v_pk_fma_f32 v[236:237], v[240:241], v[4:5], v[238:239] op_sel_hi:[0,1,1] neg_lo:[0,0,1] neg_hi:[0,0,1]
	v_cvt_pk_bf16_f32 v242, v242, v243
	v_cvt_pk_bf16_f32 v243, v236, v237
	global_store_dwordx2 v222, v[242:243], s[34:35]
	s_add_u32 s34, s34, 0x800
	s_addc_u32 s35, s35, 0
	s_waitcnt lgkmcnt(0)
	v_xor_b32_e32 v239, 0x80000000, v203
	v_xor_b32_e32 v238, 0x80000000, v202
	v_pk_fma_f32 v[4:5], v[238:239], v[224:225], v[4:5] op_sel_hi:[1,0,1]
	v_pk_fma_f32 v[2:3], v[200:201], v[224:225], v[2:3] op_sel_hi:[1,0,1] neg_lo:[1,0,0] neg_hi:[1,0,0]
	s_branch .Lpool_done
.Lpool_v1:
	ds_read_b32 v224, v223 offset:48
	ds_read_b32 v226, v223 offset:52
	ds_read_b32 v228, v223 offset:56
	ds_read_b32 v230, v223 offset:60
	ds_read_b32 v244, v223 offset:48
	ds_read_b32 v246, v223 offset:64
	v_mov_b32_e32 v2, 0
	v_mov_b32_e32 v3, 0
	v_mov_b32_e32 v4, 0
	v_mov_b32_e32 v5, 0
	s_cmp_eq_u32 s14, 0
	s_cbranch_scc1 .Lpool_v1_nopre
	s_waitcnt vmcnt(32)
	s_waitcnt lgkmcnt(5)
	v_pk_fma_f32 v[4:5], v[70:71], v[224:225], v[4:5] op_sel_hi:[1,0,1]
	v_pk_fma_f32 v[2:3], v[68:69], v[224:225], v[2:3] op_sel_hi:[1,0,1]
	ds_read_b32 v248, v223 offset:52
	s_waitcnt lgkmcnt(5)
	v_pk_fma_f32 v[4:5], v[74:75], v[226:227], v[4:5] op_sel_hi:[1,0,1]
	v_pk_fma_f32 v[2:3], v[72:73], v[226:227], v[2:3] op_sel_hi:[1,0,1]
	ds_read_b32 v232, v223 offset:68
	s_waitcnt lgkmcnt(5)
	v_pk_fma_f32 v[4:5], v[78:79], v[228:229], v[4:5] op_sel_hi:[1,0,1]
	v_pk_fma_f32 v[2:3], v[76:77], v[228:229], v[2:3] op_sel_hi:[1,0,1]
	ds_read_b32 v224, v223 offset:56
	s_branch .Lpool_v1_main
.Lpool_v1_nopre:
	ds_read_b32 v248, v223 offset:52
	ds_read_b32 v232, v223 offset:68
	ds_read_b32 v224, v223 offset:56
.Lpool_v1_main:
	s_waitcnt lgkmcnt(5)
	s_waitcnt vmcnt(31)
	v_pk_mul_f32 v[236:237], v[80:81], v[230:231] op_sel_hi:[1,0]
	v_pk_fma_f32 v[2:3], v[80:81], v[230:231], v[2:3] op_sel_hi:[1,0,1]
	v_pk_mul_f32 v[238:239], v[82:83], v[230:231] op_sel_hi:[1,0]
	v_pk_fma_f32 v[4:5], v[82:83], v[230:231], v[4:5] op_sel_hi:[1,0,1]
	ds_read_b32 v226, v223 offset:72
	s_mov_b32 s36, 0x3e800000
	s_cmp_eq_u32 s14, 0
	s_cselect_b32 s36, 0x3f800000, s36
	v_mov_b32_e32 v240, s36
	v_pk_fma_f32 v[242:243], v[240:241], v[2:3], v[236:237] op_sel_hi:[0,1,1] neg_lo:[0,0,1] neg_hi:[0,0,1]
	v_pk_fma_f32 v[236:237], v[240:241], v[4:5], v[238:239] op_sel_hi:[0,1,1] neg_lo:[0,0,1] neg_hi:[0,0,1]
	v_cvt_pk_bf16_f32 v242, v242, v243
	v_cvt_pk_bf16_f32 v243, v236, v237
	global_store_dwordx2 v222, v[242:243], s[34:35]
	s_add_u32 s34, s34, 0x800
	s_addc_u32 s35, s35, 0
	s_waitcnt lgkmcnt(5)
	s_cmp_eq_u32 s14, 0
	s_cbranch_scc1 .Lpool_v1_ns0
	v_xor_b32_e32 v239, 0x80000000, v71
	v_xor_b32_e32 v238, 0x80000000, v70
	v_pk_fma_f32 v[4:5], v[238:239], v[244:245], v[4:5] op_sel_hi:[1,0,1]
	v_pk_fma_f32 v[2:3], v[68:69], v[244:245], v[2:3] op_sel_hi:[1,0,1] neg_lo:[1,0,0] neg_hi:[1,0,0]
.Lpool_v1_ns0:
	ds_read_b32 v228, v223 offset:60
	s_waitcnt lgkmcnt(5)
	s_waitcnt vmcnt(31)
	v_pk_mul_f32 v[236:237], v[84:85], v[246:247] op_sel_hi:[1,0]
	v_pk_fma_f32 v[2:3], v[84:85], v[246:247], v[2:3] op_sel_hi:[1,0,1]
	v_pk_mul_f32 v[238:239], v[86:87], v[246:247] op_sel_hi:[1,0]
	v_pk_fma_f32 v[4:5], v[86:87], v[246:247], v[4:5] op_sel_hi:[1,0,1]
	ds_read_b32 v230, v223 offset:76
	s_mov_b32 s36, 0x3e800000
	s_cmp_eq_u32 s14, 0
	s_cselect_b32 s36, 0x3f000000, s36
	v_mov_b32_e32 v240, s36
	v_pk_fma_f32 v[242:243], v[240:241], v[2:3], v[236:237] op_sel_hi:[0,1,1] neg_lo:[0,0,1] neg_hi:[0,0,1]
	v_pk_fma_f32 v[236:237], v[240:241], v[4:5], v[238:239] op_sel_hi:[0,1,1] neg_lo:[0,0,1] neg_hi:[0,0,1]
	v_cvt_pk_bf16_f32 v242, v242, v243
	v_cvt_pk_bf16_f32 v243, v236, v237
	global_store_dwordx2 v222, v[242:243], s[34:35]
	s_add_u32 s34, s34, 0x800
	s_addc_u32 s35, s35, 0
	s_waitcnt lgkmcnt(5)
	s_cmp_eq_u32 s14, 0
	s_cbranch_scc1 .Lpool_v1_ns1
	v_xor_b32_e32 v239, 0x80000000, v75
	v_xor_b32_e32 v238, 0x80000000, v74
	v_pk_fma_f32 v[4:5], v[238:239], v[248:249], v[4:5] op_sel_hi:[1,0,1]
	v_pk_fma_f32 v[2:3], v[72:73], v[248:249], v[2:3] op_sel_hi:[1,0,1] neg_lo:[1,0,0] neg_hi:[1,0,0]
.Lpool_v1_ns1:
	ds_read_b32 v244, v223 offset:64
	s_waitcnt lgkmcnt(5)
	s_waitcnt vmcnt(31)
	v_pk_mul_f32 v[236:237], v[88:89], v[232:233] op_sel_hi:[1,0]
	v_pk_fma_f32 v[2:3], v[88:89], v[232:233], v[2:3] op_sel_hi:[1,0,1]
	v_pk_mul_f32 v[238:239], v[90:91], v[232:233] op_sel_hi:[1,0]
	v_pk_fma_f32 v[4:5], v[90:91], v[232:233], v[4:5] op_sel_hi:[1,0,1]
	ds_read_b32 v246, v223 offset:80
	s_mov_b32 s36, 0x3e800000
	s_cmp_eq_u32 s14, 0
	s_cselect_b32 s36, 0x3eaaaaab, s36
	v_mov_b32_e32 v240, s36
	v_pk_fma_f32 v[242:243], v[240:241], v[2:3], v[236:237] op_sel_hi:[0,1,1] neg_lo:[0,0,1] neg_hi:[0,0,1]
	v_pk_fma_f32 v[236:237], v[240:241], v[4:5], v[238:239] op_sel_hi:[0,1,1] neg_lo:[0,0,1] neg_hi:[0,0,1]
	v_cvt_pk_bf16_f32 v242, v242, v243
	v_cvt_pk_bf16_f32 v243, v236, v237
	global_store_dwordx2 v222, v[242:243], s[34:35]
	s_add_u32 s34, s34, 0x800
	s_addc_u32 s35, s35, 0
	s_waitcnt lgkmcnt(5)
	s_cmp_eq_u32 s14, 0
	s_cbranch_scc1 .Lpool_v1_ns2
	v_xor_b32_e32 v239, 0x80000000, v79
	v_xor_b32_e32 v238, 0x80000000, v78
	v_pk_fma_f32 v[4:5], v[238:239], v[224:225], v[4:5] op_sel_hi:[1,0,1]
	v_pk_fma_f32 v[2:3], v[76:77], v[224:225], v[2:3] op_sel_hi:[1,0,1] neg_lo:[1,0,0] neg_hi:[1,0,0]
.Lpool_v1_ns2:
	ds_read_b32 v248, v223 offset:68
	s_waitcnt lgkmcnt(5)
	s_waitcnt vmcnt(31)
	v_pk_mul_f32 v[236:237], v[92:93], v[226:227] op_sel_hi:[1,0]
	v_pk_fma_f32 v[2:3], v[92:93], v[226:227], v[2:3] op_sel_hi:[1,0,1]
	v_pk_mul_f32 v[238:239], v[94:95], v[226:227] op_sel_hi:[1,0]
	v_pk_fma_f32 v[4:5], v[94:95], v[226:227], v[4:5] op_sel_hi:[1,0,1]
	ds_read_b32 v232, v223 offset:84
	v_mov_b32_e32 v240, 0x3e800000
	v_pk_fma_f32 v[242:243], v[240:241], v[2:3], v[236:237] op_sel_hi:[0,1,1] neg_lo:[0,0,1] neg_hi:[0,0,1]
	v_pk_fma_f32 v[236:237], v[240:241], v[4:5], v[238:239] op_sel_hi:[0,1,1] neg_lo:[0,0,1] neg_hi:[0,0,1]
	v_cvt_pk_bf16_f32 v242, v242, v243
	v_cvt_pk_bf16_f32 v243, v236, v237
	global_store_dwordx2 v222, v[242:243], s[34:35]
	s_add_u32 s34, s34, 0x800
	s_addc_u32 s35, s35, 0
	s_waitcnt lgkmcnt(5)
	v_xor_b32_e32 v239, 0x80000000, v83
	v_xor_b32_e32 v238, 0x80000000, v82
	v_pk_fma_f32 v[4:5], v[238:239], v[228:229], v[4:5] op_sel_hi:[1,0,1]
	v_pk_fma_f32 v[2:3], v[80:81], v[228:229], v[2:3] op_sel_hi:[1,0,1] neg_lo:[1,0,0] neg_hi:[1,0,0]
	ds_read_b32 v224, v223 offset:72
	s_waitcnt lgkmcnt(5)
	s_waitcnt vmcnt(31)
	v_pk_mul_f32 v[236:237], v[96:97], v[230:231] op_sel_hi:[1,0]
	v_pk_fma_f32 v[2:3], v[96:97], v[230:231], v[2:3] op_sel_hi:[1,0,1]
	v_pk_mul_f32 v[238:239], v[98:99], v[230:231] op_sel_hi:[1,0]
	v_pk_fma_f32 v[4:5], v[98:99], v[230:231], v[4:5] op_sel_hi:[1,0,1]
	ds_read_b32 v226, v223 offset:88
	v_mov_b32_e32 v240, 0x3e800000
	v_pk_fma_f32 v[242:243], v[240:241], v[2:3], v[236:237] op_sel_hi:[0,1,1] neg_lo:[0,0,1] neg_hi:[0,0,1]
	v_pk_fma_f32 v[236:237], v[240:241], v[4:5], v[238:239] op_sel_hi:[0,1,1] neg_lo:[0,0,1] neg_hi:[0,0,1]
	v_cvt_pk_bf16_f32 v242, v242, v243
	v_cvt_pk_bf16_f32 v243, v236, v237
	global_store_dwordx2 v222, v[242:243], s[34:35]
	s_add_u32 s34, s34, 0x800
	s_addc_u32 s35, s35, 0
	s_waitcnt lgkmcnt(5)
	v_xor_b32_e32 v239, 0x80000000, v87
	v_xor_b32_e32 v238, 0x80000000, v86
	v_pk_fma_f32 v[4:5], v[238:239], v[244:245], v[4:5] op_sel_hi:[1,0,1]
	v_pk_fma_f32 v[2:3], v[84:85], v[244:245], v[2:3] op_sel_hi:[1,0,1] neg_lo:[1,0,0] neg_hi:[1,0,0]
	ds_read_b32 v228, v223 offset:76
	s_waitcnt lgkmcnt(5)
	s_waitcnt vmcnt(31)
	v_pk_mul_f32 v[236:237], v[100:101], v[246:247] op_sel_hi:[1,0]
	v_pk_fma_f32 v[2:3], v[100:101], v[246:247], v[2:3] op_sel_hi:[1,0,1]
	v_pk_mul_f32 v[238:239], v[102:103], v[246:247] op_sel_hi:[1,0]
	v_pk_fma_f32 v[4:5], v[102:103], v[246:247], v[4:5] op_sel_hi:[1,0,1]
	ds_read_b32 v230, v223 offset:92
	v_mov_b32_e32 v240, 0x3e800000
	v_pk_fma_f32 v[242:243], v[240:241], v[2:3], v[236:237] op_sel_hi:[0,1,1] neg_lo:[0,0,1] neg_hi:[0,0,1]
	v_pk_fma_f32 v[236:237], v[240:241], v[4:5], v[238:239] op_sel_hi:[0,1,1] neg_lo:[0,0,1] neg_hi:[0,0,1]
	v_cvt_pk_bf16_f32 v242, v242, v243
	v_cvt_pk_bf16_f32 v243, v236, v237
	global_store_dwordx2 v222, v[242:243], s[34:35]
	s_add_u32 s34, s34, 0x800
	s_addc_u32 s35, s35, 0
	s_waitcnt lgkmcnt(5)
	v_xor_b32_e32 v239, 0x80000000, v91
	v_xor_b32_e32 v238, 0x80000000, v90
	v_pk_fma_f32 v[4:5], v[238:239], v[248:249], v[4:5] op_sel_hi:[1,0,1]
	v_pk_fma_f32 v[2:3], v[88:89], v[248:249], v[2:3] op_sel_hi:[1,0,1] neg_lo:[1,0,0] neg_hi:[1,0,0]
	ds_read_b32 v244, v223 offset:80
	s_waitcnt lgkmcnt(5)
	s_waitcnt vmcnt(31)
	v_pk_mul_f32 v[236:237], v[104:105], v[232:233] op_sel_hi:[1,0]
	v_pk_fma_f32 v[2:3], v[104:105], v[232:233], v[2:3] op_sel_hi:[1,0,1]
	v_pk_mul_f32 v[238:239], v[106:107], v[232:233] op_sel_hi:[1,0]
	v_pk_fma_f32 v[4:5], v[106:107], v[232:233], v[4:5] op_sel_hi:[1,0,1]
	ds_read_b32 v246, v223 offset:96
	v_mov_b32_e32 v240, 0x3e800000
	v_pk_fma_f32 v[242:243], v[240:241], v[2:3], v[236:237] op_sel_hi:[0,1,1] neg_lo:[0,0,1] neg_hi:[0,0,1]
	v_pk_fma_f32 v[236:237], v[240:241], v[4:5], v[238:239] op_sel_hi:[0,1,1] neg_lo:[0,0,1] neg_hi:[0,0,1]
	v_cvt_pk_bf16_f32 v242, v242, v243
	v_cvt_pk_bf16_f32 v243, v236, v237
	global_store_dwordx2 v222, v[242:243], s[34:35]
	s_add_u32 s34, s34, 0x800
	s_addc_u32 s35, s35, 0
	s_waitcnt lgkmcnt(5)
	v_xor_b32_e32 v239, 0x80000000, v95
	v_xor_b32_e32 v238, 0x80000000, v94
	v_pk_fma_f32 v[4:5], v[238:239], v[224:225], v[4:5] op_sel_hi:[1,0,1]
	v_pk_fma_f32 v[2:3], v[92:93], v[224:225], v[2:3] op_sel_hi:[1,0,1] neg_lo:[1,0,0] neg_hi:[1,0,0]
	ds_read_b32 v248, v223 offset:84
	s_waitcnt lgkmcnt(5)
	s_waitcnt vmcnt(31)
	v_pk_mul_f32 v[236:237], v[108:109], v[226:227] op_sel_hi:[1,0]
	v_pk_fma_f32 v[2:3], v[108:109], v[226:227], v[2:3] op_sel_hi:[1,0,1]
	v_pk_mul_f32 v[238:239], v[110:111], v[226:227] op_sel_hi:[1,0]
	v_pk_fma_f32 v[4:5], v[110:111], v[226:227], v[4:5] op_sel_hi:[1,0,1]
	ds_read_b32 v232, v223 offset:100
	v_mov_b32_e32 v240, 0x3e800000
	v_pk_fma_f32 v[242:243], v[240:241], v[2:3], v[236:237] op_sel_hi:[0,1,1] neg_lo:[0,0,1] neg_hi:[0,0,1]
	v_pk_fma_f32 v[236:237], v[240:241], v[4:5], v[238:239] op_sel_hi:[0,1,1] neg_lo:[0,0,1] neg_hi:[0,0,1]
	v_cvt_pk_bf16_f32 v242, v242, v243
	v_cvt_pk_bf16_f32 v243, v236, v237
	global_store_dwordx2 v222, v[242:243], s[34:35]
	s_add_u32 s34, s34, 0x800
	s_addc_u32 s35, s35, 0
	s_waitcnt lgkmcnt(5)
	v_xor_b32_e32 v239, 0x80000000, v99
	v_xor_b32_e32 v238, 0x80000000, v98
	v_pk_fma_f32 v[4:5], v[238:239], v[228:229], v[4:5] op_sel_hi:[1,0,1]
	v_pk_fma_f32 v[2:3], v[96:97], v[228:229], v[2:3] op_sel_hi:[1,0,1] neg_lo:[1,0,0] neg_hi:[1,0,0]
	ds_read_b32 v224, v223 offset:88
	s_waitcnt lgkmcnt(5)
	s_waitcnt vmcnt(31)
	v_pk_mul_f32 v[236:237], v[112:113], v[230:231] op_sel_hi:[1,0]
	v_pk_fma_f32 v[2:3], v[112:113], v[230:231], v[2:3] op_sel_hi:[1,0,1]
	v_pk_mul_f32 v[238:239], v[114:115], v[230:231] op_sel_hi:[1,0]
	v_pk_fma_f32 v[4:5], v[114:115], v[230:231], v[4:5] op_sel_hi:[1,0,1]
	ds_read_b32 v226, v223 offset:104
	v_mov_b32_e32 v240, 0x3e800000
	v_pk_fma_f32 v[242:243], v[240:241], v[2:3], v[236:237] op_sel_hi:[0,1,1] neg_lo:[0,0,1] neg_hi:[0,0,1]
	v_pk_fma_f32 v[236:237], v[240:241], v[4:5], v[238:239] op_sel_hi:[0,1,1] neg_lo:[0,0,1] neg_hi:[0,0,1]
	v_cvt_pk_bf16_f32 v242, v242, v243
	v_cvt_pk_bf16_f32 v243, v236, v237
	global_store_dwordx2 v222, v[242:243], s[34:35]
	s_add_u32 s34, s34, 0x800
	s_addc_u32 s35, s35, 0
	s_waitcnt lgkmcnt(5)
	v_xor_b32_e32 v239, 0x80000000, v103
	v_xor_b32_e32 v238, 0x80000000, v102
	v_pk_fma_f32 v[4:5], v[238:239], v[244:245], v[4:5] op_sel_hi:[1,0,1]
	v_pk_fma_f32 v[2:3], v[100:101], v[244:245], v[2:3] op_sel_hi:[1,0,1] neg_lo:[1,0,0] neg_hi:[1,0,0]
	ds_read_b32 v228, v223 offset:92
	s_waitcnt lgkmcnt(5)
	s_waitcnt vmcnt(31)
	v_pk_mul_f32 v[236:237], v[116:117], v[246:247] op_sel_hi:[1,0]
	v_pk_fma_f32 v[2:3], v[116:117], v[246:247], v[2:3] op_sel_hi:[1,0,1]
	v_pk_mul_f32 v[238:239], v[118:119], v[246:247] op_sel_hi:[1,0]
	v_pk_fma_f32 v[4:5], v[118:119], v[246:247], v[4:5] op_sel_hi:[1,0,1]
	ds_read_b32 v230, v223 offset:108
	v_mov_b32_e32 v240, 0x3e800000
	v_pk_fma_f32 v[242:243], v[240:241], v[2:3], v[236:237] op_sel_hi:[0,1,1] neg_lo:[0,0,1] neg_hi:[0,0,1]
	v_pk_fma_f32 v[236:237], v[240:241], v[4:5], v[238:239] op_sel_hi:[0,1,1] neg_lo:[0,0,1] neg_hi:[0,0,1]
	v_cvt_pk_bf16_f32 v242, v242, v243
	v_cvt_pk_bf16_f32 v243, v236, v237
	global_store_dwordx2 v222, v[242:243], s[34:35]
	s_add_u32 s34, s34, 0x800
	s_addc_u32 s35, s35, 0
	s_waitcnt lgkmcnt(5)
	v_xor_b32_e32 v239, 0x80000000, v107
	v_xor_b32_e32 v238, 0x80000000, v106
	v_pk_fma_f32 v[4:5], v[238:239], v[248:249], v[4:5] op_sel_hi:[1,0,1]
	v_pk_fma_f32 v[2:3], v[104:105], v[248:249], v[2:3] op_sel_hi:[1,0,1] neg_lo:[1,0,0] neg_hi:[1,0,0]
	ds_read_b32 v244, v223 offset:96
	s_waitcnt lgkmcnt(5)
	s_waitcnt vmcnt(31)
	v_pk_mul_f32 v[236:237], v[120:121], v[232:233] op_sel_hi:[1,0]
	v_pk_fma_f32 v[2:3], v[120:121], v[232:233], v[2:3] op_sel_hi:[1,0,1]
	v_pk_mul_f32 v[238:239], v[122:123], v[232:233] op_sel_hi:[1,0]
	v_pk_fma_f32 v[4:5], v[122:123], v[232:233], v[4:5] op_sel_hi:[1,0,1]
	ds_read_b32 v246, v223 offset:112
	v_mov_b32_e32 v240, 0x3e800000
	v_pk_fma_f32 v[242:243], v[240:241], v[2:3], v[236:237] op_sel_hi:[0,1,1] neg_lo:[0,0,1] neg_hi:[0,0,1]
	v_pk_fma_f32 v[236:237], v[240:241], v[4:5], v[238:239] op_sel_hi:[0,1,1] neg_lo:[0,0,1] neg_hi:[0,0,1]
	v_cvt_pk_bf16_f32 v242, v242, v243
	v_cvt_pk_bf16_f32 v243, v236, v237
	global_store_dwordx2 v222, v[242:243], s[34:35]
	s_add_u32 s34, s34, 0x800
	s_addc_u32 s35, s35, 0
	s_waitcnt lgkmcnt(5)
	v_xor_b32_e32 v239, 0x80000000, v111
	v_xor_b32_e32 v238, 0x80000000, v110
	v_pk_fma_f32 v[4:5], v[238:239], v[224:225], v[4:5] op_sel_hi:[1,0,1]
	v_pk_fma_f32 v[2:3], v[108:109], v[224:225], v[2:3] op_sel_hi:[1,0,1] neg_lo:[1,0,0] neg_hi:[1,0,0]
	ds_read_b32 v248, v223 offset:100
	s_waitcnt lgkmcnt(5)
	s_waitcnt vmcnt(31)
	v_pk_mul_f32 v[236:237], v[124:125], v[226:227] op_sel_hi:[1,0]
	v_pk_fma_f32 v[2:3], v[124:125], v[226:227], v[2:3] op_sel_hi:[1,0,1]
	v_pk_mul_f32 v[238:239], v[126:127], v[226:227] op_sel_hi:[1,0]
	v_pk_fma_f32 v[4:5], v[126:127], v[226:227], v[4:5] op_sel_hi:[1,0,1]
	ds_read_b32 v232, v223 offset:116
	v_mov_b32_e32 v240, 0x3e800000
	v_pk_fma_f32 v[242:243], v[240:241], v[2:3], v[236:237] op_sel_hi:[0,1,1] neg_lo:[0,0,1] neg_hi:[0,0,1]
	v_pk_fma_f32 v[236:237], v[240:241], v[4:5], v[238:239] op_sel_hi:[0,1,1] neg_lo:[0,0,1] neg_hi:[0,0,1]
	v_cvt_pk_bf16_f32 v242, v242, v243
	v_cvt_pk_bf16_f32 v243, v236, v237
	global_store_dwordx2 v222, v[242:243], s[34:35]
	s_add_u32 s34, s34, 0x800
	s_addc_u32 s35, s35, 0
	s_waitcnt lgkmcnt(5)
	v_xor_b32_e32 v239, 0x80000000, v115
	v_xor_b32_e32 v238, 0x80000000, v114
	v_pk_fma_f32 v[4:5], v[238:239], v[228:229], v[4:5] op_sel_hi:[1,0,1]
	v_pk_fma_f32 v[2:3], v[112:113], v[228:229], v[2:3] op_sel_hi:[1,0,1] neg_lo:[1,0,0] neg_hi:[1,0,0]
	ds_read_b32 v224, v223 offset:104
	s_waitcnt lgkmcnt(5)
	s_waitcnt vmcnt(31)
	v_pk_mul_f32 v[236:237], v[128:129], v[230:231] op_sel_hi:[1,0]
	v_pk_fma_f32 v[2:3], v[128:129], v[230:231], v[2:3] op_sel_hi:[1,0,1]
	v_pk_mul_f32 v[238:239], v[130:131], v[230:231] op_sel_hi:[1,0]
	v_pk_fma_f32 v[4:5], v[130:131], v[230:231], v[4:5] op_sel_hi:[1,0,1]
	ds_read_b32 v226, v223 offset:120
	v_mov_b32_e32 v240, 0x3e800000
	v_pk_fma_f32 v[242:243], v[240:241], v[2:3], v[236:237] op_sel_hi:[0,1,1] neg_lo:[0,0,1] neg_hi:[0,0,1]
	v_pk_fma_f32 v[236:237], v[240:241], v[4:5], v[238:239] op_sel_hi:[0,1,1] neg_lo:[0,0,1] neg_hi:[0,0,1]
	v_cvt_pk_bf16_f32 v242, v242, v243
	v_cvt_pk_bf16_f32 v243, v236, v237
	global_store_dwordx2 v222, v[242:243], s[34:35]
	s_add_u32 s34, s34, 0x800
	s_addc_u32 s35, s35, 0
	s_waitcnt lgkmcnt(5)
	v_xor_b32_e32 v239, 0x80000000, v119
	v_xor_b32_e32 v238, 0x80000000, v118
	v_pk_fma_f32 v[4:5], v[238:239], v[244:245], v[4:5] op_sel_hi:[1,0,1]
	v_pk_fma_f32 v[2:3], v[116:117], v[244:245], v[2:3] op_sel_hi:[1,0,1] neg_lo:[1,0,0] neg_hi:[1,0,0]
	ds_read_b32 v228, v223 offset:108
	s_waitcnt lgkmcnt(5)
	s_waitcnt vmcnt(31)
	v_pk_mul_f32 v[236:237], v[132:133], v[246:247] op_sel_hi:[1,0]
	v_pk_fma_f32 v[2:3], v[132:133], v[246:247], v[2:3] op_sel_hi:[1,0,1]
	v_pk_mul_f32 v[238:239], v[134:135], v[246:247] op_sel_hi:[1,0]
	v_pk_fma_f32 v[4:5], v[134:135], v[246:247], v[4:5] op_sel_hi:[1,0,1]
	ds_read_b32 v230, v223 offset:124
	v_mov_b32_e32 v240, 0x3e800000
	v_pk_fma_f32 v[242:243], v[240:241], v[2:3], v[236:237] op_sel_hi:[0,1,1] neg_lo:[0,0,1] neg_hi:[0,0,1]
	v_pk_fma_f32 v[236:237], v[240:241], v[4:5], v[238:239] op_sel_hi:[0,1,1] neg_lo:[0,0,1] neg_hi:[0,0,1]
	v_cvt_pk_bf16_f32 v242, v242, v243
	v_cvt_pk_bf16_f32 v243, v236, v237
	global_store_dwordx2 v222, v[242:243], s[34:35]
	s_add_u32 s34, s34, 0x800
	s_addc_u32 s35, s35, 0
	s_waitcnt lgkmcnt(5)
	v_xor_b32_e32 v239, 0x80000000, v123
	v_xor_b32_e32 v238, 0x80000000, v122
	v_pk_fma_f32 v[4:5], v[238:239], v[248:249], v[4:5] op_sel_hi:[1,0,1]
	v_pk_fma_f32 v[2:3], v[120:121], v[248:249], v[2:3] op_sel_hi:[1,0,1] neg_lo:[1,0,0] neg_hi:[1,0,0]
	ds_read_b32 v244, v223 offset:112
	s_waitcnt lgkmcnt(5)
	s_waitcnt vmcnt(31)
	v_pk_mul_f32 v[236:237], v[136:137], v[232:233] op_sel_hi:[1,0]
	v_pk_fma_f32 v[2:3], v[136:137], v[232:233], v[2:3] op_sel_hi:[1,0,1]
	v_pk_mul_f32 v[238:239], v[138:139], v[232:233] op_sel_hi:[1,0]
	v_pk_fma_f32 v[4:5], v[138:139], v[232:233], v[4:5] op_sel_hi:[1,0,1]
	ds_read_b32 v246, v223 offset:128
	v_mov_b32_e32 v240, 0x3e800000
	v_pk_fma_f32 v[242:243], v[240:241], v[2:3], v[236:237] op_sel_hi:[0,1,1] neg_lo:[0,0,1] neg_hi:[0,0,1]
	v_pk_fma_f32 v[236:237], v[240:241], v[4:5], v[238:239] op_sel_hi:[0,1,1] neg_lo:[0,0,1] neg_hi:[0,0,1]
	v_cvt_pk_bf16_f32 v242, v242, v243
	v_cvt_pk_bf16_f32 v243, v236, v237
	global_store_dwordx2 v222, v[242:243], s[34:35]
	s_add_u32 s34, s34, 0x800
	s_addc_u32 s35, s35, 0
	s_waitcnt lgkmcnt(5)
	v_xor_b32_e32 v239, 0x80000000, v127
	v_xor_b32_e32 v238, 0x80000000, v126
	v_pk_fma_f32 v[4:5], v[238:239], v[224:225], v[4:5] op_sel_hi:[1,0,1]
	v_pk_fma_f32 v[2:3], v[124:125], v[224:225], v[2:3] op_sel_hi:[1,0,1] neg_lo:[1,0,0] neg_hi:[1,0,0]
	ds_read_b32 v248, v223 offset:116
	s_waitcnt lgkmcnt(5)
	s_waitcnt vmcnt(31)
	v_pk_mul_f32 v[236:237], v[140:141], v[226:227] op_sel_hi:[1,0]
	v_pk_fma_f32 v[2:3], v[140:141], v[226:227], v[2:3] op_sel_hi:[1,0,1]
	v_pk_mul_f32 v[238:239], v[142:143], v[226:227] op_sel_hi:[1,0]
	v_pk_fma_f32 v[4:5], v[142:143], v[226:227], v[4:5] op_sel_hi:[1,0,1]
	ds_read_b32 v232, v223 offset:132
	v_mov_b32_e32 v240, 0x3e800000
	v_pk_fma_f32 v[242:243], v[240:241], v[2:3], v[236:237] op_sel_hi:[0,1,1] neg_lo:[0,0,1] neg_hi:[0,0,1]
	v_pk_fma_f32 v[236:237], v[240:241], v[4:5], v[238:239] op_sel_hi:[0,1,1] neg_lo:[0,0,1] neg_hi:[0,0,1]
	v_cvt_pk_bf16_f32 v242, v242, v243
	v_cvt_pk_bf16_f32 v243, v236, v237
	global_store_dwordx2 v222, v[242:243], s[34:35]
	s_add_u32 s34, s34, 0x800
	s_addc_u32 s35, s35, 0
	s_waitcnt lgkmcnt(5)
	v_xor_b32_e32 v239, 0x80000000, v131
	v_xor_b32_e32 v238, 0x80000000, v130
	v_pk_fma_f32 v[4:5], v[238:239], v[228:229], v[4:5] op_sel_hi:[1,0,1]
	v_pk_fma_f32 v[2:3], v[128:129], v[228:229], v[2:3] op_sel_hi:[1,0,1] neg_lo:[1,0,0] neg_hi:[1,0,0]
	ds_read_b32 v224, v223 offset:120
	s_waitcnt lgkmcnt(5)
	s_waitcnt vmcnt(31)
	v_pk_mul_f32 v[236:237], v[144:145], v[230:231] op_sel_hi:[1,0]
	v_pk_fma_f32 v[2:3], v[144:145], v[230:231], v[2:3] op_sel_hi:[1,0,1]
	v_pk_mul_f32 v[238:239], v[146:147], v[230:231] op_sel_hi:[1,0]
	v_pk_fma_f32 v[4:5], v[146:147], v[230:231], v[4:5] op_sel_hi:[1,0,1]
	ds_read_b32 v226, v223 offset:136
	v_mov_b32_e32 v240, 0x3e800000
	v_pk_fma_f32 v[242:243], v[240:241], v[2:3], v[236:237] op_sel_hi:[0,1,1] neg_lo:[0,0,1] neg_hi:[0,0,1]
	v_pk_fma_f32 v[236:237], v[240:241], v[4:5], v[238:239] op_sel_hi:[0,1,1] neg_lo:[0,0,1] neg_hi:[0,0,1]
	v_cvt_pk_bf16_f32 v242, v242, v243
	v_cvt_pk_bf16_f32 v243, v236, v237
	global_store_dwordx2 v222, v[242:243], s[34:35]
	s_add_u32 s34, s34, 0x800
	s_addc_u32 s35, s35, 0
	s_waitcnt lgkmcnt(5)
	v_xor_b32_e32 v239, 0x80000000, v135
	v_xor_b32_e32 v238, 0x80000000, v134
	v_pk_fma_f32 v[4:5], v[238:239], v[244:245], v[4:5] op_sel_hi:[1,0,1]
	v_pk_fma_f32 v[2:3], v[132:133], v[244:245], v[2:3] op_sel_hi:[1,0,1] neg_lo:[1,0,0] neg_hi:[1,0,0]
	ds_read_b32 v228, v223 offset:124
	s_waitcnt lgkmcnt(5)
	s_waitcnt vmcnt(31)
	v_pk_mul_f32 v[236:237], v[148:149], v[246:247] op_sel_hi:[1,0]
	v_pk_fma_f32 v[2:3], v[148:149], v[246:247], v[2:3] op_sel_hi:[1,0,1]
	v_pk_mul_f32 v[238:239], v[150:151], v[246:247] op_sel_hi:[1,0]
	v_pk_fma_f32 v[4:5], v[150:151], v[246:247], v[4:5] op_sel_hi:[1,0,1]
	ds_read_b32 v230, v223 offset:140
	v_mov_b32_e32 v240, 0x3e800000
	v_pk_fma_f32 v[242:243], v[240:241], v[2:3], v[236:237] op_sel_hi:[0,1,1] neg_lo:[0,0,1] neg_hi:[0,0,1]
	v_pk_fma_f32 v[236:237], v[240:241], v[4:5], v[238:239] op_sel_hi:[0,1,1] neg_lo:[0,0,1] neg_hi:[0,0,1]
	v_cvt_pk_bf16_f32 v242, v242, v243
	v_cvt_pk_bf16_f32 v243, v236, v237
	global_store_dwordx2 v222, v[242:243], s[34:35]
	s_add_u32 s34, s34, 0x800
	s_addc_u32 s35, s35, 0
	s_waitcnt lgkmcnt(5)
	v_xor_b32_e32 v239, 0x80000000, v139
	v_xor_b32_e32 v238, 0x80000000, v138
	v_pk_fma_f32 v[4:5], v[238:239], v[248:249], v[4:5] op_sel_hi:[1,0,1]
	v_pk_fma_f32 v[2:3], v[136:137], v[248:249], v[2:3] op_sel_hi:[1,0,1] neg_lo:[1,0,0] neg_hi:[1,0,0]
	ds_read_b32 v244, v223 offset:128
	s_waitcnt lgkmcnt(5)
	s_waitcnt vmcnt(31)
	v_pk_mul_f32 v[236:237], v[152:153], v[232:233] op_sel_hi:[1,0]
	v_pk_fma_f32 v[2:3], v[152:153], v[232:233], v[2:3] op_sel_hi:[1,0,1]
	v_pk_mul_f32 v[238:239], v[154:155], v[232:233] op_sel_hi:[1,0]
	v_pk_fma_f32 v[4:5], v[154:155], v[232:233], v[4:5] op_sel_hi:[1,0,1]
	ds_read_b32 v246, v223 offset:144
	v_mov_b32_e32 v240, 0x3e800000
	v_pk_fma_f32 v[242:243], v[240:241], v[2:3], v[236:237] op_sel_hi:[0,1,1] neg_lo:[0,0,1] neg_hi:[0,0,1]
	v_pk_fma_f32 v[236:237], v[240:241], v[4:5], v[238:239] op_sel_hi:[0,1,1] neg_lo:[0,0,1] neg_hi:[0,0,1]
	v_cvt_pk_bf16_f32 v242, v242, v243
	v_cvt_pk_bf16_f32 v243, v236, v237
	global_store_dwordx2 v222, v[242:243], s[34:35]
	s_add_u32 s34, s34, 0x800
	s_addc_u32 s35, s35, 0
	s_waitcnt lgkmcnt(5)
	v_xor_b32_e32 v239, 0x80000000, v143
	v_xor_b32_e32 v238, 0x80000000, v142
	v_pk_fma_f32 v[4:5], v[238:239], v[224:225], v[4:5] op_sel_hi:[1,0,1]
	v_pk_fma_f32 v[2:3], v[140:141], v[224:225], v[2:3] op_sel_hi:[1,0,1] neg_lo:[1,0,0] neg_hi:[1,0,0]
	ds_read_b32 v248, v223 offset:132
	s_waitcnt lgkmcnt(5)
	s_waitcnt vmcnt(31)
	v_pk_mul_f32 v[236:237], v[156:157], v[226:227] op_sel_hi:[1,0]
	v_pk_fma_f32 v[2:3], v[156:157], v[226:227], v[2:3] op_sel_hi:[1,0,1]
	v_pk_mul_f32 v[238:239], v[158:159], v[226:227] op_sel_hi:[1,0]
	v_pk_fma_f32 v[4:5], v[158:159], v[226:227], v[4:5] op_sel_hi:[1,0,1]
	ds_read_b32 v232, v223 offset:148
	v_mov_b32_e32 v240, 0x3e800000
	v_pk_fma_f32 v[242:243], v[240:241], v[2:3], v[236:237] op_sel_hi:[0,1,1] neg_lo:[0,0,1] neg_hi:[0,0,1]
	v_pk_fma_f32 v[236:237], v[240:241], v[4:5], v[238:239] op_sel_hi:[0,1,1] neg_lo:[0,0,1] neg_hi:[0,0,1]
	v_cvt_pk_bf16_f32 v242, v242, v243
	v_cvt_pk_bf16_f32 v243, v236, v237
	global_store_dwordx2 v222, v[242:243], s[34:35]
	s_add_u32 s34, s34, 0x800
	s_addc_u32 s35, s35, 0
	s_waitcnt lgkmcnt(5)
	v_xor_b32_e32 v239, 0x80000000, v147
	v_xor_b32_e32 v238, 0x80000000, v146
	v_pk_fma_f32 v[4:5], v[238:239], v[228:229], v[4:5] op_sel_hi:[1,0,1]
	v_pk_fma_f32 v[2:3], v[144:145], v[228:229], v[2:3] op_sel_hi:[1,0,1] neg_lo:[1,0,0] neg_hi:[1,0,0]
	ds_read_b32 v224, v223 offset:136
	s_waitcnt lgkmcnt(5)
	s_waitcnt vmcnt(31)
	v_pk_mul_f32 v[236:237], v[160:161], v[230:231] op_sel_hi:[1,0]
	v_pk_fma_f32 v[2:3], v[160:161], v[230:231], v[2:3] op_sel_hi:[1,0,1]
	v_pk_mul_f32 v[238:239], v[162:163], v[230:231] op_sel_hi:[1,0]
	v_pk_fma_f32 v[4:5], v[162:163], v[230:231], v[4:5] op_sel_hi:[1,0,1]
	ds_read_b32 v226, v223 offset:152
	v_mov_b32_e32 v240, 0x3e800000
	v_pk_fma_f32 v[242:243], v[240:241], v[2:3], v[236:237] op_sel_hi:[0,1,1] neg_lo:[0,0,1] neg_hi:[0,0,1]
	v_pk_fma_f32 v[236:237], v[240:241], v[4:5], v[238:239] op_sel_hi:[0,1,1] neg_lo:[0,0,1] neg_hi:[0,0,1]
	v_cvt_pk_bf16_f32 v242, v242, v243
	v_cvt_pk_bf16_f32 v243, v236, v237
	global_store_dwordx2 v222, v[242:243], s[34:35]
	s_add_u32 s34, s34, 0x800
	s_addc_u32 s35, s35, 0
	s_waitcnt lgkmcnt(5)
	v_xor_b32_e32 v239, 0x80000000, v151
	v_xor_b32_e32 v238, 0x80000000, v150
	v_pk_fma_f32 v[4:5], v[238:239], v[244:245], v[4:5] op_sel_hi:[1,0,1]
	v_pk_fma_f32 v[2:3], v[148:149], v[244:245], v[2:3] op_sel_hi:[1,0,1] neg_lo:[1,0,0] neg_hi:[1,0,0]
	ds_read_b32 v228, v223 offset:140
	s_waitcnt lgkmcnt(5)
	s_waitcnt vmcnt(31)
	v_pk_mul_f32 v[236:237], v[164:165], v[246:247] op_sel_hi:[1,0]
	v_pk_fma_f32 v[2:3], v[164:165], v[246:247], v[2:3] op_sel_hi:[1,0,1]
	v_pk_mul_f32 v[238:239], v[166:167], v[246:247] op_sel_hi:[1,0]
	v_pk_fma_f32 v[4:5], v[166:167], v[246:247], v[4:5] op_sel_hi:[1,0,1]
	ds_read_b32 v230, v223 offset:156
	v_mov_b32_e32 v240, 0x3e800000
	v_pk_fma_f32 v[242:243], v[240:241], v[2:3], v[236:237] op_sel_hi:[0,1,1] neg_lo:[0,0,1] neg_hi:[0,0,1]
	v_pk_fma_f32 v[236:237], v[240:241], v[4:5], v[238:239] op_sel_hi:[0,1,1] neg_lo:[0,0,1] neg_hi:[0,0,1]
	v_cvt_pk_bf16_f32 v242, v242, v243
	v_cvt_pk_bf16_f32 v243, v236, v237
	global_store_dwordx2 v222, v[242:243], s[34:35]
	s_add_u32 s34, s34, 0x800
	s_addc_u32 s35, s35, 0
	s_waitcnt lgkmcnt(5)
	v_xor_b32_e32 v239, 0x80000000, v155
	v_xor_b32_e32 v238, 0x80000000, v154
	v_pk_fma_f32 v[4:5], v[238:239], v[248:249], v[4:5] op_sel_hi:[1,0,1]
	v_pk_fma_f32 v[2:3], v[152:153], v[248:249], v[2:3] op_sel_hi:[1,0,1] neg_lo:[1,0,0] neg_hi:[1,0,0]
	ds_read_b32 v244, v223 offset:144
	s_waitcnt lgkmcnt(5)
	s_waitcnt vmcnt(31)
	v_pk_mul_f32 v[236:237], v[168:169], v[232:233] op_sel_hi:[1,0]
	v_pk_fma_f32 v[2:3], v[168:169], v[232:233], v[2:3] op_sel_hi:[1,0,1]
	v_pk_mul_f32 v[238:239], v[170:171], v[232:233] op_sel_hi:[1,0]
	v_pk_fma_f32 v[4:5], v[170:171], v[232:233], v[4:5] op_sel_hi:[1,0,1]
	ds_read_b32 v246, v223 offset:160
	v_mov_b32_e32 v240, 0x3e800000
	v_pk_fma_f32 v[242:243], v[240:241], v[2:3], v[236:237] op_sel_hi:[0,1,1] neg_lo:[0,0,1] neg_hi:[0,0,1]
	v_pk_fma_f32 v[236:237], v[240:241], v[4:5], v[238:239] op_sel_hi:[0,1,1] neg_lo:[0,0,1] neg_hi:[0,0,1]
	v_cvt_pk_bf16_f32 v242, v242, v243
	v_cvt_pk_bf16_f32 v243, v236, v237
	global_store_dwordx2 v222, v[242:243], s[34:35]
	s_add_u32 s34, s34, 0x800
	s_addc_u32 s35, s35, 0
	s_waitcnt lgkmcnt(5)
	v_xor_b32_e32 v239, 0x80000000, v159
	v_xor_b32_e32 v238, 0x80000000, v158
	v_pk_fma_f32 v[4:5], v[238:239], v[224:225], v[4:5] op_sel_hi:[1,0,1]
	v_pk_fma_f32 v[2:3], v[156:157], v[224:225], v[2:3] op_sel_hi:[1,0,1] neg_lo:[1,0,0] neg_hi:[1,0,0]
	ds_read_b32 v248, v223 offset:148
	s_waitcnt lgkmcnt(5)
	s_waitcnt vmcnt(31)
	v_pk_mul_f32 v[236:237], v[172:173], v[226:227] op_sel_hi:[1,0]
	v_pk_fma_f32 v[2:3], v[172:173], v[226:227], v[2:3] op_sel_hi:[1,0,1]
	v_pk_mul_f32 v[238:239], v[174:175], v[226:227] op_sel_hi:[1,0]
	v_pk_fma_f32 v[4:5], v[174:175], v[226:227], v[4:5] op_sel_hi:[1,0,1]
	ds_read_b32 v232, v223 offset:164
	v_mov_b32_e32 v240, 0x3e800000
	v_pk_fma_f32 v[242:243], v[240:241], v[2:3], v[236:237] op_sel_hi:[0,1,1] neg_lo:[0,0,1] neg_hi:[0,0,1]
	v_pk_fma_f32 v[236:237], v[240:241], v[4:5], v[238:239] op_sel_hi:[0,1,1] neg_lo:[0,0,1] neg_hi:[0,0,1]
	v_cvt_pk_bf16_f32 v242, v242, v243
	v_cvt_pk_bf16_f32 v243, v236, v237
	global_store_dwordx2 v222, v[242:243], s[34:35]
	s_add_u32 s34, s34, 0x800
	s_addc_u32 s35, s35, 0
	s_waitcnt lgkmcnt(5)
	v_xor_b32_e32 v239, 0x80000000, v163
	v_xor_b32_e32 v238, 0x80000000, v162
	v_pk_fma_f32 v[4:5], v[238:239], v[228:229], v[4:5] op_sel_hi:[1,0,1]
	v_pk_fma_f32 v[2:3], v[160:161], v[228:229], v[2:3] op_sel_hi:[1,0,1] neg_lo:[1,0,0] neg_hi:[1,0,0]
	ds_read_b32 v224, v223 offset:152
	s_waitcnt lgkmcnt(5)
	s_waitcnt vmcnt(31)
	v_pk_mul_f32 v[236:237], v[176:177], v[230:231] op_sel_hi:[1,0]
	v_pk_fma_f32 v[2:3], v[176:177], v[230:231], v[2:3] op_sel_hi:[1,0,1]
	v_pk_mul_f32 v[238:239], v[178:179], v[230:231] op_sel_hi:[1,0]
	v_pk_fma_f32 v[4:5], v[178:179], v[230:231], v[4:5] op_sel_hi:[1,0,1]
	ds_read_b32 v226, v223 offset:168
	v_mov_b32_e32 v240, 0x3e800000
	v_pk_fma_f32 v[242:243], v[240:241], v[2:3], v[236:237] op_sel_hi:[0,1,1] neg_lo:[0,0,1] neg_hi:[0,0,1]
	v_pk_fma_f32 v[236:237], v[240:241], v[4:5], v[238:239] op_sel_hi:[0,1,1] neg_lo:[0,0,1] neg_hi:[0,0,1]
	v_cvt_pk_bf16_f32 v242, v242, v243
	v_cvt_pk_bf16_f32 v243, v236, v237
	global_store_dwordx2 v222, v[242:243], s[34:35]
	s_add_u32 s34, s34, 0x800
	s_addc_u32 s35, s35, 0
	s_waitcnt lgkmcnt(5)
	v_xor_b32_e32 v239, 0x80000000, v167
	v_xor_b32_e32 v238, 0x80000000, v166
	v_pk_fma_f32 v[4:5], v[238:239], v[244:245], v[4:5] op_sel_hi:[1,0,1]
	v_pk_fma_f32 v[2:3], v[164:165], v[244:245], v[2:3] op_sel_hi:[1,0,1] neg_lo:[1,0,0] neg_hi:[1,0,0]
	ds_read_b32 v228, v223 offset:156
	s_waitcnt lgkmcnt(5)
	s_waitcnt vmcnt(31)
	v_pk_mul_f32 v[236:237], v[180:181], v[246:247] op_sel_hi:[1,0]
	v_pk_fma_f32 v[2:3], v[180:181], v[246:247], v[2:3] op_sel_hi:[1,0,1]
	v_pk_mul_f32 v[238:239], v[182:183], v[246:247] op_sel_hi:[1,0]
	v_pk_fma_f32 v[4:5], v[182:183], v[246:247], v[4:5] op_sel_hi:[1,0,1]
	ds_read_b32 v230, v223 offset:172
	v_mov_b32_e32 v240, 0x3e800000
	v_pk_fma_f32 v[242:243], v[240:241], v[2:3], v[236:237] op_sel_hi:[0,1,1] neg_lo:[0,0,1] neg_hi:[0,0,1]
	v_pk_fma_f32 v[236:237], v[240:241], v[4:5], v[238:239] op_sel_hi:[0,1,1] neg_lo:[0,0,1] neg_hi:[0,0,1]
	v_cvt_pk_bf16_f32 v242, v242, v243
	v_cvt_pk_bf16_f32 v243, v236, v237
	global_store_dwordx2 v222, v[242:243], s[34:35]
	s_add_u32 s34, s34, 0x800
	s_addc_u32 s35, s35, 0
	s_waitcnt lgkmcnt(5)
	v_xor_b32_e32 v239, 0x80000000, v171
	v_xor_b32_e32 v238, 0x80000000, v170
	v_pk_fma_f32 v[4:5], v[238:239], v[248:249], v[4:5] op_sel_hi:[1,0,1]
	v_pk_fma_f32 v[2:3], v[168:169], v[248:249], v[2:3] op_sel_hi:[1,0,1] neg_lo:[1,0,0] neg_hi:[1,0,0]
	ds_read_b32 v244, v223 offset:160
	s_waitcnt lgkmcnt(5)
	s_waitcnt vmcnt(31)
	v_pk_mul_f32 v[236:237], v[184:185], v[232:233] op_sel_hi:[1,0]
	v_pk_fma_f32 v[2:3], v[184:185], v[232:233], v[2:3] op_sel_hi:[1,0,1]
	v_pk_mul_f32 v[238:239], v[186:187], v[232:233] op_sel_hi:[1,0]
	v_pk_fma_f32 v[4:5], v[186:187], v[232:233], v[4:5] op_sel_hi:[1,0,1]
	ds_read_b32 v246, v223 offset:176
	v_mov_b32_e32 v240, 0x3e800000
	v_pk_fma_f32 v[242:243], v[240:241], v[2:3], v[236:237] op_sel_hi:[0,1,1] neg_lo:[0,0,1] neg_hi:[0,0,1]
	v_pk_fma_f32 v[236:237], v[240:241], v[4:5], v[238:239] op_sel_hi:[0,1,1] neg_lo:[0,0,1] neg_hi:[0,0,1]
	v_cvt_pk_bf16_f32 v242, v242, v243
	v_cvt_pk_bf16_f32 v243, v236, v237
	global_store_dwordx2 v222, v[242:243], s[34:35]
	s_add_u32 s34, s34, 0x800
	s_addc_u32 s35, s35, 0
	s_waitcnt lgkmcnt(5)
	v_xor_b32_e32 v239, 0x80000000, v175
	v_xor_b32_e32 v238, 0x80000000, v174
	v_pk_fma_f32 v[4:5], v[238:239], v[224:225], v[4:5] op_sel_hi:[1,0,1]
	v_pk_fma_f32 v[2:3], v[172:173], v[224:225], v[2:3] op_sel_hi:[1,0,1] neg_lo:[1,0,0] neg_hi:[1,0,0]
	ds_read_b32 v248, v223 offset:164
	s_waitcnt lgkmcnt(5)
	s_waitcnt vmcnt(31)
	v_pk_mul_f32 v[236:237], v[188:189], v[226:227] op_sel_hi:[1,0]
	v_pk_fma_f32 v[2:3], v[188:189], v[226:227], v[2:3] op_sel_hi:[1,0,1]
	v_pk_mul_f32 v[238:239], v[190:191], v[226:227] op_sel_hi:[1,0]
	v_pk_fma_f32 v[4:5], v[190:191], v[226:227], v[4:5] op_sel_hi:[1,0,1]
	ds_read_b32 v232, v223 offset:180
	v_mov_b32_e32 v240, 0x3e800000
	v_pk_fma_f32 v[242:243], v[240:241], v[2:3], v[236:237] op_sel_hi:[0,1,1] neg_lo:[0,0,1] neg_hi:[0,0,1]
	v_pk_fma_f32 v[236:237], v[240:241], v[4:5], v[238:239] op_sel_hi:[0,1,1] neg_lo:[0,0,1] neg_hi:[0,0,1]
	v_cvt_pk_bf16_f32 v242, v242, v243
	v_cvt_pk_bf16_f32 v243, v236, v237
	global_store_dwordx2 v222, v[242:243], s[34:35]
	s_add_u32 s34, s34, 0x800
	s_addc_u32 s35, s35, 0
	s_waitcnt lgkmcnt(5)
	v_xor_b32_e32 v239, 0x80000000, v179
	v_xor_b32_e32 v238, 0x80000000, v178
	v_pk_fma_f32 v[4:5], v[238:239], v[228:229], v[4:5] op_sel_hi:[1,0,1]
	v_pk_fma_f32 v[2:3], v[176:177], v[228:229], v[2:3] op_sel_hi:[1,0,1] neg_lo:[1,0,0] neg_hi:[1,0,0]
	ds_read_b32 v224, v223 offset:168
	s_waitcnt lgkmcnt(5)
	s_waitcnt vmcnt(31)
	v_pk_mul_f32 v[236:237], v[192:193], v[230:231] op_sel_hi:[1,0]
	v_pk_fma_f32 v[2:3], v[192:193], v[230:231], v[2:3] op_sel_hi:[1,0,1]
	v_pk_mul_f32 v[238:239], v[194:195], v[230:231] op_sel_hi:[1,0]
	v_pk_fma_f32 v[4:5], v[194:195], v[230:231], v[4:5] op_sel_hi:[1,0,1]
	ds_read_b32 v226, v223 offset:184
	v_mov_b32_e32 v240, 0x3e800000
	v_pk_fma_f32 v[242:243], v[240:241], v[2:3], v[236:237] op_sel_hi:[0,1,1] neg_lo:[0,0,1] neg_hi:[0,0,1]
	v_pk_fma_f32 v[236:237], v[240:241], v[4:5], v[238:239] op_sel_hi:[0,1,1] neg_lo:[0,0,1] neg_hi:[0,0,1]
	v_cvt_pk_bf16_f32 v242, v242, v243
	v_cvt_pk_bf16_f32 v243, v236, v237
	global_store_dwordx2 v222, v[242:243], s[34:35]
	s_add_u32 s34, s34, 0x800
	s_addc_u32 s35, s35, 0
	s_waitcnt lgkmcnt(5)
	v_xor_b32_e32 v239, 0x80000000, v183
	v_xor_b32_e32 v238, 0x80000000, v182
	v_pk_fma_f32 v[4:5], v[238:239], v[244:245], v[4:5] op_sel_hi:[1,0,1]
	v_pk_fma_f32 v[2:3], v[180:181], v[244:245], v[2:3] op_sel_hi:[1,0,1] neg_lo:[1,0,0] neg_hi:[1,0,0]
	ds_read_b32 v228, v223 offset:172
	s_waitcnt lgkmcnt(5)
	s_waitcnt vmcnt(31)
	v_pk_mul_f32 v[236:237], v[196:197], v[246:247] op_sel_hi:[1,0]
	v_pk_fma_f32 v[2:3], v[196:197], v[246:247], v[2:3] op_sel_hi:[1,0,1]
	v_pk_mul_f32 v[238:239], v[198:199], v[246:247] op_sel_hi:[1,0]
	v_pk_fma_f32 v[4:5], v[198:199], v[246:247], v[4:5] op_sel_hi:[1,0,1]
	v_mov_b32_e32 v240, 0x3e800000
	v_pk_fma_f32 v[242:243], v[240:241], v[2:3], v[236:237] op_sel_hi:[0,1,1] neg_lo:[0,0,1] neg_hi:[0,0,1]
	v_pk_fma_f32 v[236:237], v[240:241], v[4:5], v[238:239] op_sel_hi:[0,1,1] neg_lo:[0,0,1] neg_hi:[0,0,1]
	v_cvt_pk_bf16_f32 v242, v242, v243
	v_cvt_pk_bf16_f32 v243, v236, v237
	global_store_dwordx2 v222, v[242:243], s[34:35]
	s_add_u32 s34, s34, 0x800
	s_addc_u32 s35, s35, 0
	s_waitcnt lgkmcnt(4)
	v_xor_b32_e32 v239, 0x80000000, v187
	v_xor_b32_e32 v238, 0x80000000, v186
	v_pk_fma_f32 v[4:5], v[238:239], v[248:249], v[4:5] op_sel_hi:[1,0,1]
	v_pk_fma_f32 v[2:3], v[184:185], v[248:249], v[2:3] op_sel_hi:[1,0,1] neg_lo:[1,0,0] neg_hi:[1,0,0]
	s_waitcnt lgkmcnt(3)
	s_waitcnt vmcnt(31)
	v_pk_mul_f32 v[236:237], v[200:201], v[232:233] op_sel_hi:[1,0]
	v_pk_fma_f32 v[2:3], v[200:201], v[232:233], v[2:3] op_sel_hi:[1,0,1]
	v_pk_mul_f32 v[238:239], v[202:203], v[232:233] op_sel_hi:[1,0]
	v_pk_fma_f32 v[4:5], v[202:203], v[232:233], v[4:5] op_sel_hi:[1,0,1]
	v_mov_b32_e32 v240, 0x3e800000
	v_pk_fma_f32 v[242:243], v[240:241], v[2:3], v[236:237] op_sel_hi:[0,1,1] neg_lo:[0,0,1] neg_hi:[0,0,1]
	v_pk_fma_f32 v[236:237], v[240:241], v[4:5], v[238:239] op_sel_hi:[0,1,1] neg_lo:[0,0,1] neg_hi:[0,0,1]
	v_cvt_pk_bf16_f32 v242, v242, v243
	v_cvt_pk_bf16_f32 v243, v236, v237
	global_store_dwordx2 v222, v[242:243], s[34:35]
	s_add_u32 s34, s34, 0x800
	s_addc_u32 s35, s35, 0
	s_waitcnt lgkmcnt(2)
	v_xor_b32_e32 v239, 0x80000000, v191
	v_xor_b32_e32 v238, 0x80000000, v190
	v_pk_fma_f32 v[4:5], v[238:239], v[224:225], v[4:5] op_sel_hi:[1,0,1]
	v_pk_fma_f32 v[2:3], v[188:189], v[224:225], v[2:3] op_sel_hi:[1,0,1] neg_lo:[1,0,0] neg_hi:[1,0,0]
	s_waitcnt lgkmcnt(1)
	s_waitcnt vmcnt(31)
	v_pk_mul_f32 v[236:237], v[216:217], v[226:227] op_sel_hi:[1,0]
	v_pk_fma_f32 v[2:3], v[216:217], v[226:227], v[2:3] op_sel_hi:[1,0,1]
	v_pk_mul_f32 v[238:239], v[218:219], v[226:227] op_sel_hi:[1,0]
	v_pk_fma_f32 v[4:5], v[218:219], v[226:227], v[4:5] op_sel_hi:[1,0,1]
	v_mov_b32_e32 v240, 0x3e800000
	v_pk_fma_f32 v[242:243], v[240:241], v[2:3], v[236:237] op_sel_hi:[0,1,1] neg_lo:[0,0,1] neg_hi:[0,0,1]
	v_pk_fma_f32 v[236:237], v[240:241], v[4:5], v[238:239] op_sel_hi:[0,1,1] neg_lo:[0,0,1] neg_hi:[0,0,1]
	v_cvt_pk_bf16_f32 v242, v242, v243
	v_cvt_pk_bf16_f32 v243, v236, v237
	global_store_dwordx2 v222, v[242:243], s[34:35]
	s_add_u32 s34, s34, 0x800
	s_addc_u32 s35, s35, 0
	s_waitcnt lgkmcnt(0)
	v_xor_b32_e32 v239, 0x80000000, v195
	v_xor_b32_e32 v238, 0x80000000, v194
	v_pk_fma_f32 v[4:5], v[238:239], v[228:229], v[4:5] op_sel_hi:[1,0,1]
	v_pk_fma_f32 v[2:3], v[192:193], v[228:229], v[2:3] op_sel_hi:[1,0,1] neg_lo:[1,0,0] neg_hi:[1,0,0]
	s_branch .Lpool_done
.Lpool_v2:
	ds_read_b32 v224, v223 offset:32
	ds_read_b32 v226, v223 offset:36
	ds_read_b32 v228, v223 offset:40
	ds_read_b32 v230, v223 offset:44
	ds_read_b32 v244, v223 offset:48
	ds_read_b32 v246, v223 offset:52
	v_mov_b32_e32 v2, 0
	v_mov_b32_e32 v3, 0
	v_mov_b32_e32 v4, 0
	v_mov_b32_e32 v5, 0
	s_cmp_eq_u32 s14, 0
	s_cbranch_scc1 .Lpool_v2_nopre
	s_waitcnt vmcnt(32)
	s_waitcnt lgkmcnt(5)
	v_pk_fma_f32 v[4:5], v[54:55], v[224:225], v[4:5] op_sel_hi:[1,0,1]
	v_pk_fma_f32 v[2:3], v[52:53], v[224:225], v[2:3] op_sel_hi:[1,0,1]
	ds_read_b32 v248, v223 offset:56
	s_waitcnt lgkmcnt(5)
	v_pk_fma_f32 v[4:5], v[58:59], v[226:227], v[4:5] op_sel_hi:[1,0,1]
	v_pk_fma_f32 v[2:3], v[56:57], v[226:227], v[2:3] op_sel_hi:[1,0,1]
	ds_read_b32 v232, v223 offset:60
	s_waitcnt lgkmcnt(5)
	v_pk_fma_f32 v[4:5], v[62:63], v[228:229], v[4:5] op_sel_hi:[1,0,1]
	v_pk_fma_f32 v[2:3], v[60:61], v[228:229], v[2:3] op_sel_hi:[1,0,1]
	ds_read_b32 v224, v223 offset:32
	s_waitcnt lgkmcnt(5)
	v_pk_fma_f32 v[4:5], v[66:67], v[230:231], v[4:5] op_sel_hi:[1,0,1]
	v_pk_fma_f32 v[2:3], v[64:65], v[230:231], v[2:3] op_sel_hi:[1,0,1]
	ds_read_b32 v226, v223 offset:64
	s_waitcnt lgkmcnt(5)
	v_pk_fma_f32 v[4:5], v[70:71], v[244:245], v[4:5] op_sel_hi:[1,0,1]
	v_pk_fma_f32 v[2:3], v[68:69], v[244:245], v[2:3] op_sel_hi:[1,0,1]
	ds_read_b32 v228, v223 offset:36
	s_waitcnt lgkmcnt(5)
	v_pk_fma_f32 v[4:5], v[74:75], v[246:247], v[4:5] op_sel_hi:[1,0,1]
	v_pk_fma_f32 v[2:3], v[72:73], v[246:247], v[2:3] op_sel_hi:[1,0,1]
	ds_read_b32 v230, v223 offset:68
	s_waitcnt lgkmcnt(5)
	v_pk_fma_f32 v[4:5], v[78:79], v[248:249], v[4:5] op_sel_hi:[1,0,1]
	v_pk_fma_f32 v[2:3], v[76:77], v[248:249], v[2:3] op_sel_hi:[1,0,1]
	ds_read_b32 v244, v223 offset:40
	s_branch .Lpool_v2_main
.Lpool_v2_nopre:
	ds_read_b32 v248, v223 offset:56
	ds_read_b32 v232, v223 offset:60
	ds_read_b32 v224, v223 offset:32
	ds_read_b32 v226, v223 offset:64
	ds_read_b32 v228, v223 offset:36
	ds_read_b32 v230, v223 offset:68
	ds_read_b32 v244, v223 offset:40
.Lpool_v2_main:
	s_waitcnt lgkmcnt(5)
	s_waitcnt vmcnt(31)
	v_pk_mul_f32 v[236:237], v[80:81], v[232:233] op_sel_hi:[1,0]
	v_pk_fma_f32 v[2:3], v[80:81], v[232:233], v[2:3] op_sel_hi:[1,0,1]
	v_pk_mul_f32 v[238:239], v[82:83], v[232:233] op_sel_hi:[1,0]
	v_pk_fma_f32 v[4:5], v[82:83], v[232:233], v[4:5] op_sel_hi:[1,0,1]
	ds_read_b32 v246, v223 offset:72
	s_mov_b32 s36, 0x3e000000
	s_cmp_eq_u32 s14, 0
	s_cselect_b32 s36, 0x3f800000, s36
	v_mov_b32_e32 v240, s36
	v_pk_fma_f32 v[242:243], v[240:241], v[2:3], v[236:237] op_sel_hi:[0,1,1] neg_lo:[0,0,1] neg_hi:[0,0,1]
	v_pk_fma_f32 v[236:237], v[240:241], v[4:5], v[238:239] op_sel_hi:[0,1,1] neg_lo:[0,0,1] neg_hi:[0,0,1]
	v_cvt_pk_bf16_f32 v242, v242, v243
	v_cvt_pk_bf16_f32 v243, v236, v237
	global_store_dwordx2 v222, v[242:243], s[34:35]
	s_add_u32 s34, s34, 0x800
	s_addc_u32 s35, s35, 0
	s_waitcnt lgkmcnt(5)
	s_cmp_eq_u32 s14, 0
	s_cbranch_scc1 .Lpool_v2_ns0
	v_xor_b32_e32 v239, 0x80000000, v55
	v_xor_b32_e32 v238, 0x80000000, v54
	v_pk_fma_f32 v[4:5], v[238:239], v[224:225], v[4:5] op_sel_hi:[1,0,1]
	v_pk_fma_f32 v[2:3], v[52:53], v[224:225], v[2:3] op_sel_hi:[1,0,1] neg_lo:[1,0,0] neg_hi:[1,0,0]
.Lpool_v2_ns0:
	ds_read_b32 v248, v223 offset:44
	s_waitcnt lgkmcnt(5)
	s_waitcnt vmcnt(31)
	v_pk_mul_f32 v[236:237], v[84:85], v[226:227] op_sel_hi:[1,0]
	v_pk_fma_f32 v[2:3], v[84:85], v[226:227], v[2:3] op_sel_hi:[1,0,1]
	v_pk_mul_f32 v[238:239], v[86:87], v[226:227] op_sel_hi:[1,0]
	v_pk_fma_f32 v[4:5], v[86:87], v[226:227], v[4:5] op_sel_hi:[1,0,1]
	ds_read_b32 v232, v223 offset:76
	s_mov_b32 s36, 0x3e000000
	s_cmp_eq_u32 s14, 0
	s_cselect_b32 s36, 0x3f000000, s36
	v_mov_b32_e32 v240, s36
	v_pk_fma_f32 v[242:243], v[240:241], v[2:3], v[236:237] op_sel_hi:[0,1,1] neg_lo:[0,0,1] neg_hi:[0,0,1]
	v_pk_fma_f32 v[236:237], v[240:241], v[4:5], v[238:239] op_sel_hi:[0,1,1] neg_lo:[0,0,1] neg_hi:[0,0,1]
	v_cvt_pk_bf16_f32 v242, v242, v243
	v_cvt_pk_bf16_f32 v243, v236, v237
	global_store_dwordx2 v222, v[242:243], s[34:35]
	s_add_u32 s34, s34, 0x800
	s_addc_u32 s35, s35, 0
	s_waitcnt lgkmcnt(5)
	s_cmp_eq_u32 s14, 0
	s_cbranch_scc1 .Lpool_v2_ns1
	v_xor_b32_e32 v239, 0x80000000, v59
	v_xor_b32_e32 v238, 0x80000000, v58
	v_pk_fma_f32 v[4:5], v[238:239], v[228:229], v[4:5] op_sel_hi:[1,0,1]
	v_pk_fma_f32 v[2:3], v[56:57], v[228:229], v[2:3] op_sel_hi:[1,0,1] neg_lo:[1,0,0] neg_hi:[1,0,0]
.Lpool_v2_ns1:
	ds_read_b32 v224, v223 offset:48
	s_waitcnt lgkmcnt(5)
	s_waitcnt vmcnt(31)
	v_pk_mul_f32 v[236:237], v[88:89], v[230:231] op_sel_hi:[1,0]
	v_pk_fma_f32 v[2:3], v[88:89], v[230:231], v[2:3] op_sel_hi:[1,0,1]
	v_pk_mul_f32 v[238:239], v[90:91], v[230:231] op_sel_hi:[1,0]
	v_pk_fma_f32 v[4:5], v[90:91], v[230:231], v[4:5] op_sel_hi:[1,0,1]
	ds_read_b32 v226, v223 offset:80
	s_mov_b32 s36, 0x3e000000
	s_cmp_eq_u32 s14, 0
	s_cselect_b32 s36, 0x3eaaaaab, s36
	v_mov_b32_e32 v240, s36
	v_pk_fma_f32 v[242:243], v[240:241], v[2:3], v[236:237] op_sel_hi:[0,1,1] neg_lo:[0,0,1] neg_hi:[0,0,1]
	v_pk_fma_f32 v[236:237], v[240:241], v[4:5], v[238:239] op_sel_hi:[0,1,1] neg_lo:[0,0,1] neg_hi:[0,0,1]
	v_cvt_pk_bf16_f32 v242, v242, v243
	v_cvt_pk_bf16_f32 v243, v236, v237
	global_store_dwordx2 v222, v[242:243], s[34:35]
	s_add_u32 s34, s34, 0x800
	s_addc_u32 s35, s35, 0
	s_waitcnt lgkmcnt(5)
	s_cmp_eq_u32 s14, 0
	s_cbranch_scc1 .Lpool_v2_ns2
	v_xor_b32_e32 v239, 0x80000000, v63
	v_xor_b32_e32 v238, 0x80000000, v62
	v_pk_fma_f32 v[4:5], v[238:239], v[244:245], v[4:5] op_sel_hi:[1,0,1]
	v_pk_fma_f32 v[2:3], v[60:61], v[244:245], v[2:3] op_sel_hi:[1,0,1] neg_lo:[1,0,0] neg_hi:[1,0,0]
.Lpool_v2_ns2:
	ds_read_b32 v228, v223 offset:52
	s_waitcnt lgkmcnt(5)
	s_waitcnt vmcnt(31)
	v_pk_mul_f32 v[236:237], v[92:93], v[246:247] op_sel_hi:[1,0]
	v_pk_fma_f32 v[2:3], v[92:93], v[246:247], v[2:3] op_sel_hi:[1,0,1]
	v_pk_mul_f32 v[238:239], v[94:95], v[246:247] op_sel_hi:[1,0]
	v_pk_fma_f32 v[4:5], v[94:95], v[246:247], v[4:5] op_sel_hi:[1,0,1]
	ds_read_b32 v230, v223 offset:84
	s_mov_b32 s36, 0x3e000000
	s_cmp_eq_u32 s14, 0
	s_cselect_b32 s36, 0x3e800000, s36
	v_mov_b32_e32 v240, s36
	v_pk_fma_f32 v[242:243], v[240:241], v[2:3], v[236:237] op_sel_hi:[0,1,1] neg_lo:[0,0,1] neg_hi:[0,0,1]
	v_pk_fma_f32 v[236:237], v[240:241], v[4:5], v[238:239] op_sel_hi:[0,1,1] neg_lo:[0,0,1] neg_hi:[0,0,1]
	v_cvt_pk_bf16_f32 v242, v242, v243
	v_cvt_pk_bf16_f32 v243, v236, v237
	global_store_dwordx2 v222, v[242:243], s[34:35]
	s_add_u32 s34, s34, 0x800
	s_addc_u32 s35, s35, 0
	s_waitcnt lgkmcnt(5)
	s_cmp_eq_u32 s14, 0
	s_cbranch_scc1 .Lpool_v2_ns3
	v_xor_b32_e32 v239, 0x80000000, v67
	v_xor_b32_e32 v238, 0x80000000, v66
	v_pk_fma_f32 v[4:5], v[238:239], v[248:249], v[4:5] op_sel_hi:[1,0,1]
	v_pk_fma_f32 v[2:3], v[64:65], v[248:249], v[2:3] op_sel_hi:[1,0,1] neg_lo:[1,0,0] neg_hi:[1,0,0]
.Lpool_v2_ns3:
	ds_read_b32 v244, v223 offset:56
	s_waitcnt lgkmcnt(5)
	s_waitcnt vmcnt(31)
	v_pk_mul_f32 v[236:237], v[96:97], v[232:233] op_sel_hi:[1,0]
	v_pk_fma_f32 v[2:3], v[96:97], v[232:233], v[2:3] op_sel_hi:[1,0,1]
	v_pk_mul_f32 v[238:239], v[98:99], v[232:233] op_sel_hi:[1,0]
	v_pk_fma_f32 v[4:5], v[98:99], v[232:233], v[4:5] op_sel_hi:[1,0,1]
	ds_read_b32 v246, v223 offset:88
	s_mov_b32 s36, 0x3e000000
	s_cmp_eq_u32 s14, 0
	s_cselect_b32 s36, 0x3e4ccccd, s36
	v_mov_b32_e32 v240, s36
	v_pk_fma_f32 v[242:243], v[240:241], v[2:3], v[236:237] op_sel_hi:[0,1,1] neg_lo:[0,0,1] neg_hi:[0,0,1]
	v_pk_fma_f32 v[236:237], v[240:241], v[4:5], v[238:239] op_sel_hi:[0,1,1] neg_lo:[0,0,1] neg_hi:[0,0,1]
	v_cvt_pk_bf16_f32 v242, v242, v243
	v_cvt_pk_bf16_f32 v243, v236, v237
	global_store_dwordx2 v222, v[242:243], s[34:35]
	s_add_u32 s34, s34, 0x800
	s_addc_u32 s35, s35, 0
	s_waitcnt lgkmcnt(5)
	s_cmp_eq_u32 s14, 0
	s_cbranch_scc1 .Lpool_v2_ns4
	v_xor_b32_e32 v239, 0x80000000, v71
	v_xor_b32_e32 v238, 0x80000000, v70
	v_pk_fma_f32 v[4:5], v[238:239], v[224:225], v[4:5] op_sel_hi:[1,0,1]
	v_pk_fma_f32 v[2:3], v[68:69], v[224:225], v[2:3] op_sel_hi:[1,0,1] neg_lo:[1,0,0] neg_hi:[1,0,0]
.Lpool_v2_ns4:
	ds_read_b32 v248, v223 offset:60
	s_waitcnt lgkmcnt(5)
	s_waitcnt vmcnt(31)
	v_pk_mul_f32 v[236:237], v[100:101], v[226:227] op_sel_hi:[1,0]
	v_pk_fma_f32 v[2:3], v[100:101], v[226:227], v[2:3] op_sel_hi:[1,0,1]
	v_pk_mul_f32 v[238:239], v[102:103], v[226:227] op_sel_hi:[1,0]
	v_pk_fma_f32 v[4:5], v[102:103], v[226:227], v[4:5] op_sel_hi:[1,0,1]
	ds_read_b32 v232, v223 offset:92
	s_mov_b32 s36, 0x3e000000
	s_cmp_eq_u32 s14, 0
	s_cselect_b32 s36, 0x3e2aaaab, s36
	v_mov_b32_e32 v240, s36
	v_pk_fma_f32 v[242:243], v[240:241], v[2:3], v[236:237] op_sel_hi:[0,1,1] neg_lo:[0,0,1] neg_hi:[0,0,1]
	v_pk_fma_f32 v[236:237], v[240:241], v[4:5], v[238:239] op_sel_hi:[0,1,1] neg_lo:[0,0,1] neg_hi:[0,0,1]
	v_cvt_pk_bf16_f32 v242, v242, v243
	v_cvt_pk_bf16_f32 v243, v236, v237
	global_store_dwordx2 v222, v[242:243], s[34:35]
	s_add_u32 s34, s34, 0x800
	s_addc_u32 s35, s35, 0
	s_waitcnt lgkmcnt(5)
	s_cmp_eq_u32 s14, 0
	s_cbranch_scc1 .Lpool_v2_ns5
	v_xor_b32_e32 v239, 0x80000000, v75
	v_xor_b32_e32 v238, 0x80000000, v74
	v_pk_fma_f32 v[4:5], v[238:239], v[228:229], v[4:5] op_sel_hi:[1,0,1]
	v_pk_fma_f32 v[2:3], v[72:73], v[228:229], v[2:3] op_sel_hi:[1,0,1] neg_lo:[1,0,0] neg_hi:[1,0,0]
.Lpool_v2_ns5:
	ds_read_b32 v224, v223 offset:64
	s_waitcnt lgkmcnt(5)
	s_waitcnt vmcnt(31)
	v_pk_mul_f32 v[236:237], v[104:105], v[230:231] op_sel_hi:[1,0]
	v_pk_fma_f32 v[2:3], v[104:105], v[230:231], v[2:3] op_sel_hi:[1,0,1]
	v_pk_mul_f32 v[238:239], v[106:107], v[230:231] op_sel_hi:[1,0]
	v_pk_fma_f32 v[4:5], v[106:107], v[230:231], v[4:5] op_sel_hi:[1,0,1]
	ds_read_b32 v226, v223 offset:96
	s_mov_b32 s36, 0x3e000000
	s_cmp_eq_u32 s14, 0
	s_cselect_b32 s36, 0x3e124925, s36
	v_mov_b32_e32 v240, s36
	v_pk_fma_f32 v[242:243], v[240:241], v[2:3], v[236:237] op_sel_hi:[0,1,1] neg_lo:[0,0,1] neg_hi:[0,0,1]
	v_pk_fma_f32 v[236:237], v[240:241], v[4:5], v[238:239] op_sel_hi:[0,1,1] neg_lo:[0,0,1] neg_hi:[0,0,1]
	v_cvt_pk_bf16_f32 v242, v242, v243
	v_cvt_pk_bf16_f32 v243, v236, v237
	global_store_dwordx2 v222, v[242:243], s[34:35]
	s_add_u32 s34, s34, 0x800
	s_addc_u32 s35, s35, 0
	s_waitcnt lgkmcnt(5)
	s_cmp_eq_u32 s14, 0
	s_cbranch_scc1 .Lpool_v2_ns6
	v_xor_b32_e32 v239, 0x80000000, v79
	v_xor_b32_e32 v238, 0x80000000, v78
	v_pk_fma_f32 v[4:5], v[238:239], v[244:245], v[4:5] op_sel_hi:[1,0,1]
	v_pk_fma_f32 v[2:3], v[76:77], v[244:245], v[2:3] op_sel_hi:[1,0,1] neg_lo:[1,0,0] neg_hi:[1,0,0]
.Lpool_v2_ns6:
	ds_read_b32 v228, v223 offset:68
	s_waitcnt lgkmcnt(5)
	s_waitcnt vmcnt(31)
	v_pk_mul_f32 v[236:237], v[108:109], v[246:247] op_sel_hi:[1,0]
	v_pk_fma_f32 v[2:3], v[108:109], v[246:247], v[2:3] op_sel_hi:[1,0,1]
	v_pk_mul_f32 v[238:239], v[110:111], v[246:247] op_sel_hi:[1,0]
	v_pk_fma_f32 v[4:5], v[110:111], v[246:247], v[4:5] op_sel_hi:[1,0,1]
	ds_read_b32 v230, v223 offset:100
	v_mov_b32_e32 v240, 0x3e000000
	v_pk_fma_f32 v[242:243], v[240:241], v[2:3], v[236:237] op_sel_hi:[0,1,1] neg_lo:[0,0,1] neg_hi:[0,0,1]
	v_pk_fma_f32 v[236:237], v[240:241], v[4:5], v[238:239] op_sel_hi:[0,1,1] neg_lo:[0,0,1] neg_hi:[0,0,1]
	v_cvt_pk_bf16_f32 v242, v242, v243
	v_cvt_pk_bf16_f32 v243, v236, v237
	global_store_dwordx2 v222, v[242:243], s[34:35]
	s_add_u32 s34, s34, 0x800
	s_addc_u32 s35, s35, 0
	s_waitcnt lgkmcnt(5)
	v_xor_b32_e32 v239, 0x80000000, v83
	v_xor_b32_e32 v238, 0x80000000, v82
	v_pk_fma_f32 v[4:5], v[238:239], v[248:249], v[4:5] op_sel_hi:[1,0,1]
	v_pk_fma_f32 v[2:3], v[80:81], v[248:249], v[2:3] op_sel_hi:[1,0,1] neg_lo:[1,0,0] neg_hi:[1,0,0]
	ds_read_b32 v244, v223 offset:72
	s_waitcnt lgkmcnt(5)
	s_waitcnt vmcnt(31)
	v_pk_mul_f32 v[236:237], v[112:113], v[232:233] op_sel_hi:[1,0]
	v_pk_fma_f32 v[2:3], v[112:113], v[232:233], v[2:3] op_sel_hi:[1,0,1]
	v_pk_mul_f32 v[238:239], v[114:115], v[232:233] op_sel_hi:[1,0]
	v_pk_fma_f32 v[4:5], v[114:115], v[232:233], v[4:5] op_sel_hi:[1,0,1]
	ds_read_b32 v246, v223 offset:104
	v_mov_b32_e32 v240, 0x3e000000
	v_pk_fma_f32 v[242:243], v[240:241], v[2:3], v[236:237] op_sel_hi:[0,1,1] neg_lo:[0,0,1] neg_hi:[0,0,1]
	v_pk_fma_f32 v[236:237], v[240:241], v[4:5], v[238:239] op_sel_hi:[0,1,1] neg_lo:[0,0,1] neg_hi:[0,0,1]
	v_cvt_pk_bf16_f32 v242, v242, v243
	v_cvt_pk_bf16_f32 v243, v236, v237
	global_store_dwordx2 v222, v[242:243], s[34:35]
	s_add_u32 s34, s34, 0x800
	s_addc_u32 s35, s35, 0
	s_waitcnt lgkmcnt(5)
	v_xor_b32_e32 v239, 0x80000000, v87
	v_xor_b32_e32 v238, 0x80000000, v86
	v_pk_fma_f32 v[4:5], v[238:239], v[224:225], v[4:5] op_sel_hi:[1,0,1]
	v_pk_fma_f32 v[2:3], v[84:85], v[224:225], v[2:3] op_sel_hi:[1,0,1] neg_lo:[1,0,0] neg_hi:[1,0,0]
	ds_read_b32 v248, v223 offset:76
	s_waitcnt lgkmcnt(5)
	s_waitcnt vmcnt(31)
	v_pk_mul_f32 v[236:237], v[116:117], v[226:227] op_sel_hi:[1,0]
	v_pk_fma_f32 v[2:3], v[116:117], v[226:227], v[2:3] op_sel_hi:[1,0,1]
	v_pk_mul_f32 v[238:239], v[118:119], v[226:227] op_sel_hi:[1,0]
	v_pk_fma_f32 v[4:5], v[118:119], v[226:227], v[4:5] op_sel_hi:[1,0,1]
	ds_read_b32 v232, v223 offset:108
	v_mov_b32_e32 v240, 0x3e000000
	v_pk_fma_f32 v[242:243], v[240:241], v[2:3], v[236:237] op_sel_hi:[0,1,1] neg_lo:[0,0,1] neg_hi:[0,0,1]
	v_pk_fma_f32 v[236:237], v[240:241], v[4:5], v[238:239] op_sel_hi:[0,1,1] neg_lo:[0,0,1] neg_hi:[0,0,1]
	v_cvt_pk_bf16_f32 v242, v242, v243
	v_cvt_pk_bf16_f32 v243, v236, v237
	global_store_dwordx2 v222, v[242:243], s[34:35]
	s_add_u32 s34, s34, 0x800
	s_addc_u32 s35, s35, 0
	s_waitcnt lgkmcnt(5)
	v_xor_b32_e32 v239, 0x80000000, v91
	v_xor_b32_e32 v238, 0x80000000, v90
	v_pk_fma_f32 v[4:5], v[238:239], v[228:229], v[4:5] op_sel_hi:[1,0,1]
	v_pk_fma_f32 v[2:3], v[88:89], v[228:229], v[2:3] op_sel_hi:[1,0,1] neg_lo:[1,0,0] neg_hi:[1,0,0]
	ds_read_b32 v224, v223 offset:80
	s_waitcnt lgkmcnt(5)
	s_waitcnt vmcnt(31)
	v_pk_mul_f32 v[236:237], v[120:121], v[230:231] op_sel_hi:[1,0]
	v_pk_fma_f32 v[2:3], v[120:121], v[230:231], v[2:3] op_sel_hi:[1,0,1]
	v_pk_mul_f32 v[238:239], v[122:123], v[230:231] op_sel_hi:[1,0]
	v_pk_fma_f32 v[4:5], v[122:123], v[230:231], v[4:5] op_sel_hi:[1,0,1]
	ds_read_b32 v226, v223 offset:112
	v_mov_b32_e32 v240, 0x3e000000
	v_pk_fma_f32 v[242:243], v[240:241], v[2:3], v[236:237] op_sel_hi:[0,1,1] neg_lo:[0,0,1] neg_hi:[0,0,1]
	v_pk_fma_f32 v[236:237], v[240:241], v[4:5], v[238:239] op_sel_hi:[0,1,1] neg_lo:[0,0,1] neg_hi:[0,0,1]
	v_cvt_pk_bf16_f32 v242, v242, v243
	v_cvt_pk_bf16_f32 v243, v236, v237
	global_store_dwordx2 v222, v[242:243], s[34:35]
	s_add_u32 s34, s34, 0x800
	s_addc_u32 s35, s35, 0
	s_waitcnt lgkmcnt(5)
	v_xor_b32_e32 v239, 0x80000000, v95
	v_xor_b32_e32 v238, 0x80000000, v94
	v_pk_fma_f32 v[4:5], v[238:239], v[244:245], v[4:5] op_sel_hi:[1,0,1]
	v_pk_fma_f32 v[2:3], v[92:93], v[244:245], v[2:3] op_sel_hi:[1,0,1] neg_lo:[1,0,0] neg_hi:[1,0,0]
	ds_read_b32 v228, v223 offset:84
	s_waitcnt lgkmcnt(5)
	s_waitcnt vmcnt(31)
	v_pk_mul_f32 v[236:237], v[124:125], v[246:247] op_sel_hi:[1,0]
	v_pk_fma_f32 v[2:3], v[124:125], v[246:247], v[2:3] op_sel_hi:[1,0,1]
	v_pk_mul_f32 v[238:239], v[126:127], v[246:247] op_sel_hi:[1,0]
	v_pk_fma_f32 v[4:5], v[126:127], v[246:247], v[4:5] op_sel_hi:[1,0,1]
	ds_read_b32 v230, v223 offset:116
	v_mov_b32_e32 v240, 0x3e000000
	v_pk_fma_f32 v[242:243], v[240:241], v[2:3], v[236:237] op_sel_hi:[0,1,1] neg_lo:[0,0,1] neg_hi:[0,0,1]
	v_pk_fma_f32 v[236:237], v[240:241], v[4:5], v[238:239] op_sel_hi:[0,1,1] neg_lo:[0,0,1] neg_hi:[0,0,1]
	v_cvt_pk_bf16_f32 v242, v242, v243
	v_cvt_pk_bf16_f32 v243, v236, v237
	global_store_dwordx2 v222, v[242:243], s[34:35]
	s_add_u32 s34, s34, 0x800
	s_addc_u32 s35, s35, 0
	s_waitcnt lgkmcnt(5)
	v_xor_b32_e32 v239, 0x80000000, v99
	v_xor_b32_e32 v238, 0x80000000, v98
	v_pk_fma_f32 v[4:5], v[238:239], v[248:249], v[4:5] op_sel_hi:[1,0,1]
	v_pk_fma_f32 v[2:3], v[96:97], v[248:249], v[2:3] op_sel_hi:[1,0,1] neg_lo:[1,0,0] neg_hi:[1,0,0]
	ds_read_b32 v244, v223 offset:88
	s_waitcnt lgkmcnt(5)
	s_waitcnt vmcnt(31)
	v_pk_mul_f32 v[236:237], v[128:129], v[232:233] op_sel_hi:[1,0]
	v_pk_fma_f32 v[2:3], v[128:129], v[232:233], v[2:3] op_sel_hi:[1,0,1]
	v_pk_mul_f32 v[238:239], v[130:131], v[232:233] op_sel_hi:[1,0]
	v_pk_fma_f32 v[4:5], v[130:131], v[232:233], v[4:5] op_sel_hi:[1,0,1]
	ds_read_b32 v246, v223 offset:120
	v_mov_b32_e32 v240, 0x3e000000
	v_pk_fma_f32 v[242:243], v[240:241], v[2:3], v[236:237] op_sel_hi:[0,1,1] neg_lo:[0,0,1] neg_hi:[0,0,1]
	v_pk_fma_f32 v[236:237], v[240:241], v[4:5], v[238:239] op_sel_hi:[0,1,1] neg_lo:[0,0,1] neg_hi:[0,0,1]
	v_cvt_pk_bf16_f32 v242, v242, v243
	v_cvt_pk_bf16_f32 v243, v236, v237
	global_store_dwordx2 v222, v[242:243], s[34:35]
	s_add_u32 s34, s34, 0x800
	s_addc_u32 s35, s35, 0
	s_waitcnt lgkmcnt(5)
	v_xor_b32_e32 v239, 0x80000000, v103
	v_xor_b32_e32 v238, 0x80000000, v102
	v_pk_fma_f32 v[4:5], v[238:239], v[224:225], v[4:5] op_sel_hi:[1,0,1]
	v_pk_fma_f32 v[2:3], v[100:101], v[224:225], v[2:3] op_sel_hi:[1,0,1] neg_lo:[1,0,0] neg_hi:[1,0,0]
	ds_read_b32 v248, v223 offset:92
	s_waitcnt lgkmcnt(5)
	s_waitcnt vmcnt(31)
	v_pk_mul_f32 v[236:237], v[132:133], v[226:227] op_sel_hi:[1,0]
	v_pk_fma_f32 v[2:3], v[132:133], v[226:227], v[2:3] op_sel_hi:[1,0,1]
	v_pk_mul_f32 v[238:239], v[134:135], v[226:227] op_sel_hi:[1,0]
	v_pk_fma_f32 v[4:5], v[134:135], v[226:227], v[4:5] op_sel_hi:[1,0,1]
	ds_read_b32 v232, v223 offset:124
	v_mov_b32_e32 v240, 0x3e000000
	v_pk_fma_f32 v[242:243], v[240:241], v[2:3], v[236:237] op_sel_hi:[0,1,1] neg_lo:[0,0,1] neg_hi:[0,0,1]
	v_pk_fma_f32 v[236:237], v[240:241], v[4:5], v[238:239] op_sel_hi:[0,1,1] neg_lo:[0,0,1] neg_hi:[0,0,1]
	v_cvt_pk_bf16_f32 v242, v242, v243
	v_cvt_pk_bf16_f32 v243, v236, v237
	global_store_dwordx2 v222, v[242:243], s[34:35]
	s_add_u32 s34, s34, 0x800
	s_addc_u32 s35, s35, 0
	s_waitcnt lgkmcnt(5)
	v_xor_b32_e32 v239, 0x80000000, v107
	v_xor_b32_e32 v238, 0x80000000, v106
	v_pk_fma_f32 v[4:5], v[238:239], v[228:229], v[4:5] op_sel_hi:[1,0,1]
	v_pk_fma_f32 v[2:3], v[104:105], v[228:229], v[2:3] op_sel_hi:[1,0,1] neg_lo:[1,0,0] neg_hi:[1,0,0]
	ds_read_b32 v224, v223 offset:96
	s_waitcnt lgkmcnt(5)
	s_waitcnt vmcnt(31)
	v_pk_mul_f32 v[236:237], v[136:137], v[230:231] op_sel_hi:[1,0]
	v_pk_fma_f32 v[2:3], v[136:137], v[230:231], v[2:3] op_sel_hi:[1,0,1]
	v_pk_mul_f32 v[238:239], v[138:139], v[230:231] op_sel_hi:[1,0]
	v_pk_fma_f32 v[4:5], v[138:139], v[230:231], v[4:5] op_sel_hi:[1,0,1]
	ds_read_b32 v226, v223 offset:128
	v_mov_b32_e32 v240, 0x3e000000
	v_pk_fma_f32 v[242:243], v[240:241], v[2:3], v[236:237] op_sel_hi:[0,1,1] neg_lo:[0,0,1] neg_hi:[0,0,1]
	v_pk_fma_f32 v[236:237], v[240:241], v[4:5], v[238:239] op_sel_hi:[0,1,1] neg_lo:[0,0,1] neg_hi:[0,0,1]
	v_cvt_pk_bf16_f32 v242, v242, v243
	v_cvt_pk_bf16_f32 v243, v236, v237
	global_store_dwordx2 v222, v[242:243], s[34:35]
	s_add_u32 s34, s34, 0x800
	s_addc_u32 s35, s35, 0
	s_waitcnt lgkmcnt(5)
	v_xor_b32_e32 v239, 0x80000000, v111
	v_xor_b32_e32 v238, 0x80000000, v110
	v_pk_fma_f32 v[4:5], v[238:239], v[244:245], v[4:5] op_sel_hi:[1,0,1]
	v_pk_fma_f32 v[2:3], v[108:109], v[244:245], v[2:3] op_sel_hi:[1,0,1] neg_lo:[1,0,0] neg_hi:[1,0,0]
	ds_read_b32 v228, v223 offset:100
	s_waitcnt lgkmcnt(5)
	s_waitcnt vmcnt(31)
	v_pk_mul_f32 v[236:237], v[140:141], v[246:247] op_sel_hi:[1,0]
	v_pk_fma_f32 v[2:3], v[140:141], v[246:247], v[2:3] op_sel_hi:[1,0,1]
	v_pk_mul_f32 v[238:239], v[142:143], v[246:247] op_sel_hi:[1,0]
	v_pk_fma_f32 v[4:5], v[142:143], v[246:247], v[4:5] op_sel_hi:[1,0,1]
	ds_read_b32 v230, v223 offset:132
	v_mov_b32_e32 v240, 0x3e000000
	v_pk_fma_f32 v[242:243], v[240:241], v[2:3], v[236:237] op_sel_hi:[0,1,1] neg_lo:[0,0,1] neg_hi:[0,0,1]
	v_pk_fma_f32 v[236:237], v[240:241], v[4:5], v[238:239] op_sel_hi:[0,1,1] neg_lo:[0,0,1] neg_hi:[0,0,1]
	v_cvt_pk_bf16_f32 v242, v242, v243
	v_cvt_pk_bf16_f32 v243, v236, v237
	global_store_dwordx2 v222, v[242:243], s[34:35]
	s_add_u32 s34, s34, 0x800
	s_addc_u32 s35, s35, 0
	s_waitcnt lgkmcnt(5)
	v_xor_b32_e32 v239, 0x80000000, v115
	v_xor_b32_e32 v238, 0x80000000, v114
	v_pk_fma_f32 v[4:5], v[238:239], v[248:249], v[4:5] op_sel_hi:[1,0,1]
	v_pk_fma_f32 v[2:3], v[112:113], v[248:249], v[2:3] op_sel_hi:[1,0,1] neg_lo:[1,0,0] neg_hi:[1,0,0]
	ds_read_b32 v244, v223 offset:104
	s_waitcnt lgkmcnt(5)
	s_waitcnt vmcnt(31)
	v_pk_mul_f32 v[236:237], v[144:145], v[232:233] op_sel_hi:[1,0]
	v_pk_fma_f32 v[2:3], v[144:145], v[232:233], v[2:3] op_sel_hi:[1,0,1]
	v_pk_mul_f32 v[238:239], v[146:147], v[232:233] op_sel_hi:[1,0]
	v_pk_fma_f32 v[4:5], v[146:147], v[232:233], v[4:5] op_sel_hi:[1,0,1]
	ds_read_b32 v246, v223 offset:136
	v_mov_b32_e32 v240, 0x3e000000
	v_pk_fma_f32 v[242:243], v[240:241], v[2:3], v[236:237] op_sel_hi:[0,1,1] neg_lo:[0,0,1] neg_hi:[0,0,1]
	v_pk_fma_f32 v[236:237], v[240:241], v[4:5], v[238:239] op_sel_hi:[0,1,1] neg_lo:[0,0,1] neg_hi:[0,0,1]
	v_cvt_pk_bf16_f32 v242, v242, v243
	v_cvt_pk_bf16_f32 v243, v236, v237
	global_store_dwordx2 v222, v[242:243], s[34:35]
	s_add_u32 s34, s34, 0x800
	s_addc_u32 s35, s35, 0
	s_waitcnt lgkmcnt(5)
	v_xor_b32_e32 v239, 0x80000000, v119
	v_xor_b32_e32 v238, 0x80000000, v118
	v_pk_fma_f32 v[4:5], v[238:239], v[224:225], v[4:5] op_sel_hi:[1,0,1]
	v_pk_fma_f32 v[2:3], v[116:117], v[224:225], v[2:3] op_sel_hi:[1,0,1] neg_lo:[1,0,0] neg_hi:[1,0,0]
	ds_read_b32 v248, v223 offset:108
	s_waitcnt lgkmcnt(5)
	s_waitcnt vmcnt(31)
	v_pk_mul_f32 v[236:237], v[148:149], v[226:227] op_sel_hi:[1,0]
	v_pk_fma_f32 v[2:3], v[148:149], v[226:227], v[2:3] op_sel_hi:[1,0,1]
	v_pk_mul_f32 v[238:239], v[150:151], v[226:227] op_sel_hi:[1,0]
	v_pk_fma_f32 v[4:5], v[150:151], v[226:227], v[4:5] op_sel_hi:[1,0,1]
	ds_read_b32 v232, v223 offset:140
	v_mov_b32_e32 v240, 0x3e000000
	v_pk_fma_f32 v[242:243], v[240:241], v[2:3], v[236:237] op_sel_hi:[0,1,1] neg_lo:[0,0,1] neg_hi:[0,0,1]
	v_pk_fma_f32 v[236:237], v[240:241], v[4:5], v[238:239] op_sel_hi:[0,1,1] neg_lo:[0,0,1] neg_hi:[0,0,1]
	v_cvt_pk_bf16_f32 v242, v242, v243
	v_cvt_pk_bf16_f32 v243, v236, v237
	global_store_dwordx2 v222, v[242:243], s[34:35]
	s_add_u32 s34, s34, 0x800
	s_addc_u32 s35, s35, 0
	s_waitcnt lgkmcnt(5)
	v_xor_b32_e32 v239, 0x80000000, v123
	v_xor_b32_e32 v238, 0x80000000, v122
	v_pk_fma_f32 v[4:5], v[238:239], v[228:229], v[4:5] op_sel_hi:[1,0,1]
	v_pk_fma_f32 v[2:3], v[120:121], v[228:229], v[2:3] op_sel_hi:[1,0,1] neg_lo:[1,0,0] neg_hi:[1,0,0]
	ds_read_b32 v224, v223 offset:112
	s_waitcnt lgkmcnt(5)
	s_waitcnt vmcnt(31)
	v_pk_mul_f32 v[236:237], v[152:153], v[230:231] op_sel_hi:[1,0]
	v_pk_fma_f32 v[2:3], v[152:153], v[230:231], v[2:3] op_sel_hi:[1,0,1]
	v_pk_mul_f32 v[238:239], v[154:155], v[230:231] op_sel_hi:[1,0]
	v_pk_fma_f32 v[4:5], v[154:155], v[230:231], v[4:5] op_sel_hi:[1,0,1]
	ds_read_b32 v226, v223 offset:144
	v_mov_b32_e32 v240, 0x3e000000
	v_pk_fma_f32 v[242:243], v[240:241], v[2:3], v[236:237] op_sel_hi:[0,1,1] neg_lo:[0,0,1] neg_hi:[0,0,1]
	v_pk_fma_f32 v[236:237], v[240:241], v[4:5], v[238:239] op_sel_hi:[0,1,1] neg_lo:[0,0,1] neg_hi:[0,0,1]
	v_cvt_pk_bf16_f32 v242, v242, v243
	v_cvt_pk_bf16_f32 v243, v236, v237
	global_store_dwordx2 v222, v[242:243], s[34:35]
	s_add_u32 s34, s34, 0x800
	s_addc_u32 s35, s35, 0
	s_waitcnt lgkmcnt(5)
	v_xor_b32_e32 v239, 0x80000000, v127
	v_xor_b32_e32 v238, 0x80000000, v126
	v_pk_fma_f32 v[4:5], v[238:239], v[244:245], v[4:5] op_sel_hi:[1,0,1]
	v_pk_fma_f32 v[2:3], v[124:125], v[244:245], v[2:3] op_sel_hi:[1,0,1] neg_lo:[1,0,0] neg_hi:[1,0,0]
	ds_read_b32 v228, v223 offset:116
	s_waitcnt lgkmcnt(5)
	s_waitcnt vmcnt(31)
	v_pk_mul_f32 v[236:237], v[156:157], v[246:247] op_sel_hi:[1,0]
	v_pk_fma_f32 v[2:3], v[156:157], v[246:247], v[2:3] op_sel_hi:[1,0,1]
	v_pk_mul_f32 v[238:239], v[158:159], v[246:247] op_sel_hi:[1,0]
	v_pk_fma_f32 v[4:5], v[158:159], v[246:247], v[4:5] op_sel_hi:[1,0,1]
	ds_read_b32 v230, v223 offset:148
	v_mov_b32_e32 v240, 0x3e000000
	v_pk_fma_f32 v[242:243], v[240:241], v[2:3], v[236:237] op_sel_hi:[0,1,1] neg_lo:[0,0,1] neg_hi:[0,0,1]
	v_pk_fma_f32 v[236:237], v[240:241], v[4:5], v[238:239] op_sel_hi:[0,1,1] neg_lo:[0,0,1] neg_hi:[0,0,1]
	v_cvt_pk_bf16_f32 v242, v242, v243
	v_cvt_pk_bf16_f32 v243, v236, v237
	global_store_dwordx2 v222, v[242:243], s[34:35]
	s_add_u32 s34, s34, 0x800
	s_addc_u32 s35, s35, 0
	s_waitcnt lgkmcnt(5)
	v_xor_b32_e32 v239, 0x80000000, v131
	v_xor_b32_e32 v238, 0x80000000, v130
	v_pk_fma_f32 v[4:5], v[238:239], v[248:249], v[4:5] op_sel_hi:[1,0,1]
	v_pk_fma_f32 v[2:3], v[128:129], v[248:249], v[2:3] op_sel_hi:[1,0,1] neg_lo:[1,0,0] neg_hi:[1,0,0]
	ds_read_b32 v244, v223 offset:120
	s_waitcnt lgkmcnt(5)
	s_waitcnt vmcnt(31)
	v_pk_mul_f32 v[236:237], v[160:161], v[232:233] op_sel_hi:[1,0]
	v_pk_fma_f32 v[2:3], v[160:161], v[232:233], v[2:3] op_sel_hi:[1,0,1]
	v_pk_mul_f32 v[238:239], v[162:163], v[232:233] op_sel_hi:[1,0]
	v_pk_fma_f32 v[4:5], v[162:163], v[232:233], v[4:5] op_sel_hi:[1,0,1]
	ds_read_b32 v246, v223 offset:152
	v_mov_b32_e32 v240, 0x3e000000
	v_pk_fma_f32 v[242:243], v[240:241], v[2:3], v[236:237] op_sel_hi:[0,1,1] neg_lo:[0,0,1] neg_hi:[0,0,1]
	v_pk_fma_f32 v[236:237], v[240:241], v[4:5], v[238:239] op_sel_hi:[0,1,1] neg_lo:[0,0,1] neg_hi:[0,0,1]
	v_cvt_pk_bf16_f32 v242, v242, v243
	v_cvt_pk_bf16_f32 v243, v236, v237
	global_store_dwordx2 v222, v[242:243], s[34:35]
	s_add_u32 s34, s34, 0x800
	s_addc_u32 s35, s35, 0
	s_waitcnt lgkmcnt(5)
	v_xor_b32_e32 v239, 0x80000000, v135
	v_xor_b32_e32 v238, 0x80000000, v134
	v_pk_fma_f32 v[4:5], v[238:239], v[224:225], v[4:5] op_sel_hi:[1,0,1]
	v_pk_fma_f32 v[2:3], v[132:133], v[224:225], v[2:3] op_sel_hi:[1,0,1] neg_lo:[1,0,0] neg_hi:[1,0,0]
	ds_read_b32 v248, v223 offset:124
	s_waitcnt lgkmcnt(5)
	s_waitcnt vmcnt(31)
	v_pk_mul_f32 v[236:237], v[164:165], v[226:227] op_sel_hi:[1,0]
	v_pk_fma_f32 v[2:3], v[164:165], v[226:227], v[2:3] op_sel_hi:[1,0,1]
	v_pk_mul_f32 v[238:239], v[166:167], v[226:227] op_sel_hi:[1,0]
	v_pk_fma_f32 v[4:5], v[166:167], v[226:227], v[4:5] op_sel_hi:[1,0,1]
	ds_read_b32 v232, v223 offset:156
	v_mov_b32_e32 v240, 0x3e000000
	v_pk_fma_f32 v[242:243], v[240:241], v[2:3], v[236:237] op_sel_hi:[0,1,1] neg_lo:[0,0,1] neg_hi:[0,0,1]
	v_pk_fma_f32 v[236:237], v[240:241], v[4:5], v[238:239] op_sel_hi:[0,1,1] neg_lo:[0,0,1] neg_hi:[0,0,1]
	v_cvt_pk_bf16_f32 v242, v242, v243
	v_cvt_pk_bf16_f32 v243, v236, v237
	global_store_dwordx2 v222, v[242:243], s[34:35]
	s_add_u32 s34, s34, 0x800
	s_addc_u32 s35, s35, 0
	s_waitcnt lgkmcnt(5)
	v_xor_b32_e32 v239, 0x80000000, v139
	v_xor_b32_e32 v238, 0x80000000, v138
	v_pk_fma_f32 v[4:5], v[238:239], v[228:229], v[4:5] op_sel_hi:[1,0,1]
	v_pk_fma_f32 v[2:3], v[136:137], v[228:229], v[2:3] op_sel_hi:[1,0,1] neg_lo:[1,0,0] neg_hi:[1,0,0]
	ds_read_b32 v224, v223 offset:128
	s_waitcnt lgkmcnt(5)
	s_waitcnt vmcnt(31)
	v_pk_mul_f32 v[236:237], v[168:169], v[230:231] op_sel_hi:[1,0]
	v_pk_fma_f32 v[2:3], v[168:169], v[230:231], v[2:3] op_sel_hi:[1,0,1]
	v_pk_mul_f32 v[238:239], v[170:171], v[230:231] op_sel_hi:[1,0]
	v_pk_fma_f32 v[4:5], v[170:171], v[230:231], v[4:5] op_sel_hi:[1,0,1]
	ds_read_b32 v226, v223 offset:160
	v_mov_b32_e32 v240, 0x3e000000
	v_pk_fma_f32 v[242:243], v[240:241], v[2:3], v[236:237] op_sel_hi:[0,1,1] neg_lo:[0,0,1] neg_hi:[0,0,1]
	v_pk_fma_f32 v[236:237], v[240:241], v[4:5], v[238:239] op_sel_hi:[0,1,1] neg_lo:[0,0,1] neg_hi:[0,0,1]
	v_cvt_pk_bf16_f32 v242, v242, v243
	v_cvt_pk_bf16_f32 v243, v236, v237
	global_store_dwordx2 v222, v[242:243], s[34:35]
	s_add_u32 s34, s34, 0x800
	s_addc_u32 s35, s35, 0
	s_waitcnt lgkmcnt(5)
	v_xor_b32_e32 v239, 0x80000000, v143
	v_xor_b32_e32 v238, 0x80000000, v142
	v_pk_fma_f32 v[4:5], v[238:239], v[244:245], v[4:5] op_sel_hi:[1,0,1]
	v_pk_fma_f32 v[2:3], v[140:141], v[244:245], v[2:3] op_sel_hi:[1,0,1] neg_lo:[1,0,0] neg_hi:[1,0,0]
	ds_read_b32 v228, v223 offset:132
	s_waitcnt lgkmcnt(5)
	s_waitcnt vmcnt(31)
	v_pk_mul_f32 v[236:237], v[172:173], v[246:247] op_sel_hi:[1,0]
	v_pk_fma_f32 v[2:3], v[172:173], v[246:247], v[2:3] op_sel_hi:[1,0,1]
	v_pk_mul_f32 v[238:239], v[174:175], v[246:247] op_sel_hi:[1,0]
	v_pk_fma_f32 v[4:5], v[174:175], v[246:247], v[4:5] op_sel_hi:[1,0,1]
	ds_read_b32 v230, v223 offset:164
	v_mov_b32_e32 v240, 0x3e000000
	v_pk_fma_f32 v[242:243], v[240:241], v[2:3], v[236:237] op_sel_hi:[0,1,1] neg_lo:[0,0,1] neg_hi:[0,0,1]
	v_pk_fma_f32 v[236:237], v[240:241], v[4:5], v[238:239] op_sel_hi:[0,1,1] neg_lo:[0,0,1] neg_hi:[0,0,1]
	v_cvt_pk_bf16_f32 v242, v242, v243
	v_cvt_pk_bf16_f32 v243, v236, v237
	global_store_dwordx2 v222, v[242:243], s[34:35]
	s_add_u32 s34, s34, 0x800
	s_addc_u32 s35, s35, 0
	s_waitcnt lgkmcnt(5)
	v_xor_b32_e32 v239, 0x80000000, v147
	v_xor_b32_e32 v238, 0x80000000, v146
	v_pk_fma_f32 v[4:5], v[238:239], v[248:249], v[4:5] op_sel_hi:[1,0,1]
	v_pk_fma_f32 v[2:3], v[144:145], v[248:249], v[2:3] op_sel_hi:[1,0,1] neg_lo:[1,0,0] neg_hi:[1,0,0]
	ds_read_b32 v244, v223 offset:136
	s_waitcnt lgkmcnt(5)
	s_waitcnt vmcnt(31)
	v_pk_mul_f32 v[236:237], v[176:177], v[232:233] op_sel_hi:[1,0]
	v_pk_fma_f32 v[2:3], v[176:177], v[232:233], v[2:3] op_sel_hi:[1,0,1]
	v_pk_mul_f32 v[238:239], v[178:179], v[232:233] op_sel_hi:[1,0]
	v_pk_fma_f32 v[4:5], v[178:179], v[232:233], v[4:5] op_sel_hi:[1,0,1]
	ds_read_b32 v246, v223 offset:168
	v_mov_b32_e32 v240, 0x3e000000
	v_pk_fma_f32 v[242:243], v[240:241], v[2:3], v[236:237] op_sel_hi:[0,1,1] neg_lo:[0,0,1] neg_hi:[0,0,1]
	v_pk_fma_f32 v[236:237], v[240:241], v[4:5], v[238:239] op_sel_hi:[0,1,1] neg_lo:[0,0,1] neg_hi:[0,0,1]
	v_cvt_pk_bf16_f32 v242, v242, v243
	v_cvt_pk_bf16_f32 v243, v236, v237
	global_store_dwordx2 v222, v[242:243], s[34:35]
	s_add_u32 s34, s34, 0x800
	s_addc_u32 s35, s35, 0
	s_waitcnt lgkmcnt(5)
	v_xor_b32_e32 v239, 0x80000000, v151
	v_xor_b32_e32 v238, 0x80000000, v150
	v_pk_fma_f32 v[4:5], v[238:239], v[224:225], v[4:5] op_sel_hi:[1,0,1]
	v_pk_fma_f32 v[2:3], v[148:149], v[224:225], v[2:3] op_sel_hi:[1,0,1] neg_lo:[1,0,0] neg_hi:[1,0,0]
	ds_read_b32 v248, v223 offset:140
	s_waitcnt lgkmcnt(5)
	s_waitcnt vmcnt(31)
	v_pk_mul_f32 v[236:237], v[180:181], v[226:227] op_sel_hi:[1,0]
	v_pk_fma_f32 v[2:3], v[180:181], v[226:227], v[2:3] op_sel_hi:[1,0,1]
	v_pk_mul_f32 v[238:239], v[182:183], v[226:227] op_sel_hi:[1,0]
	v_pk_fma_f32 v[4:5], v[182:183], v[226:227], v[4:5] op_sel_hi:[1,0,1]
	ds_read_b32 v232, v223 offset:172
	v_mov_b32_e32 v240, 0x3e000000
	v_pk_fma_f32 v[242:243], v[240:241], v[2:3], v[236:237] op_sel_hi:[0,1,1] neg_lo:[0,0,1] neg_hi:[0,0,1]
	v_pk_fma_f32 v[236:237], v[240:241], v[4:5], v[238:239] op_sel_hi:[0,1,1] neg_lo:[0,0,1] neg_hi:[0,0,1]
	v_cvt_pk_bf16_f32 v242, v242, v243
	v_cvt_pk_bf16_f32 v243, v236, v237
	global_store_dwordx2 v222, v[242:243], s[34:35]
	s_add_u32 s34, s34, 0x800
	s_addc_u32 s35, s35, 0
	s_waitcnt lgkmcnt(5)
	v_xor_b32_e32 v239, 0x80000000, v155
	v_xor_b32_e32 v238, 0x80000000, v154
	v_pk_fma_f32 v[4:5], v[238:239], v[228:229], v[4:5] op_sel_hi:[1,0,1]
	v_pk_fma_f32 v[2:3], v[152:153], v[228:229], v[2:3] op_sel_hi:[1,0,1] neg_lo:[1,0,0] neg_hi:[1,0,0]
	ds_read_b32 v224, v223 offset:144
	s_waitcnt lgkmcnt(5)
	s_waitcnt vmcnt(31)
	v_pk_mul_f32 v[236:237], v[184:185], v[230:231] op_sel_hi:[1,0]
	v_pk_fma_f32 v[2:3], v[184:185], v[230:231], v[2:3] op_sel_hi:[1,0,1]
	v_pk_mul_f32 v[238:239], v[186:187], v[230:231] op_sel_hi:[1,0]
	v_pk_fma_f32 v[4:5], v[186:187], v[230:231], v[4:5] op_sel_hi:[1,0,1]
	ds_read_b32 v226, v223 offset:176
	v_mov_b32_e32 v240, 0x3e000000
	v_pk_fma_f32 v[242:243], v[240:241], v[2:3], v[236:237] op_sel_hi:[0,1,1] neg_lo:[0,0,1] neg_hi:[0,0,1]
	v_pk_fma_f32 v[236:237], v[240:241], v[4:5], v[238:239] op_sel_hi:[0,1,1] neg_lo:[0,0,1] neg_hi:[0,0,1]
	v_cvt_pk_bf16_f32 v242, v242, v243
	v_cvt_pk_bf16_f32 v243, v236, v237
	global_store_dwordx2 v222, v[242:243], s[34:35]
	s_add_u32 s34, s34, 0x800
	s_addc_u32 s35, s35, 0
	s_waitcnt lgkmcnt(5)
	v_xor_b32_e32 v239, 0x80000000, v159
	v_xor_b32_e32 v238, 0x80000000, v158
	v_pk_fma_f32 v[4:5], v[238:239], v[244:245], v[4:5] op_sel_hi:[1,0,1]
	v_pk_fma_f32 v[2:3], v[156:157], v[244:245], v[2:3] op_sel_hi:[1,0,1] neg_lo:[1,0,0] neg_hi:[1,0,0]
	ds_read_b32 v228, v223 offset:148
	s_waitcnt lgkmcnt(5)
	s_waitcnt vmcnt(31)
	v_pk_mul_f32 v[236:237], v[188:189], v[246:247] op_sel_hi:[1,0]
	v_pk_fma_f32 v[2:3], v[188:189], v[246:247], v[2:3] op_sel_hi:[1,0,1]
	v_pk_mul_f32 v[238:239], v[190:191], v[246:247] op_sel_hi:[1,0]
	v_pk_fma_f32 v[4:5], v[190:191], v[246:247], v[4:5] op_sel_hi:[1,0,1]
	ds_read_b32 v230, v223 offset:180
	v_mov_b32_e32 v240, 0x3e000000
	v_pk_fma_f32 v[242:243], v[240:241], v[2:3], v[236:237] op_sel_hi:[0,1,1] neg_lo:[0,0,1] neg_hi:[0,0,1]
	v_pk_fma_f32 v[236:237], v[240:241], v[4:5], v[238:239] op_sel_hi:[0,1,1] neg_lo:[0,0,1] neg_hi:[0,0,1]
	v_cvt_pk_bf16_f32 v242, v242, v243
	v_cvt_pk_bf16_f32 v243, v236, v237
	global_store_dwordx2 v222, v[242:243], s[34:35]
	s_add_u32 s34, s34, 0x800
	s_addc_u32 s35, s35, 0
	s_waitcnt lgkmcnt(5)
	v_xor_b32_e32 v239, 0x80000000, v163
	v_xor_b32_e32 v238, 0x80000000, v162
	v_pk_fma_f32 v[4:5], v[238:239], v[248:249], v[4:5] op_sel_hi:[1,0,1]
	v_pk_fma_f32 v[2:3], v[160:161], v[248:249], v[2:3] op_sel_hi:[1,0,1] neg_lo:[1,0,0] neg_hi:[1,0,0]
	ds_read_b32 v244, v223 offset:152
	s_waitcnt lgkmcnt(5)
	s_waitcnt vmcnt(31)
	v_pk_mul_f32 v[236:237], v[192:193], v[232:233] op_sel_hi:[1,0]
	v_pk_fma_f32 v[2:3], v[192:193], v[232:233], v[2:3] op_sel_hi:[1,0,1]
	v_pk_mul_f32 v[238:239], v[194:195], v[232:233] op_sel_hi:[1,0]
	v_pk_fma_f32 v[4:5], v[194:195], v[232:233], v[4:5] op_sel_hi:[1,0,1]
	ds_read_b32 v246, v223 offset:184
	v_mov_b32_e32 v240, 0x3e000000
	v_pk_fma_f32 v[242:243], v[240:241], v[2:3], v[236:237] op_sel_hi:[0,1,1] neg_lo:[0,0,1] neg_hi:[0,0,1]
	v_pk_fma_f32 v[236:237], v[240:241], v[4:5], v[238:239] op_sel_hi:[0,1,1] neg_lo:[0,0,1] neg_hi:[0,0,1]
	v_cvt_pk_bf16_f32 v242, v242, v243
	v_cvt_pk_bf16_f32 v243, v236, v237
	global_store_dwordx2 v222, v[242:243], s[34:35]
	s_add_u32 s34, s34, 0x800
	s_addc_u32 s35, s35, 0
	s_waitcnt lgkmcnt(5)
	v_xor_b32_e32 v239, 0x80000000, v167
	v_xor_b32_e32 v238, 0x80000000, v166
	v_pk_fma_f32 v[4:5], v[238:239], v[224:225], v[4:5] op_sel_hi:[1,0,1]
	v_pk_fma_f32 v[2:3], v[164:165], v[224:225], v[2:3] op_sel_hi:[1,0,1] neg_lo:[1,0,0] neg_hi:[1,0,0]
	ds_read_b32 v248, v223 offset:156
	s_waitcnt lgkmcnt(5)
	s_waitcnt vmcnt(31)
	v_pk_mul_f32 v[236:237], v[196:197], v[226:227] op_sel_hi:[1,0]
	v_pk_fma_f32 v[2:3], v[196:197], v[226:227], v[2:3] op_sel_hi:[1,0,1]
	v_pk_mul_f32 v[238:239], v[198:199], v[226:227] op_sel_hi:[1,0]
	v_pk_fma_f32 v[4:5], v[198:199], v[226:227], v[4:5] op_sel_hi:[1,0,1]
	v_mov_b32_e32 v240, 0x3e000000
	v_pk_fma_f32 v[242:243], v[240:241], v[2:3], v[236:237] op_sel_hi:[0,1,1] neg_lo:[0,0,1] neg_hi:[0,0,1]
	v_pk_fma_f32 v[236:237], v[240:241], v[4:5], v[238:239] op_sel_hi:[0,1,1] neg_lo:[0,0,1] neg_hi:[0,0,1]
	v_cvt_pk_bf16_f32 v242, v242, v243
	v_cvt_pk_bf16_f32 v243, v236, v237
	global_store_dwordx2 v222, v[242:243], s[34:35]
	s_add_u32 s34, s34, 0x800
	s_addc_u32 s35, s35, 0
	s_waitcnt lgkmcnt(4)
	v_xor_b32_e32 v239, 0x80000000, v171
	v_xor_b32_e32 v238, 0x80000000, v170
	v_pk_fma_f32 v[4:5], v[238:239], v[228:229], v[4:5] op_sel_hi:[1,0,1]
	v_pk_fma_f32 v[2:3], v[168:169], v[228:229], v[2:3] op_sel_hi:[1,0,1] neg_lo:[1,0,0] neg_hi:[1,0,0]
	s_waitcnt lgkmcnt(3)
	s_waitcnt vmcnt(31)
	v_pk_mul_f32 v[236:237], v[200:201], v[230:231] op_sel_hi:[1,0]
	v_pk_fma_f32 v[2:3], v[200:201], v[230:231], v[2:3] op_sel_hi:[1,0,1]
	v_pk_mul_f32 v[238:239], v[202:203], v[230:231] op_sel_hi:[1,0]
	v_pk_fma_f32 v[4:5], v[202:203], v[230:231], v[4:5] op_sel_hi:[1,0,1]
	v_mov_b32_e32 v240, 0x3e000000
	v_pk_fma_f32 v[242:243], v[240:241], v[2:3], v[236:237] op_sel_hi:[0,1,1] neg_lo:[0,0,1] neg_hi:[0,0,1]
	v_pk_fma_f32 v[236:237], v[240:241], v[4:5], v[238:239] op_sel_hi:[0,1,1] neg_lo:[0,0,1] neg_hi:[0,0,1]
	v_cvt_pk_bf16_f32 v242, v242, v243
	v_cvt_pk_bf16_f32 v243, v236, v237
	global_store_dwordx2 v222, v[242:243], s[34:35]
	s_add_u32 s34, s34, 0x800
	s_addc_u32 s35, s35, 0
	s_waitcnt lgkmcnt(2)
	v_xor_b32_e32 v239, 0x80000000, v175
	v_xor_b32_e32 v238, 0x80000000, v174
	v_pk_fma_f32 v[4:5], v[238:239], v[244:245], v[4:5] op_sel_hi:[1,0,1]
	v_pk_fma_f32 v[2:3], v[172:173], v[244:245], v[2:3] op_sel_hi:[1,0,1] neg_lo:[1,0,0] neg_hi:[1,0,0]
	s_waitcnt lgkmcnt(1)
	s_waitcnt vmcnt(31)
	v_pk_mul_f32 v[236:237], v[216:217], v[246:247] op_sel_hi:[1,0]
	v_pk_fma_f32 v[2:3], v[216:217], v[246:247], v[2:3] op_sel_hi:[1,0,1]
	v_pk_mul_f32 v[238:239], v[218:219], v[246:247] op_sel_hi:[1,0]
	v_pk_fma_f32 v[4:5], v[218:219], v[246:247], v[4:5] op_sel_hi:[1,0,1]
	v_mov_b32_e32 v240, 0x3e000000
	v_pk_fma_f32 v[242:243], v[240:241], v[2:3], v[236:237] op_sel_hi:[0,1,1] neg_lo:[0,0,1] neg_hi:[0,0,1]
	v_pk_fma_f32 v[236:237], v[240:241], v[4:5], v[238:239] op_sel_hi:[0,1,1] neg_lo:[0,0,1] neg_hi:[0,0,1]
	v_cvt_pk_bf16_f32 v242, v242, v243
	v_cvt_pk_bf16_f32 v243, v236, v237
	global_store_dwordx2 v222, v[242:243], s[34:35]
	s_add_u32 s34, s34, 0x800
	s_addc_u32 s35, s35, 0
	s_waitcnt lgkmcnt(0)
	v_xor_b32_e32 v239, 0x80000000, v179
	v_xor_b32_e32 v238, 0x80000000, v178
	v_pk_fma_f32 v[4:5], v[238:239], v[248:249], v[4:5] op_sel_hi:[1,0,1]
	v_pk_fma_f32 v[2:3], v[176:177], v[248:249], v[2:3] op_sel_hi:[1,0,1] neg_lo:[1,0,0] neg_hi:[1,0,0]
	s_branch .Lpool_done
.Lpool_v3:
	ds_read_b32 v224, v223 offset:0
	ds_read_b32 v226, v223 offset:4
	ds_read_b32 v228, v223 offset:8
	ds_read_b32 v230, v223 offset:12
	ds_read_b32 v244, v223 offset:16
	ds_read_b32 v246, v223 offset:20
	v_mov_b32_e32 v2, 0
	v_mov_b32_e32 v3, 0
	v_mov_b32_e32 v4, 0
	v_mov_b32_e32 v5, 0
	s_cmp_eq_u32 s14, 0
	s_cbranch_scc1 .Lpool_v3_nopre
	s_waitcnt vmcnt(32)
	s_waitcnt lgkmcnt(5)
	v_pk_fma_f32 v[4:5], v[22:23], v[224:225], v[4:5] op_sel_hi:[1,0,1]
	v_pk_fma_f32 v[2:3], v[20:21], v[224:225], v[2:3] op_sel_hi:[1,0,1]
	ds_read_b32 v248, v223 offset:24
	s_waitcnt lgkmcnt(5)
	v_pk_fma_f32 v[4:5], v[26:27], v[226:227], v[4:5] op_sel_hi:[1,0,1]
	v_pk_fma_f32 v[2:3], v[24:25], v[226:227], v[2:3] op_sel_hi:[1,0,1]
	ds_read_b32 v232, v223 offset:28
	s_waitcnt lgkmcnt(5)
	v_pk_fma_f32 v[4:5], v[30:31], v[228:229], v[4:5] op_sel_hi:[1,0,1]
	v_pk_fma_f32 v[2:3], v[28:29], v[228:229], v[2:3] op_sel_hi:[1,0,1]
	ds_read_b32 v224, v223 offset:32
	s_waitcnt lgkmcnt(5)
	v_pk_fma_f32 v[4:5], v[34:35], v[230:231], v[4:5] op_sel_hi:[1,0,1]
	v_pk_fma_f32 v[2:3], v[32:33], v[230:231], v[2:3] op_sel_hi:[1,0,1]
	ds_read_b32 v226, v223 offset:36
	s_waitcnt lgkmcnt(5)
	v_pk_fma_f32 v[4:5], v[38:39], v[244:245], v[4:5] op_sel_hi:[1,0,1]
	v_pk_fma_f32 v[2:3], v[36:37], v[244:245], v[2:3] op_sel_hi:[1,0,1]
	ds_read_b32 v228, v223 offset:40
	s_waitcnt lgkmcnt(5)
	v_pk_fma_f32 v[4:5], v[42:43], v[246:247], v[4:5] op_sel_hi:[1,0,1]
	v_pk_fma_f32 v[2:3], v[40:41], v[246:247], v[2:3] op_sel_hi:[1,0,1]
	ds_read_b32 v230, v223 offset:44
	s_waitcnt lgkmcnt(5)
	v_pk_fma_f32 v[4:5], v[46:47], v[248:249], v[4:5] op_sel_hi:[1,0,1]
	v_pk_fma_f32 v[2:3], v[44:45], v[248:249], v[2:3] op_sel_hi:[1,0,1]
	ds_read_b32 v244, v223 offset:48
	s_waitcnt lgkmcnt(5)
	v_pk_fma_f32 v[4:5], v[50:51], v[232:233], v[4:5] op_sel_hi:[1,0,1]
	v_pk_fma_f32 v[2:3], v[48:49], v[232:233], v[2:3] op_sel_hi:[1,0,1]
	ds_read_b32 v246, v223 offset:52
	s_waitcnt lgkmcnt(5)
	v_pk_fma_f32 v[4:5], v[54:55], v[224:225], v[4:5] op_sel_hi:[1,0,1]
	v_pk_fma_f32 v[2:3], v[52:53], v[224:225], v[2:3] op_sel_hi:[1,0,1]
	ds_read_b32 v248, v223 offset:56
	s_waitcnt lgkmcnt(5)
	v_pk_fma_f32 v[4:5], v[58:59], v[226:227], v[4:5] op_sel_hi:[1,0,1]
	v_pk_fma_f32 v[2:3], v[56:57], v[226:227], v[2:3] op_sel_hi:[1,0,1]
	ds_read_b32 v232, v223 offset:60
	s_waitcnt lgkmcnt(5)
	v_pk_fma_f32 v[4:5], v[62:63], v[228:229], v[4:5] op_sel_hi:[1,0,1]
	v_pk_fma_f32 v[2:3], v[60:61], v[228:229], v[2:3] op_sel_hi:[1,0,1]
	ds_read_b32 v224, v223 offset:0
	s_waitcnt lgkmcnt(5)
	v_pk_fma_f32 v[4:5], v[66:67], v[230:231], v[4:5] op_sel_hi:[1,0,1]
	v_pk_fma_f32 v[2:3], v[64:65], v[230:231], v[2:3] op_sel_hi:[1,0,1]
	ds_read_b32 v226, v223 offset:64
	s_waitcnt lgkmcnt(5)
	v_pk_fma_f32 v[4:5], v[70:71], v[244:245], v[4:5] op_sel_hi:[1,0,1]
	v_pk_fma_f32 v[2:3], v[68:69], v[244:245], v[2:3] op_sel_hi:[1,0,1]
	ds_read_b32 v228, v223 offset:4
	s_waitcnt lgkmcnt(5)
	v_pk_fma_f32 v[4:5], v[74:75], v[246:247], v[4:5] op_sel_hi:[1,0,1]
	v_pk_fma_f32 v[2:3], v[72:73], v[246:247], v[2:3] op_sel_hi:[1,0,1]
	ds_read_b32 v230, v223 offset:68
	s_waitcnt lgkmcnt(5)
	v_pk_fma_f32 v[4:5], v[78:79], v[248:249], v[4:5] op_sel_hi:[1,0,1]
	v_pk_fma_f32 v[2:3], v[76:77], v[248:249], v[2:3] op_sel_hi:[1,0,1]
	ds_read_b32 v244, v223 offset:8
	s_branch .Lpool_v3_main
.Lpool_v3_nopre:
	ds_read_b32 v248, v223 offset:24
	ds_read_b32 v232, v223 offset:28
	ds_read_b32 v224, v223 offset:32
	ds_read_b32 v226, v223 offset:36
	ds_read_b32 v228, v223 offset:40
	ds_read_b32 v230, v223 offset:44
	ds_read_b32 v244, v223 offset:48
	ds_read_b32 v246, v223 offset:52
	ds_read_b32 v248, v223 offset:56
	ds_read_b32 v232, v223 offset:60
	ds_read_b32 v224, v223 offset:0
	ds_read_b32 v226, v223 offset:64
	ds_read_b32 v228, v223 offset:4
	ds_read_b32 v230, v223 offset:68
	ds_read_b32 v244, v223 offset:8
.Lpool_v3_main:
	s_waitcnt lgkmcnt(5)
	s_waitcnt vmcnt(31)
	v_pk_mul_f32 v[236:237], v[80:81], v[232:233] op_sel_hi:[1,0]
	v_pk_fma_f32 v[2:3], v[80:81], v[232:233], v[2:3] op_sel_hi:[1,0,1]
	v_pk_mul_f32 v[238:239], v[82:83], v[232:233] op_sel_hi:[1,0]
	v_pk_fma_f32 v[4:5], v[82:83], v[232:233], v[4:5] op_sel_hi:[1,0,1]
	ds_read_b32 v246, v223 offset:72
	s_mov_b32 s36, 0x3d800000
	s_cmp_eq_u32 s14, 0
	s_cselect_b32 s36, 0x3f800000, s36
	v_mov_b32_e32 v240, s36
	v_pk_fma_f32 v[242:243], v[240:241], v[2:3], v[236:237] op_sel_hi:[0,1,1] neg_lo:[0,0,1] neg_hi:[0,0,1]
	v_pk_fma_f32 v[236:237], v[240:241], v[4:5], v[238:239] op_sel_hi:[0,1,1] neg_lo:[0,0,1] neg_hi:[0,0,1]
	v_cvt_pk_bf16_f32 v242, v242, v243
	v_cvt_pk_bf16_f32 v243, v236, v237
	global_store_dwordx2 v222, v[242:243], s[34:35]
	s_add_u32 s34, s34, 0x800
	s_addc_u32 s35, s35, 0
	s_waitcnt lgkmcnt(5)
	s_cmp_eq_u32 s14, 0
	s_cbranch_scc1 .Lpool_v3_ns0
	v_xor_b32_e32 v239, 0x80000000, v23
	v_xor_b32_e32 v238, 0x80000000, v22
	v_pk_fma_f32 v[4:5], v[238:239], v[224:225], v[4:5] op_sel_hi:[1,0,1]
	v_pk_fma_f32 v[2:3], v[20:21], v[224:225], v[2:3] op_sel_hi:[1,0,1] neg_lo:[1,0,0] neg_hi:[1,0,0]
.Lpool_v3_ns0:
	ds_read_b32 v248, v223 offset:12
	s_waitcnt lgkmcnt(5)
	s_waitcnt vmcnt(31)
	v_pk_mul_f32 v[236:237], v[84:85], v[226:227] op_sel_hi:[1,0]
	v_pk_fma_f32 v[2:3], v[84:85], v[226:227], v[2:3] op_sel_hi:[1,0,1]
	v_pk_mul_f32 v[238:239], v[86:87], v[226:227] op_sel_hi:[1,0]
	v_pk_fma_f32 v[4:5], v[86:87], v[226:227], v[4:5] op_sel_hi:[1,0,1]
	ds_read_b32 v232, v223 offset:76
	s_mov_b32 s36, 0x3d800000
	s_cmp_eq_u32 s14, 0
	s_cselect_b32 s36, 0x3f000000, s36
	v_mov_b32_e32 v240, s36
	v_pk_fma_f32 v[242:243], v[240:241], v[2:3], v[236:237] op_sel_hi:[0,1,1] neg_lo:[0,0,1] neg_hi:[0,0,1]
	v_pk_fma_f32 v[236:237], v[240:241], v[4:5], v[238:239] op_sel_hi:[0,1,1] neg_lo:[0,0,1] neg_hi:[0,0,1]
	v_cvt_pk_bf16_f32 v242, v242, v243
	v_cvt_pk_bf16_f32 v243, v236, v237
	global_store_dwordx2 v222, v[242:243], s[34:35]
	s_add_u32 s34, s34, 0x800
	s_addc_u32 s35, s35, 0
	s_waitcnt lgkmcnt(5)
	s_cmp_eq_u32 s14, 0
	s_cbranch_scc1 .Lpool_v3_ns1
	v_xor_b32_e32 v239, 0x80000000, v27
	v_xor_b32_e32 v238, 0x80000000, v26
	v_pk_fma_f32 v[4:5], v[238:239], v[228:229], v[4:5] op_sel_hi:[1,0,1]
	v_pk_fma_f32 v[2:3], v[24:25], v[228:229], v[2:3] op_sel_hi:[1,0,1] neg_lo:[1,0,0] neg_hi:[1,0,0]
.Lpool_v3_ns1:
	ds_read_b32 v224, v223 offset:16
	s_waitcnt lgkmcnt(5)
	s_waitcnt vmcnt(31)
	v_pk_mul_f32 v[236:237], v[88:89], v[230:231] op_sel_hi:[1,0]
	v_pk_fma_f32 v[2:3], v[88:89], v[230:231], v[2:3] op_sel_hi:[1,0,1]
	v_pk_mul_f32 v[238:239], v[90:91], v[230:231] op_sel_hi:[1,0]
	v_pk_fma_f32 v[4:5], v[90:91], v[230:231], v[4:5] op_sel_hi:[1,0,1]
	ds_read_b32 v226, v223 offset:80
	s_mov_b32 s36, 0x3d800000
	s_cmp_eq_u32 s14, 0
	s_cselect_b32 s36, 0x3eaaaaab, s36
	v_mov_b32_e32 v240, s36
	v_pk_fma_f32 v[242:243], v[240:241], v[2:3], v[236:237] op_sel_hi:[0,1,1] neg_lo:[0,0,1] neg_hi:[0,0,1]
	v_pk_fma_f32 v[236:237], v[240:241], v[4:5], v[238:239] op_sel_hi:[0,1,1] neg_lo:[0,0,1] neg_hi:[0,0,1]
	v_cvt_pk_bf16_f32 v242, v242, v243
	v_cvt_pk_bf16_f32 v243, v236, v237
	global_store_dwordx2 v222, v[242:243], s[34:35]
	s_add_u32 s34, s34, 0x800
	s_addc_u32 s35, s35, 0
	s_waitcnt lgkmcnt(5)
	s_cmp_eq_u32 s14, 0
	s_cbranch_scc1 .Lpool_v3_ns2
	v_xor_b32_e32 v239, 0x80000000, v31
	v_xor_b32_e32 v238, 0x80000000, v30
	v_pk_fma_f32 v[4:5], v[238:239], v[244:245], v[4:5] op_sel_hi:[1,0,1]
	v_pk_fma_f32 v[2:3], v[28:29], v[244:245], v[2:3] op_sel_hi:[1,0,1] neg_lo:[1,0,0] neg_hi:[1,0,0]
.Lpool_v3_ns2:
	ds_read_b32 v228, v223 offset:20
	s_waitcnt lgkmcnt(5)
	s_waitcnt vmcnt(31)
	v_pk_mul_f32 v[236:237], v[92:93], v[246:247] op_sel_hi:[1,0]
	v_pk_fma_f32 v[2:3], v[92:93], v[246:247], v[2:3] op_sel_hi:[1,0,1]
	v_pk_mul_f32 v[238:239], v[94:95], v[246:247] op_sel_hi:[1,0]
	v_pk_fma_f32 v[4:5], v[94:95], v[246:247], v[4:5] op_sel_hi:[1,0,1]
	ds_read_b32 v230, v223 offset:84
	s_mov_b32 s36, 0x3d800000
	s_cmp_eq_u32 s14, 0
	s_cselect_b32 s36, 0x3e800000, s36
	v_mov_b32_e32 v240, s36
	v_pk_fma_f32 v[242:243], v[240:241], v[2:3], v[236:237] op_sel_hi:[0,1,1] neg_lo:[0,0,1] neg_hi:[0,0,1]
	v_pk_fma_f32 v[236:237], v[240:241], v[4:5], v[238:239] op_sel_hi:[0,1,1] neg_lo:[0,0,1] neg_hi:[0,0,1]
	v_cvt_pk_bf16_f32 v242, v242, v243
	v_cvt_pk_bf16_f32 v243, v236, v237
	global_store_dwordx2 v222, v[242:243], s[34:35]
	s_add_u32 s34, s34, 0x800
	s_addc_u32 s35, s35, 0
	s_waitcnt lgkmcnt(5)
	s_cmp_eq_u32 s14, 0
	s_cbranch_scc1 .Lpool_v3_ns3
	v_xor_b32_e32 v239, 0x80000000, v35
	v_xor_b32_e32 v238, 0x80000000, v34
	v_pk_fma_f32 v[4:5], v[238:239], v[248:249], v[4:5] op_sel_hi:[1,0,1]
	v_pk_fma_f32 v[2:3], v[32:33], v[248:249], v[2:3] op_sel_hi:[1,0,1] neg_lo:[1,0,0] neg_hi:[1,0,0]
.Lpool_v3_ns3:
	ds_read_b32 v244, v223 offset:24
	s_waitcnt lgkmcnt(5)
	s_waitcnt vmcnt(31)
	v_pk_mul_f32 v[236:237], v[96:97], v[232:233] op_sel_hi:[1,0]
	v_pk_fma_f32 v[2:3], v[96:97], v[232:233], v[2:3] op_sel_hi:[1,0,1]
	v_pk_mul_f32 v[238:239], v[98:99], v[232:233] op_sel_hi:[1,0]
	v_pk_fma_f32 v[4:5], v[98:99], v[232:233], v[4:5] op_sel_hi:[1,0,1]
	ds_read_b32 v246, v223 offset:88
	s_mov_b32 s36, 0x3d800000
	s_cmp_eq_u32 s14, 0
	s_cselect_b32 s36, 0x3e4ccccd, s36
	v_mov_b32_e32 v240, s36
	v_pk_fma_f32 v[242:243], v[240:241], v[2:3], v[236:237] op_sel_hi:[0,1,1] neg_lo:[0,0,1] neg_hi:[0,0,1]
	v_pk_fma_f32 v[236:237], v[240:241], v[4:5], v[238:239] op_sel_hi:[0,1,1] neg_lo:[0,0,1] neg_hi:[0,0,1]
	v_cvt_pk_bf16_f32 v242, v242, v243
	v_cvt_pk_bf16_f32 v243, v236, v237
	global_store_dwordx2 v222, v[242:243], s[34:35]
	s_add_u32 s34, s34, 0x800
	s_addc_u32 s35, s35, 0
	s_waitcnt lgkmcnt(5)
	s_cmp_eq_u32 s14, 0
	s_cbranch_scc1 .Lpool_v3_ns4
	v_xor_b32_e32 v239, 0x80000000, v39
	v_xor_b32_e32 v238, 0x80000000, v38
	v_pk_fma_f32 v[4:5], v[238:239], v[224:225], v[4:5] op_sel_hi:[1,0,1]
	v_pk_fma_f32 v[2:3], v[36:37], v[224:225], v[2:3] op_sel_hi:[1,0,1] neg_lo:[1,0,0] neg_hi:[1,0,0]
.Lpool_v3_ns4:
	ds_read_b32 v248, v223 offset:28
	s_waitcnt lgkmcnt(5)
	s_waitcnt vmcnt(31)
	v_pk_mul_f32 v[236:237], v[100:101], v[226:227] op_sel_hi:[1,0]
	v_pk_fma_f32 v[2:3], v[100:101], v[226:227], v[2:3] op_sel_hi:[1,0,1]
	v_pk_mul_f32 v[238:239], v[102:103], v[226:227] op_sel_hi:[1,0]
	v_pk_fma_f32 v[4:5], v[102:103], v[226:227], v[4:5] op_sel_hi:[1,0,1]
	ds_read_b32 v232, v223 offset:92
	s_mov_b32 s36, 0x3d800000
	s_cmp_eq_u32 s14, 0
	s_cselect_b32 s36, 0x3e2aaaab, s36
	v_mov_b32_e32 v240, s36
	v_pk_fma_f32 v[242:243], v[240:241], v[2:3], v[236:237] op_sel_hi:[0,1,1] neg_lo:[0,0,1] neg_hi:[0,0,1]
	v_pk_fma_f32 v[236:237], v[240:241], v[4:5], v[238:239] op_sel_hi:[0,1,1] neg_lo:[0,0,1] neg_hi:[0,0,1]
	v_cvt_pk_bf16_f32 v242, v242, v243
	v_cvt_pk_bf16_f32 v243, v236, v237
	global_store_dwordx2 v222, v[242:243], s[34:35]
	s_add_u32 s34, s34, 0x800
	s_addc_u32 s35, s35, 0
	s_waitcnt lgkmcnt(5)
	s_cmp_eq_u32 s14, 0
	s_cbranch_scc1 .Lpool_v3_ns5
	v_xor_b32_e32 v239, 0x80000000, v43
	v_xor_b32_e32 v238, 0x80000000, v42
	v_pk_fma_f32 v[4:5], v[238:239], v[228:229], v[4:5] op_sel_hi:[1,0,1]
	v_pk_fma_f32 v[2:3], v[40:41], v[228:229], v[2:3] op_sel_hi:[1,0,1] neg_lo:[1,0,0] neg_hi:[1,0,0]
.Lpool_v3_ns5:
	ds_read_b32 v224, v223 offset:32
	s_waitcnt lgkmcnt(5)
	s_waitcnt vmcnt(31)
	v_pk_mul_f32 v[236:237], v[104:105], v[230:231] op_sel_hi:[1,0]
	v_pk_fma_f32 v[2:3], v[104:105], v[230:231], v[2:3] op_sel_hi:[1,0,1]
	v_pk_mul_f32 v[238:239], v[106:107], v[230:231] op_sel_hi:[1,0]
	v_pk_fma_f32 v[4:5], v[106:107], v[230:231], v[4:5] op_sel_hi:[1,0,1]
	ds_read_b32 v226, v223 offset:96
	s_mov_b32 s36, 0x3d800000
	s_cmp_eq_u32 s14, 0
	s_cselect_b32 s36, 0x3e124925, s36
	v_mov_b32_e32 v240, s36
	v_pk_fma_f32 v[242:243], v[240:241], v[2:3], v[236:237] op_sel_hi:[0,1,1] neg_lo:[0,0,1] neg_hi:[0,0,1]
	v_pk_fma_f32 v[236:237], v[240:241], v[4:5], v[238:239] op_sel_hi:[0,1,1] neg_lo:[0,0,1] neg_hi:[0,0,1]
	v_cvt_pk_bf16_f32 v242, v242, v243
	v_cvt_pk_bf16_f32 v243, v236, v237
	global_store_dwordx2 v222, v[242:243], s[34:35]
	s_add_u32 s34, s34, 0x800
	s_addc_u32 s35, s35, 0
	s_waitcnt lgkmcnt(5)
	s_cmp_eq_u32 s14, 0
	s_cbranch_scc1 .Lpool_v3_ns6
	v_xor_b32_e32 v239, 0x80000000, v47
	v_xor_b32_e32 v238, 0x80000000, v46
	v_pk_fma_f32 v[4:5], v[238:239], v[244:245], v[4:5] op_sel_hi:[1,0,1]
	v_pk_fma_f32 v[2:3], v[44:45], v[244:245], v[2:3] op_sel_hi:[1,0,1] neg_lo:[1,0,0] neg_hi:[1,0,0]
.Lpool_v3_ns6:
	ds_read_b32 v228, v223 offset:36
	s_waitcnt lgkmcnt(5)
	s_waitcnt vmcnt(31)
	v_pk_mul_f32 v[236:237], v[108:109], v[246:247] op_sel_hi:[1,0]
	v_pk_fma_f32 v[2:3], v[108:109], v[246:247], v[2:3] op_sel_hi:[1,0,1]
	v_pk_mul_f32 v[238:239], v[110:111], v[246:247] op_sel_hi:[1,0]
	v_pk_fma_f32 v[4:5], v[110:111], v[246:247], v[4:5] op_sel_hi:[1,0,1]
	ds_read_b32 v230, v223 offset:100
	s_mov_b32 s36, 0x3d800000
	s_cmp_eq_u32 s14, 0
	s_cselect_b32 s36, 0x3e000000, s36
	v_mov_b32_e32 v240, s36
	v_pk_fma_f32 v[242:243], v[240:241], v[2:3], v[236:237] op_sel_hi:[0,1,1] neg_lo:[0,0,1] neg_hi:[0,0,1]
	v_pk_fma_f32 v[236:237], v[240:241], v[4:5], v[238:239] op_sel_hi:[0,1,1] neg_lo:[0,0,1] neg_hi:[0,0,1]
	v_cvt_pk_bf16_f32 v242, v242, v243
	v_cvt_pk_bf16_f32 v243, v236, v237
	global_store_dwordx2 v222, v[242:243], s[34:35]
	s_add_u32 s34, s34, 0x800
	s_addc_u32 s35, s35, 0
	s_waitcnt lgkmcnt(5)
	s_cmp_eq_u32 s14, 0
	s_cbranch_scc1 .Lpool_v3_ns7
	v_xor_b32_e32 v239, 0x80000000, v51
	v_xor_b32_e32 v238, 0x80000000, v50
	v_pk_fma_f32 v[4:5], v[238:239], v[248:249], v[4:5] op_sel_hi:[1,0,1]
	v_pk_fma_f32 v[2:3], v[48:49], v[248:249], v[2:3] op_sel_hi:[1,0,1] neg_lo:[1,0,0] neg_hi:[1,0,0]
.Lpool_v3_ns7:
	ds_read_b32 v244, v223 offset:40
	s_waitcnt lgkmcnt(5)
	s_waitcnt vmcnt(31)
	v_pk_mul_f32 v[236:237], v[112:113], v[232:233] op_sel_hi:[1,0]
	v_pk_fma_f32 v[2:3], v[112:113], v[232:233], v[2:3] op_sel_hi:[1,0,1]
	v_pk_mul_f32 v[238:239], v[114:115], v[232:233] op_sel_hi:[1,0]
	v_pk_fma_f32 v[4:5], v[114:115], v[232:233], v[4:5] op_sel_hi:[1,0,1]
	ds_read_b32 v246, v223 offset:104
	s_mov_b32 s36, 0x3d800000
	s_cmp_eq_u32 s14, 0
	s_cselect_b32 s36, 0x3de38e39, s36
	v_mov_b32_e32 v240, s36
	v_pk_fma_f32 v[242:243], v[240:241], v[2:3], v[236:237] op_sel_hi:[0,1,1] neg_lo:[0,0,1] neg_hi:[0,0,1]
	v_pk_fma_f32 v[236:237], v[240:241], v[4:5], v[238:239] op_sel_hi:[0,1,1] neg_lo:[0,0,1] neg_hi:[0,0,1]
	v_cvt_pk_bf16_f32 v242, v242, v243
	v_cvt_pk_bf16_f32 v243, v236, v237
	global_store_dwordx2 v222, v[242:243], s[34:35]
	s_add_u32 s34, s34, 0x800
	s_addc_u32 s35, s35, 0
	s_waitcnt lgkmcnt(5)
	s_cmp_eq_u32 s14, 0
	s_cbranch_scc1 .Lpool_v3_ns8
	v_xor_b32_e32 v239, 0x80000000, v55
	v_xor_b32_e32 v238, 0x80000000, v54
	v_pk_fma_f32 v[4:5], v[238:239], v[224:225], v[4:5] op_sel_hi:[1,0,1]
	v_pk_fma_f32 v[2:3], v[52:53], v[224:225], v[2:3] op_sel_hi:[1,0,1] neg_lo:[1,0,0] neg_hi:[1,0,0]
.Lpool_v3_ns8:
	ds_read_b32 v248, v223 offset:44
	s_waitcnt lgkmcnt(5)
	s_waitcnt vmcnt(31)
	v_pk_mul_f32 v[236:237], v[116:117], v[226:227] op_sel_hi:[1,0]
	v_pk_fma_f32 v[2:3], v[116:117], v[226:227], v[2:3] op_sel_hi:[1,0,1]
	v_pk_mul_f32 v[238:239], v[118:119], v[226:227] op_sel_hi:[1,0]
	v_pk_fma_f32 v[4:5], v[118:119], v[226:227], v[4:5] op_sel_hi:[1,0,1]
	ds_read_b32 v232, v223 offset:108
	s_mov_b32 s36, 0x3d800000
	s_cmp_eq_u32 s14, 0
	s_cselect_b32 s36, 0x3dcccccd, s36
	v_mov_b32_e32 v240, s36
	v_pk_fma_f32 v[242:243], v[240:241], v[2:3], v[236:237] op_sel_hi:[0,1,1] neg_lo:[0,0,1] neg_hi:[0,0,1]
	v_pk_fma_f32 v[236:237], v[240:241], v[4:5], v[238:239] op_sel_hi:[0,1,1] neg_lo:[0,0,1] neg_hi:[0,0,1]
	v_cvt_pk_bf16_f32 v242, v242, v243
	v_cvt_pk_bf16_f32 v243, v236, v237
	global_store_dwordx2 v222, v[242:243], s[34:35]
	s_add_u32 s34, s34, 0x800
	s_addc_u32 s35, s35, 0
	s_waitcnt lgkmcnt(5)
	s_cmp_eq_u32 s14, 0
	s_cbranch_scc1 .Lpool_v3_ns9
	v_xor_b32_e32 v239, 0x80000000, v59
	v_xor_b32_e32 v238, 0x80000000, v58
	v_pk_fma_f32 v[4:5], v[238:239], v[228:229], v[4:5] op_sel_hi:[1,0,1]
	v_pk_fma_f32 v[2:3], v[56:57], v[228:229], v[2:3] op_sel_hi:[1,0,1] neg_lo:[1,0,0] neg_hi:[1,0,0]
.Lpool_v3_ns9:
	ds_read_b32 v224, v223 offset:48
	s_waitcnt lgkmcnt(5)
	s_waitcnt vmcnt(31)
	v_pk_mul_f32 v[236:237], v[120:121], v[230:231] op_sel_hi:[1,0]
	v_pk_fma_f32 v[2:3], v[120:121], v[230:231], v[2:3] op_sel_hi:[1,0,1]
	v_pk_mul_f32 v[238:239], v[122:123], v[230:231] op_sel_hi:[1,0]
	v_pk_fma_f32 v[4:5], v[122:123], v[230:231], v[4:5] op_sel_hi:[1,0,1]
	ds_read_b32 v226, v223 offset:112
	s_mov_b32 s36, 0x3d800000
	s_cmp_eq_u32 s14, 0
	s_cselect_b32 s36, 0x3dba2e8c, s36
	v_mov_b32_e32 v240, s36
	v_pk_fma_f32 v[242:243], v[240:241], v[2:3], v[236:237] op_sel_hi:[0,1,1] neg_lo:[0,0,1] neg_hi:[0,0,1]
	v_pk_fma_f32 v[236:237], v[240:241], v[4:5], v[238:239] op_sel_hi:[0,1,1] neg_lo:[0,0,1] neg_hi:[0,0,1]
	v_cvt_pk_bf16_f32 v242, v242, v243
	v_cvt_pk_bf16_f32 v243, v236, v237
	global_store_dwordx2 v222, v[242:243], s[34:35]
	s_add_u32 s34, s34, 0x800
	s_addc_u32 s35, s35, 0
	s_waitcnt lgkmcnt(5)
	s_cmp_eq_u32 s14, 0
	s_cbranch_scc1 .Lpool_v3_ns10
	v_xor_b32_e32 v239, 0x80000000, v63
	v_xor_b32_e32 v238, 0x80000000, v62
	v_pk_fma_f32 v[4:5], v[238:239], v[244:245], v[4:5] op_sel_hi:[1,0,1]
	v_pk_fma_f32 v[2:3], v[60:61], v[244:245], v[2:3] op_sel_hi:[1,0,1] neg_lo:[1,0,0] neg_hi:[1,0,0]
.Lpool_v3_ns10:
	ds_read_b32 v228, v223 offset:52
	s_waitcnt lgkmcnt(5)
	s_waitcnt vmcnt(31)
	v_pk_mul_f32 v[236:237], v[124:125], v[246:247] op_sel_hi:[1,0]
	v_pk_fma_f32 v[2:3], v[124:125], v[246:247], v[2:3] op_sel_hi:[1,0,1]
	v_pk_mul_f32 v[238:239], v[126:127], v[246:247] op_sel_hi:[1,0]
	v_pk_fma_f32 v[4:5], v[126:127], v[246:247], v[4:5] op_sel_hi:[1,0,1]
	ds_read_b32 v230, v223 offset:116
	s_mov_b32 s36, 0x3d800000
	s_cmp_eq_u32 s14, 0
	s_cselect_b32 s36, 0x3daaaaab, s36
	v_mov_b32_e32 v240, s36
	v_pk_fma_f32 v[242:243], v[240:241], v[2:3], v[236:237] op_sel_hi:[0,1,1] neg_lo:[0,0,1] neg_hi:[0,0,1]
	v_pk_fma_f32 v[236:237], v[240:241], v[4:5], v[238:239] op_sel_hi:[0,1,1] neg_lo:[0,0,1] neg_hi:[0,0,1]
	v_cvt_pk_bf16_f32 v242, v242, v243
	v_cvt_pk_bf16_f32 v243, v236, v237
	global_store_dwordx2 v222, v[242:243], s[34:35]
	s_add_u32 s34, s34, 0x800
	s_addc_u32 s35, s35, 0
	s_waitcnt lgkmcnt(5)
	s_cmp_eq_u32 s14, 0
	s_cbranch_scc1 .Lpool_v3_ns11
	v_xor_b32_e32 v239, 0x80000000, v67
	v_xor_b32_e32 v238, 0x80000000, v66
	v_pk_fma_f32 v[4:5], v[238:239], v[248:249], v[4:5] op_sel_hi:[1,0,1]
	v_pk_fma_f32 v[2:3], v[64:65], v[248:249], v[2:3] op_sel_hi:[1,0,1] neg_lo:[1,0,0] neg_hi:[1,0,0]
.Lpool_v3_ns11:
	ds_read_b32 v244, v223 offset:56
	s_waitcnt lgkmcnt(5)
	s_waitcnt vmcnt(31)
	v_pk_mul_f32 v[236:237], v[128:129], v[232:233] op_sel_hi:[1,0]
	v_pk_fma_f32 v[2:3], v[128:129], v[232:233], v[2:3] op_sel_hi:[1,0,1]
	v_pk_mul_f32 v[238:239], v[130:131], v[232:233] op_sel_hi:[1,0]
	v_pk_fma_f32 v[4:5], v[130:131], v[232:233], v[4:5] op_sel_hi:[1,0,1]
	ds_read_b32 v246, v223 offset:120
	s_mov_b32 s36, 0x3d800000
	s_cmp_eq_u32 s14, 0
	s_cselect_b32 s36, 0x3d9d89d9, s36
	v_mov_b32_e32 v240, s36
	v_pk_fma_f32 v[242:243], v[240:241], v[2:3], v[236:237] op_sel_hi:[0,1,1] neg_lo:[0,0,1] neg_hi:[0,0,1]
	v_pk_fma_f32 v[236:237], v[240:241], v[4:5], v[238:239] op_sel_hi:[0,1,1] neg_lo:[0,0,1] neg_hi:[0,0,1]
	v_cvt_pk_bf16_f32 v242, v242, v243
	v_cvt_pk_bf16_f32 v243, v236, v237
	global_store_dwordx2 v222, v[242:243], s[34:35]
	s_add_u32 s34, s34, 0x800
	s_addc_u32 s35, s35, 0
	s_waitcnt lgkmcnt(5)
	s_cmp_eq_u32 s14, 0
	s_cbranch_scc1 .Lpool_v3_ns12
	v_xor_b32_e32 v239, 0x80000000, v71
	v_xor_b32_e32 v238, 0x80000000, v70
	v_pk_fma_f32 v[4:5], v[238:239], v[224:225], v[4:5] op_sel_hi:[1,0,1]
	v_pk_fma_f32 v[2:3], v[68:69], v[224:225], v[2:3] op_sel_hi:[1,0,1] neg_lo:[1,0,0] neg_hi:[1,0,0]
.Lpool_v3_ns12:
	ds_read_b32 v248, v223 offset:60
	s_waitcnt lgkmcnt(5)
	s_waitcnt vmcnt(31)
	v_pk_mul_f32 v[236:237], v[132:133], v[226:227] op_sel_hi:[1,0]
	v_pk_fma_f32 v[2:3], v[132:133], v[226:227], v[2:3] op_sel_hi:[1,0,1]
	v_pk_mul_f32 v[238:239], v[134:135], v[226:227] op_sel_hi:[1,0]
	v_pk_fma_f32 v[4:5], v[134:135], v[226:227], v[4:5] op_sel_hi:[1,0,1]
	ds_read_b32 v232, v223 offset:124
	s_mov_b32 s36, 0x3d800000
	s_cmp_eq_u32 s14, 0
	s_cselect_b32 s36, 0x3d924925, s36
	v_mov_b32_e32 v240, s36
	v_pk_fma_f32 v[242:243], v[240:241], v[2:3], v[236:237] op_sel_hi:[0,1,1] neg_lo:[0,0,1] neg_hi:[0,0,1]
	v_pk_fma_f32 v[236:237], v[240:241], v[4:5], v[238:239] op_sel_hi:[0,1,1] neg_lo:[0,0,1] neg_hi:[0,0,1]
	v_cvt_pk_bf16_f32 v242, v242, v243
	v_cvt_pk_bf16_f32 v243, v236, v237
	global_store_dwordx2 v222, v[242:243], s[34:35]
	s_add_u32 s34, s34, 0x800
	s_addc_u32 s35, s35, 0
	s_waitcnt lgkmcnt(5)
	s_cmp_eq_u32 s14, 0
	s_cbranch_scc1 .Lpool_v3_ns13
	v_xor_b32_e32 v239, 0x80000000, v75
	v_xor_b32_e32 v238, 0x80000000, v74
	v_pk_fma_f32 v[4:5], v[238:239], v[228:229], v[4:5] op_sel_hi:[1,0,1]
	v_pk_fma_f32 v[2:3], v[72:73], v[228:229], v[2:3] op_sel_hi:[1,0,1] neg_lo:[1,0,0] neg_hi:[1,0,0]
.Lpool_v3_ns13:
	ds_read_b32 v224, v223 offset:64
	s_waitcnt lgkmcnt(5)
	s_waitcnt vmcnt(31)
	v_pk_mul_f32 v[236:237], v[136:137], v[230:231] op_sel_hi:[1,0]
	v_pk_fma_f32 v[2:3], v[136:137], v[230:231], v[2:3] op_sel_hi:[1,0,1]
	v_pk_mul_f32 v[238:239], v[138:139], v[230:231] op_sel_hi:[1,0]
	v_pk_fma_f32 v[4:5], v[138:139], v[230:231], v[4:5] op_sel_hi:[1,0,1]
	ds_read_b32 v226, v223 offset:128
	s_mov_b32 s36, 0x3d800000
	s_cmp_eq_u32 s14, 0
	s_cselect_b32 s36, 0x3d888889, s36
	v_mov_b32_e32 v240, s36
	v_pk_fma_f32 v[242:243], v[240:241], v[2:3], v[236:237] op_sel_hi:[0,1,1] neg_lo:[0,0,1] neg_hi:[0,0,1]
	v_pk_fma_f32 v[236:237], v[240:241], v[4:5], v[238:239] op_sel_hi:[0,1,1] neg_lo:[0,0,1] neg_hi:[0,0,1]
	v_cvt_pk_bf16_f32 v242, v242, v243
	v_cvt_pk_bf16_f32 v243, v236, v237
	global_store_dwordx2 v222, v[242:243], s[34:35]
	s_add_u32 s34, s34, 0x800
	s_addc_u32 s35, s35, 0
	s_waitcnt lgkmcnt(5)
	s_cmp_eq_u32 s14, 0
	s_cbranch_scc1 .Lpool_v3_ns14
	v_xor_b32_e32 v239, 0x80000000, v79
	v_xor_b32_e32 v238, 0x80000000, v78
	v_pk_fma_f32 v[4:5], v[238:239], v[244:245], v[4:5] op_sel_hi:[1,0,1]
	v_pk_fma_f32 v[2:3], v[76:77], v[244:245], v[2:3] op_sel_hi:[1,0,1] neg_lo:[1,0,0] neg_hi:[1,0,0]
.Lpool_v3_ns14:
	ds_read_b32 v228, v223 offset:68
	s_waitcnt lgkmcnt(5)
	s_waitcnt vmcnt(31)
	v_pk_mul_f32 v[236:237], v[140:141], v[246:247] op_sel_hi:[1,0]
	v_pk_fma_f32 v[2:3], v[140:141], v[246:247], v[2:3] op_sel_hi:[1,0,1]
	v_pk_mul_f32 v[238:239], v[142:143], v[246:247] op_sel_hi:[1,0]
	v_pk_fma_f32 v[4:5], v[142:143], v[246:247], v[4:5] op_sel_hi:[1,0,1]
	ds_read_b32 v230, v223 offset:132
	v_mov_b32_e32 v240, 0x3d800000
	v_pk_fma_f32 v[242:243], v[240:241], v[2:3], v[236:237] op_sel_hi:[0,1,1] neg_lo:[0,0,1] neg_hi:[0,0,1]
	v_pk_fma_f32 v[236:237], v[240:241], v[4:5], v[238:239] op_sel_hi:[0,1,1] neg_lo:[0,0,1] neg_hi:[0,0,1]
	v_cvt_pk_bf16_f32 v242, v242, v243
	v_cvt_pk_bf16_f32 v243, v236, v237
	global_store_dwordx2 v222, v[242:243], s[34:35]
	s_add_u32 s34, s34, 0x800
	s_addc_u32 s35, s35, 0
	s_waitcnt lgkmcnt(5)
	v_xor_b32_e32 v239, 0x80000000, v83
	v_xor_b32_e32 v238, 0x80000000, v82
	v_pk_fma_f32 v[4:5], v[238:239], v[248:249], v[4:5] op_sel_hi:[1,0,1]
	v_pk_fma_f32 v[2:3], v[80:81], v[248:249], v[2:3] op_sel_hi:[1,0,1] neg_lo:[1,0,0] neg_hi:[1,0,0]
	ds_read_b32 v244, v223 offset:72
	s_waitcnt lgkmcnt(5)
	s_waitcnt vmcnt(31)
	v_pk_mul_f32 v[236:237], v[144:145], v[232:233] op_sel_hi:[1,0]
	v_pk_fma_f32 v[2:3], v[144:145], v[232:233], v[2:3] op_sel_hi:[1,0,1]
	v_pk_mul_f32 v[238:239], v[146:147], v[232:233] op_sel_hi:[1,0]
	v_pk_fma_f32 v[4:5], v[146:147], v[232:233], v[4:5] op_sel_hi:[1,0,1]
	ds_read_b32 v246, v223 offset:136
	v_mov_b32_e32 v240, 0x3d800000
	v_pk_fma_f32 v[242:243], v[240:241], v[2:3], v[236:237] op_sel_hi:[0,1,1] neg_lo:[0,0,1] neg_hi:[0,0,1]
	v_pk_fma_f32 v[236:237], v[240:241], v[4:5], v[238:239] op_sel_hi:[0,1,1] neg_lo:[0,0,1] neg_hi:[0,0,1]
	v_cvt_pk_bf16_f32 v242, v242, v243
	v_cvt_pk_bf16_f32 v243, v236, v237
	global_store_dwordx2 v222, v[242:243], s[34:35]
	s_add_u32 s34, s34, 0x800
	s_addc_u32 s35, s35, 0
	s_waitcnt lgkmcnt(5)
	v_xor_b32_e32 v239, 0x80000000, v87
	v_xor_b32_e32 v238, 0x80000000, v86
	v_pk_fma_f32 v[4:5], v[238:239], v[224:225], v[4:5] op_sel_hi:[1,0,1]
	v_pk_fma_f32 v[2:3], v[84:85], v[224:225], v[2:3] op_sel_hi:[1,0,1] neg_lo:[1,0,0] neg_hi:[1,0,0]
	ds_read_b32 v248, v223 offset:76
	s_waitcnt lgkmcnt(5)
	s_waitcnt vmcnt(31)
	v_pk_mul_f32 v[236:237], v[148:149], v[226:227] op_sel_hi:[1,0]
	v_pk_fma_f32 v[2:3], v[148:149], v[226:227], v[2:3] op_sel_hi:[1,0,1]
	v_pk_mul_f32 v[238:239], v[150:151], v[226:227] op_sel_hi:[1,0]
	v_pk_fma_f32 v[4:5], v[150:151], v[226:227], v[4:5] op_sel_hi:[1,0,1]
	ds_read_b32 v232, v223 offset:140
	v_mov_b32_e32 v240, 0x3d800000
	v_pk_fma_f32 v[242:243], v[240:241], v[2:3], v[236:237] op_sel_hi:[0,1,1] neg_lo:[0,0,1] neg_hi:[0,0,1]
	v_pk_fma_f32 v[236:237], v[240:241], v[4:5], v[238:239] op_sel_hi:[0,1,1] neg_lo:[0,0,1] neg_hi:[0,0,1]
	v_cvt_pk_bf16_f32 v242, v242, v243
	v_cvt_pk_bf16_f32 v243, v236, v237
	global_store_dwordx2 v222, v[242:243], s[34:35]
	s_add_u32 s34, s34, 0x800
	s_addc_u32 s35, s35, 0
	s_waitcnt lgkmcnt(5)
	v_xor_b32_e32 v239, 0x80000000, v91
	v_xor_b32_e32 v238, 0x80000000, v90
	v_pk_fma_f32 v[4:5], v[238:239], v[228:229], v[4:5] op_sel_hi:[1,0,1]
	v_pk_fma_f32 v[2:3], v[88:89], v[228:229], v[2:3] op_sel_hi:[1,0,1] neg_lo:[1,0,0] neg_hi:[1,0,0]
	ds_read_b32 v224, v223 offset:80
	s_waitcnt lgkmcnt(5)
	s_waitcnt vmcnt(31)
	v_pk_mul_f32 v[236:237], v[152:153], v[230:231] op_sel_hi:[1,0]
	v_pk_fma_f32 v[2:3], v[152:153], v[230:231], v[2:3] op_sel_hi:[1,0,1]
	v_pk_mul_f32 v[238:239], v[154:155], v[230:231] op_sel_hi:[1,0]
	v_pk_fma_f32 v[4:5], v[154:155], v[230:231], v[4:5] op_sel_hi:[1,0,1]
	ds_read_b32 v226, v223 offset:144
	v_mov_b32_e32 v240, 0x3d800000
	v_pk_fma_f32 v[242:243], v[240:241], v[2:3], v[236:237] op_sel_hi:[0,1,1] neg_lo:[0,0,1] neg_hi:[0,0,1]
	v_pk_fma_f32 v[236:237], v[240:241], v[4:5], v[238:239] op_sel_hi:[0,1,1] neg_lo:[0,0,1] neg_hi:[0,0,1]
	v_cvt_pk_bf16_f32 v242, v242, v243
	v_cvt_pk_bf16_f32 v243, v236, v237
	global_store_dwordx2 v222, v[242:243], s[34:35]
	s_add_u32 s34, s34, 0x800
	s_addc_u32 s35, s35, 0
	s_waitcnt lgkmcnt(5)
	v_xor_b32_e32 v239, 0x80000000, v95
	v_xor_b32_e32 v238, 0x80000000, v94
	v_pk_fma_f32 v[4:5], v[238:239], v[244:245], v[4:5] op_sel_hi:[1,0,1]
	v_pk_fma_f32 v[2:3], v[92:93], v[244:245], v[2:3] op_sel_hi:[1,0,1] neg_lo:[1,0,0] neg_hi:[1,0,0]
	ds_read_b32 v228, v223 offset:84
	s_waitcnt lgkmcnt(5)
	s_waitcnt vmcnt(31)
	v_pk_mul_f32 v[236:237], v[156:157], v[246:247] op_sel_hi:[1,0]
	v_pk_fma_f32 v[2:3], v[156:157], v[246:247], v[2:3] op_sel_hi:[1,0,1]
	v_pk_mul_f32 v[238:239], v[158:159], v[246:247] op_sel_hi:[1,0]
	v_pk_fma_f32 v[4:5], v[158:159], v[246:247], v[4:5] op_sel_hi:[1,0,1]
	ds_read_b32 v230, v223 offset:148
	v_mov_b32_e32 v240, 0x3d800000
	v_pk_fma_f32 v[242:243], v[240:241], v[2:3], v[236:237] op_sel_hi:[0,1,1] neg_lo:[0,0,1] neg_hi:[0,0,1]
	v_pk_fma_f32 v[236:237], v[240:241], v[4:5], v[238:239] op_sel_hi:[0,1,1] neg_lo:[0,0,1] neg_hi:[0,0,1]
	v_cvt_pk_bf16_f32 v242, v242, v243
	v_cvt_pk_bf16_f32 v243, v236, v237
	global_store_dwordx2 v222, v[242:243], s[34:35]
	s_add_u32 s34, s34, 0x800
	s_addc_u32 s35, s35, 0
	s_waitcnt lgkmcnt(5)
	v_xor_b32_e32 v239, 0x80000000, v99
	v_xor_b32_e32 v238, 0x80000000, v98
	v_pk_fma_f32 v[4:5], v[238:239], v[248:249], v[4:5] op_sel_hi:[1,0,1]
	v_pk_fma_f32 v[2:3], v[96:97], v[248:249], v[2:3] op_sel_hi:[1,0,1] neg_lo:[1,0,0] neg_hi:[1,0,0]
	ds_read_b32 v244, v223 offset:88
	s_waitcnt lgkmcnt(5)
	s_waitcnt vmcnt(31)
	v_pk_mul_f32 v[236:237], v[160:161], v[232:233] op_sel_hi:[1,0]
	v_pk_fma_f32 v[2:3], v[160:161], v[232:233], v[2:3] op_sel_hi:[1,0,1]
	v_pk_mul_f32 v[238:239], v[162:163], v[232:233] op_sel_hi:[1,0]
	v_pk_fma_f32 v[4:5], v[162:163], v[232:233], v[4:5] op_sel_hi:[1,0,1]
	ds_read_b32 v246, v223 offset:152
	v_mov_b32_e32 v240, 0x3d800000
	v_pk_fma_f32 v[242:243], v[240:241], v[2:3], v[236:237] op_sel_hi:[0,1,1] neg_lo:[0,0,1] neg_hi:[0,0,1]
	v_pk_fma_f32 v[236:237], v[240:241], v[4:5], v[238:239] op_sel_hi:[0,1,1] neg_lo:[0,0,1] neg_hi:[0,0,1]
	v_cvt_pk_bf16_f32 v242, v242, v243
	v_cvt_pk_bf16_f32 v243, v236, v237
	global_store_dwordx2 v222, v[242:243], s[34:35]
	s_add_u32 s34, s34, 0x800
	s_addc_u32 s35, s35, 0
	s_waitcnt lgkmcnt(5)
	v_xor_b32_e32 v239, 0x80000000, v103
	v_xor_b32_e32 v238, 0x80000000, v102
	v_pk_fma_f32 v[4:5], v[238:239], v[224:225], v[4:5] op_sel_hi:[1,0,1]
	v_pk_fma_f32 v[2:3], v[100:101], v[224:225], v[2:3] op_sel_hi:[1,0,1] neg_lo:[1,0,0] neg_hi:[1,0,0]
	ds_read_b32 v248, v223 offset:92
	s_waitcnt lgkmcnt(5)
	s_waitcnt vmcnt(31)
	v_pk_mul_f32 v[236:237], v[164:165], v[226:227] op_sel_hi:[1,0]
	v_pk_fma_f32 v[2:3], v[164:165], v[226:227], v[2:3] op_sel_hi:[1,0,1]
	v_pk_mul_f32 v[238:239], v[166:167], v[226:227] op_sel_hi:[1,0]
	v_pk_fma_f32 v[4:5], v[166:167], v[226:227], v[4:5] op_sel_hi:[1,0,1]
	ds_read_b32 v232, v223 offset:156
	v_mov_b32_e32 v240, 0x3d800000
	v_pk_fma_f32 v[242:243], v[240:241], v[2:3], v[236:237] op_sel_hi:[0,1,1] neg_lo:[0,0,1] neg_hi:[0,0,1]
	v_pk_fma_f32 v[236:237], v[240:241], v[4:5], v[238:239] op_sel_hi:[0,1,1] neg_lo:[0,0,1] neg_hi:[0,0,1]
	v_cvt_pk_bf16_f32 v242, v242, v243
	v_cvt_pk_bf16_f32 v243, v236, v237
	global_store_dwordx2 v222, v[242:243], s[34:35]
	s_add_u32 s34, s34, 0x800
	s_addc_u32 s35, s35, 0
	s_waitcnt lgkmcnt(5)
	v_xor_b32_e32 v239, 0x80000000, v107
	v_xor_b32_e32 v238, 0x80000000, v106
	v_pk_fma_f32 v[4:5], v[238:239], v[228:229], v[4:5] op_sel_hi:[1,0,1]
	v_pk_fma_f32 v[2:3], v[104:105], v[228:229], v[2:3] op_sel_hi:[1,0,1] neg_lo:[1,0,0] neg_hi:[1,0,0]
	ds_read_b32 v224, v223 offset:96
	s_waitcnt lgkmcnt(5)
	s_waitcnt vmcnt(31)
	v_pk_mul_f32 v[236:237], v[168:169], v[230:231] op_sel_hi:[1,0]
	v_pk_fma_f32 v[2:3], v[168:169], v[230:231], v[2:3] op_sel_hi:[1,0,1]
	v_pk_mul_f32 v[238:239], v[170:171], v[230:231] op_sel_hi:[1,0]
	v_pk_fma_f32 v[4:5], v[170:171], v[230:231], v[4:5] op_sel_hi:[1,0,1]
	ds_read_b32 v226, v223 offset:160
	v_mov_b32_e32 v240, 0x3d800000
	v_pk_fma_f32 v[242:243], v[240:241], v[2:3], v[236:237] op_sel_hi:[0,1,1] neg_lo:[0,0,1] neg_hi:[0,0,1]
	v_pk_fma_f32 v[236:237], v[240:241], v[4:5], v[238:239] op_sel_hi:[0,1,1] neg_lo:[0,0,1] neg_hi:[0,0,1]
	v_cvt_pk_bf16_f32 v242, v242, v243
	v_cvt_pk_bf16_f32 v243, v236, v237
	global_store_dwordx2 v222, v[242:243], s[34:35]
	s_add_u32 s34, s34, 0x800
	s_addc_u32 s35, s35, 0
	s_waitcnt lgkmcnt(5)
	v_xor_b32_e32 v239, 0x80000000, v111
	v_xor_b32_e32 v238, 0x80000000, v110
	v_pk_fma_f32 v[4:5], v[238:239], v[244:245], v[4:5] op_sel_hi:[1,0,1]
	v_pk_fma_f32 v[2:3], v[108:109], v[244:245], v[2:3] op_sel_hi:[1,0,1] neg_lo:[1,0,0] neg_hi:[1,0,0]
	ds_read_b32 v228, v223 offset:100
	s_waitcnt lgkmcnt(5)
	s_waitcnt vmcnt(31)
	v_pk_mul_f32 v[236:237], v[172:173], v[246:247] op_sel_hi:[1,0]
	v_pk_fma_f32 v[2:3], v[172:173], v[246:247], v[2:3] op_sel_hi:[1,0,1]
	v_pk_mul_f32 v[238:239], v[174:175], v[246:247] op_sel_hi:[1,0]
	v_pk_fma_f32 v[4:5], v[174:175], v[246:247], v[4:5] op_sel_hi:[1,0,1]
	ds_read_b32 v230, v223 offset:164
	v_mov_b32_e32 v240, 0x3d800000
	v_pk_fma_f32 v[242:243], v[240:241], v[2:3], v[236:237] op_sel_hi:[0,1,1] neg_lo:[0,0,1] neg_hi:[0,0,1]
	v_pk_fma_f32 v[236:237], v[240:241], v[4:5], v[238:239] op_sel_hi:[0,1,1] neg_lo:[0,0,1] neg_hi:[0,0,1]
	v_cvt_pk_bf16_f32 v242, v242, v243
	v_cvt_pk_bf16_f32 v243, v236, v237
	global_store_dwordx2 v222, v[242:243], s[34:35]
	s_add_u32 s34, s34, 0x800
	s_addc_u32 s35, s35, 0
	s_waitcnt lgkmcnt(5)
	v_xor_b32_e32 v239, 0x80000000, v115
	v_xor_b32_e32 v238, 0x80000000, v114
	v_pk_fma_f32 v[4:5], v[238:239], v[248:249], v[4:5] op_sel_hi:[1,0,1]
	v_pk_fma_f32 v[2:3], v[112:113], v[248:249], v[2:3] op_sel_hi:[1,0,1] neg_lo:[1,0,0] neg_hi:[1,0,0]
	ds_read_b32 v244, v223 offset:104
	s_waitcnt lgkmcnt(5)
	s_waitcnt vmcnt(31)
	v_pk_mul_f32 v[236:237], v[176:177], v[232:233] op_sel_hi:[1,0]
	v_pk_fma_f32 v[2:3], v[176:177], v[232:233], v[2:3] op_sel_hi:[1,0,1]
	v_pk_mul_f32 v[238:239], v[178:179], v[232:233] op_sel_hi:[1,0]
	v_pk_fma_f32 v[4:5], v[178:179], v[232:233], v[4:5] op_sel_hi:[1,0,1]
	ds_read_b32 v246, v223 offset:168
	v_mov_b32_e32 v240, 0x3d800000
	v_pk_fma_f32 v[242:243], v[240:241], v[2:3], v[236:237] op_sel_hi:[0,1,1] neg_lo:[0,0,1] neg_hi:[0,0,1]
	v_pk_fma_f32 v[236:237], v[240:241], v[4:5], v[238:239] op_sel_hi:[0,1,1] neg_lo:[0,0,1] neg_hi:[0,0,1]
	v_cvt_pk_bf16_f32 v242, v242, v243
	v_cvt_pk_bf16_f32 v243, v236, v237
	global_store_dwordx2 v222, v[242:243], s[34:35]
	s_add_u32 s34, s34, 0x800
	s_addc_u32 s35, s35, 0
	s_waitcnt lgkmcnt(5)
	v_xor_b32_e32 v239, 0x80000000, v119
	v_xor_b32_e32 v238, 0x80000000, v118
	v_pk_fma_f32 v[4:5], v[238:239], v[224:225], v[4:5] op_sel_hi:[1,0,1]
	v_pk_fma_f32 v[2:3], v[116:117], v[224:225], v[2:3] op_sel_hi:[1,0,1] neg_lo:[1,0,0] neg_hi:[1,0,0]
	ds_read_b32 v248, v223 offset:108
	s_waitcnt lgkmcnt(5)
	s_waitcnt vmcnt(31)
	v_pk_mul_f32 v[236:237], v[180:181], v[226:227] op_sel_hi:[1,0]
	v_pk_fma_f32 v[2:3], v[180:181], v[226:227], v[2:3] op_sel_hi:[1,0,1]
	v_pk_mul_f32 v[238:239], v[182:183], v[226:227] op_sel_hi:[1,0]
	v_pk_fma_f32 v[4:5], v[182:183], v[226:227], v[4:5] op_sel_hi:[1,0,1]
	ds_read_b32 v232, v223 offset:172
	v_mov_b32_e32 v240, 0x3d800000
	v_pk_fma_f32 v[242:243], v[240:241], v[2:3], v[236:237] op_sel_hi:[0,1,1] neg_lo:[0,0,1] neg_hi:[0,0,1]
	v_pk_fma_f32 v[236:237], v[240:241], v[4:5], v[238:239] op_sel_hi:[0,1,1] neg_lo:[0,0,1] neg_hi:[0,0,1]
	v_cvt_pk_bf16_f32 v242, v242, v243
	v_cvt_pk_bf16_f32 v243, v236, v237
	global_store_dwordx2 v222, v[242:243], s[34:35]
	s_add_u32 s34, s34, 0x800
	s_addc_u32 s35, s35, 0
	s_waitcnt lgkmcnt(5)
	v_xor_b32_e32 v239, 0x80000000, v123
	v_xor_b32_e32 v238, 0x80000000, v122
	v_pk_fma_f32 v[4:5], v[238:239], v[228:229], v[4:5] op_sel_hi:[1,0,1]
	v_pk_fma_f32 v[2:3], v[120:121], v[228:229], v[2:3] op_sel_hi:[1,0,1] neg_lo:[1,0,0] neg_hi:[1,0,0]
	ds_read_b32 v224, v223 offset:112
	s_waitcnt lgkmcnt(5)
	s_waitcnt vmcnt(31)
	v_pk_mul_f32 v[236:237], v[184:185], v[230:231] op_sel_hi:[1,0]
	v_pk_fma_f32 v[2:3], v[184:185], v[230:231], v[2:3] op_sel_hi:[1,0,1]
	v_pk_mul_f32 v[238:239], v[186:187], v[230:231] op_sel_hi:[1,0]
	v_pk_fma_f32 v[4:5], v[186:187], v[230:231], v[4:5] op_sel_hi:[1,0,1]
	ds_read_b32 v226, v223 offset:176
	v_mov_b32_e32 v240, 0x3d800000
	v_pk_fma_f32 v[242:243], v[240:241], v[2:3], v[236:237] op_sel_hi:[0,1,1] neg_lo:[0,0,1] neg_hi:[0,0,1]
	v_pk_fma_f32 v[236:237], v[240:241], v[4:5], v[238:239] op_sel_hi:[0,1,1] neg_lo:[0,0,1] neg_hi:[0,0,1]
	v_cvt_pk_bf16_f32 v242, v242, v243
	v_cvt_pk_bf16_f32 v243, v236, v237
	global_store_dwordx2 v222, v[242:243], s[34:35]
	s_add_u32 s34, s34, 0x800
	s_addc_u32 s35, s35, 0
	s_waitcnt lgkmcnt(5)
	v_xor_b32_e32 v239, 0x80000000, v127
	v_xor_b32_e32 v238, 0x80000000, v126
	v_pk_fma_f32 v[4:5], v[238:239], v[244:245], v[4:5] op_sel_hi:[1,0,1]
	v_pk_fma_f32 v[2:3], v[124:125], v[244:245], v[2:3] op_sel_hi:[1,0,1] neg_lo:[1,0,0] neg_hi:[1,0,0]
	ds_read_b32 v228, v223 offset:116
	s_waitcnt lgkmcnt(5)
	s_waitcnt vmcnt(31)
	v_pk_mul_f32 v[236:237], v[188:189], v[246:247] op_sel_hi:[1,0]
	v_pk_fma_f32 v[2:3], v[188:189], v[246:247], v[2:3] op_sel_hi:[1,0,1]
	v_pk_mul_f32 v[238:239], v[190:191], v[246:247] op_sel_hi:[1,0]
	v_pk_fma_f32 v[4:5], v[190:191], v[246:247], v[4:5] op_sel_hi:[1,0,1]
	ds_read_b32 v230, v223 offset:180
	v_mov_b32_e32 v240, 0x3d800000
	v_pk_fma_f32 v[242:243], v[240:241], v[2:3], v[236:237] op_sel_hi:[0,1,1] neg_lo:[0,0,1] neg_hi:[0,0,1]
	v_pk_fma_f32 v[236:237], v[240:241], v[4:5], v[238:239] op_sel_hi:[0,1,1] neg_lo:[0,0,1] neg_hi:[0,0,1]
	v_cvt_pk_bf16_f32 v242, v242, v243
	v_cvt_pk_bf16_f32 v243, v236, v237
	global_store_dwordx2 v222, v[242:243], s[34:35]
	s_add_u32 s34, s34, 0x800
	s_addc_u32 s35, s35, 0
	s_waitcnt lgkmcnt(5)
	v_xor_b32_e32 v239, 0x80000000, v131
	v_xor_b32_e32 v238, 0x80000000, v130
	v_pk_fma_f32 v[4:5], v[238:239], v[248:249], v[4:5] op_sel_hi:[1,0,1]
	v_pk_fma_f32 v[2:3], v[128:129], v[248:249], v[2:3] op_sel_hi:[1,0,1] neg_lo:[1,0,0] neg_hi:[1,0,0]
	ds_read_b32 v244, v223 offset:120
	s_waitcnt lgkmcnt(5)
	s_waitcnt vmcnt(31)
	v_pk_mul_f32 v[236:237], v[192:193], v[232:233] op_sel_hi:[1,0]
	v_pk_fma_f32 v[2:3], v[192:193], v[232:233], v[2:3] op_sel_hi:[1,0,1]
	v_pk_mul_f32 v[238:239], v[194:195], v[232:233] op_sel_hi:[1,0]
	v_pk_fma_f32 v[4:5], v[194:195], v[232:233], v[4:5] op_sel_hi:[1,0,1]
	ds_read_b32 v246, v223 offset:184
	v_mov_b32_e32 v240, 0x3d800000
	v_pk_fma_f32 v[242:243], v[240:241], v[2:3], v[236:237] op_sel_hi:[0,1,1] neg_lo:[0,0,1] neg_hi:[0,0,1]
	v_pk_fma_f32 v[236:237], v[240:241], v[4:5], v[238:239] op_sel_hi:[0,1,1] neg_lo:[0,0,1] neg_hi:[0,0,1]
	v_cvt_pk_bf16_f32 v242, v242, v243
	v_cvt_pk_bf16_f32 v243, v236, v237
	global_store_dwordx2 v222, v[242:243], s[34:35]
	s_add_u32 s34, s34, 0x800
	s_addc_u32 s35, s35, 0
	s_waitcnt lgkmcnt(5)
	v_xor_b32_e32 v239, 0x80000000, v135
	v_xor_b32_e32 v238, 0x80000000, v134
	v_pk_fma_f32 v[4:5], v[238:239], v[224:225], v[4:5] op_sel_hi:[1,0,1]
	v_pk_fma_f32 v[2:3], v[132:133], v[224:225], v[2:3] op_sel_hi:[1,0,1] neg_lo:[1,0,0] neg_hi:[1,0,0]
	ds_read_b32 v248, v223 offset:124
	s_waitcnt lgkmcnt(5)
	s_waitcnt vmcnt(31)
	v_pk_mul_f32 v[236:237], v[196:197], v[226:227] op_sel_hi:[1,0]
	v_pk_fma_f32 v[2:3], v[196:197], v[226:227], v[2:3] op_sel_hi:[1,0,1]
	v_pk_mul_f32 v[238:239], v[198:199], v[226:227] op_sel_hi:[1,0]
	v_pk_fma_f32 v[4:5], v[198:199], v[226:227], v[4:5] op_sel_hi:[1,0,1]
	v_mov_b32_e32 v240, 0x3d800000
	v_pk_fma_f32 v[242:243], v[240:241], v[2:3], v[236:237] op_sel_hi:[0,1,1] neg_lo:[0,0,1] neg_hi:[0,0,1]
	v_pk_fma_f32 v[236:237], v[240:241], v[4:5], v[238:239] op_sel_hi:[0,1,1] neg_lo:[0,0,1] neg_hi:[0,0,1]
	v_cvt_pk_bf16_f32 v242, v242, v243
	v_cvt_pk_bf16_f32 v243, v236, v237
	global_store_dwordx2 v222, v[242:243], s[34:35]
	s_add_u32 s34, s34, 0x800
	s_addc_u32 s35, s35, 0
	s_waitcnt lgkmcnt(4)
	v_xor_b32_e32 v239, 0x80000000, v139
	v_xor_b32_e32 v238, 0x80000000, v138
	v_pk_fma_f32 v[4:5], v[238:239], v[228:229], v[4:5] op_sel_hi:[1,0,1]
	v_pk_fma_f32 v[2:3], v[136:137], v[228:229], v[2:3] op_sel_hi:[1,0,1] neg_lo:[1,0,0] neg_hi:[1,0,0]
	s_waitcnt lgkmcnt(3)
	s_waitcnt vmcnt(31)
	v_pk_mul_f32 v[236:237], v[200:201], v[230:231] op_sel_hi:[1,0]
	v_pk_fma_f32 v[2:3], v[200:201], v[230:231], v[2:3] op_sel_hi:[1,0,1]
	v_pk_mul_f32 v[238:239], v[202:203], v[230:231] op_sel_hi:[1,0]
	v_pk_fma_f32 v[4:5], v[202:203], v[230:231], v[4:5] op_sel_hi:[1,0,1]
	v_mov_b32_e32 v240, 0x3d800000
	v_pk_fma_f32 v[242:243], v[240:241], v[2:3], v[236:237] op_sel_hi:[0,1,1] neg_lo:[0,0,1] neg_hi:[0,0,1]
	v_pk_fma_f32 v[236:237], v[240:241], v[4:5], v[238:239] op_sel_hi:[0,1,1] neg_lo:[0,0,1] neg_hi:[0,0,1]
	v_cvt_pk_bf16_f32 v242, v242, v243
	v_cvt_pk_bf16_f32 v243, v236, v237
	global_store_dwordx2 v222, v[242:243], s[34:35]
	s_add_u32 s34, s34, 0x800
	s_addc_u32 s35, s35, 0
	s_waitcnt lgkmcnt(2)
	v_xor_b32_e32 v239, 0x80000000, v143
	v_xor_b32_e32 v238, 0x80000000, v142
	v_pk_fma_f32 v[4:5], v[238:239], v[244:245], v[4:5] op_sel_hi:[1,0,1]
	v_pk_fma_f32 v[2:3], v[140:141], v[244:245], v[2:3] op_sel_hi:[1,0,1] neg_lo:[1,0,0] neg_hi:[1,0,0]
	s_waitcnt lgkmcnt(1)
	s_waitcnt vmcnt(31)
	v_pk_mul_f32 v[236:237], v[216:217], v[246:247] op_sel_hi:[1,0]
	v_pk_fma_f32 v[2:3], v[216:217], v[246:247], v[2:3] op_sel_hi:[1,0,1]
	v_pk_mul_f32 v[238:239], v[218:219], v[246:247] op_sel_hi:[1,0]
	v_pk_fma_f32 v[4:5], v[218:219], v[246:247], v[4:5] op_sel_hi:[1,0,1]
	v_mov_b32_e32 v240, 0x3d800000
	v_pk_fma_f32 v[242:243], v[240:241], v[2:3], v[236:237] op_sel_hi:[0,1,1] neg_lo:[0,0,1] neg_hi:[0,0,1]
	v_pk_fma_f32 v[236:237], v[240:241], v[4:5], v[238:239] op_sel_hi:[0,1,1] neg_lo:[0,0,1] neg_hi:[0,0,1]
	v_cvt_pk_bf16_f32 v242, v242, v243
	v_cvt_pk_bf16_f32 v243, v236, v237
	global_store_dwordx2 v222, v[242:243], s[34:35]
	s_add_u32 s34, s34, 0x800
	s_addc_u32 s35, s35, 0
	s_waitcnt lgkmcnt(0)
	v_xor_b32_e32 v239, 0x80000000, v147
	v_xor_b32_e32 v238, 0x80000000, v146
	v_pk_fma_f32 v[4:5], v[238:239], v[248:249], v[4:5] op_sel_hi:[1,0,1]
	v_pk_fma_f32 v[2:3], v[144:145], v[248:249], v[2:3] op_sel_hi:[1,0,1] neg_lo:[1,0,0] neg_hi:[1,0,0]
	s_branch .Lpool_done
.Lpool_done:
	s_branch .LBB0_1217
.LBB0_1236:
	s_mov_b64 s[0:1], 0

.LBB0_1261:
	ds_read2_b32 v[140:141], v219 offset1:32
	ds_read2_b32 v[136:137], v219 offset0:64 offset1:96
	v_and_b32_e32 v0, 1, v199
	v_and_b32_e32 v228, 63, v198
	v_mov_b32_e32 v142, v199
	v_mov_b32_e32 v139, v202
	v_mov_b32_e32 v130, v200
	v_bfe_u32 v131, v199, 1, 1
	v_mov_b32_e32 v135, v201
	s_lshl_b32 s1, s6, 8
	v_readfirstlane_b32 s0, v131
	s_lshl_b32 s3, s0, 7
	s_add_i32 s3, s3, s1
	v_lshl_add_u32 v134, v130, 7, s2
	v_lshlrev_b32_e32 v0, 6, v0
	v_lshlrev_b32_e32 v130, 2, v139
	v_add_u32_e32 v138, s3, v0
	s_mov_b64 s[0:1], -1
	s_cmpk_gt_i32 s3, 0x7ff
	v_ashrrev_i32_e32 v131, 31, v130
	s_cbranch_scc0 .LBB0_1263
	v_readfirstlane_b32 s8, v204
	s_lshr_b32 s8, s8, 6
	s_and_b32 s9, s8, 1
	s_lshr_b32 s10, s8, 2
	s_lshl_b32 s11, s9, 6
	s_add_i32 s11, s11, s3
	s_sub_i32 s11, s11, 0x800
	s_lshr_b32 s12, s11, 7
	s_and_b32 s11, s11, 0x7f
	s_lshl_b32 s10, s10, 7
	s_add_i32 s10, s10, s2
	s_lshr_b32 s13, s10, 12
	s_and_b32 s10, s10, 0xfff
	s_lshl_b32 s13, s13, 3
	s_add_i32 s13, s13, s12
	s_lshl_b32 s13, s13, 7
	s_add_i32 s13, s13, s11
	s_lshl_b32 s13, s13, 13
	s_lshl_b32 s10, s10, 1
	s_add_u32 s13, s13, s10
	v_readlane_b32 s14, v252, 27
	v_readlane_b32 s15, v252, 28
	s_add_u32 s14, s14, s13
	s_addc_u32 s15, s15, 0
	v_and_b32_e32 v130, 63, v204
	v_and_b32_e32 v131, 31, v130
	v_lshrrev_b32_e32 v132, 5, v130
	s_lshl_b32 s8, s8, 14
	v_lshlrev_b32_e32 v133, 10, v132
	v_lshl_add_u32 v133, v131, 1, v133
	v_add_u32_e32 v133, s8, v133
	v_lshrrev_b32_e32 v134, 4, v130
	v_and_b32_e32 v135, 15, v130
	v_lshlrev_b32_e32 v135, 4, v135
	v_lshl_add_u32 v138, v134, 8, v135
	v_add_u32_e32 v138, s8, v138
	v_lshl_add_u32 v139, v134, 13, v135
	s_waitcnt lgkmcnt(0)
	v_mul_f32_e32 v142, v98, v140
	v_mul_f32_e32 v143, v99, v140
	v_cvt_pk_bf16_f32 v142, v142, v143
	ds_write_b16 v133, v142 offset:0
	ds_write_b16_d16_hi v133, v142 offset:256
	v_mul_f32_e32 v144, v100, v140
	v_mul_f32_e32 v145, v101, v140
	v_cvt_pk_bf16_f32 v144, v144, v145
	ds_write_b16 v133, v144 offset:512
	ds_write_b16_d16_hi v133, v144 offset:768
	v_mul_f32_e32 v146, v102, v140
	v_mul_f32_e32 v147, v103, v140
	v_cvt_pk_bf16_f32 v146, v146, v147
	ds_write_b16 v133, v146 offset:2048
	ds_write_b16_d16_hi v133, v146 offset:2304
	v_mul_f32_e32 v148, v104, v140
	v_mul_f32_e32 v149, v105, v140
	v_cvt_pk_bf16_f32 v148, v148, v149
	ds_write_b16 v133, v148 offset:2560
	ds_write_b16_d16_hi v133, v148 offset:2816
	v_mul_f32_e32 v142, v106, v140
	v_mul_f32_e32 v143, v107, v140
	v_cvt_pk_bf16_f32 v142, v142, v143
	ds_write_b16 v133, v142 offset:4096
	ds_write_b16_d16_hi v133, v142 offset:4352
	v_mul_f32_e32 v144, v108, v140
	v_mul_f32_e32 v145, v109, v140
	v_cvt_pk_bf16_f32 v144, v144, v145
	ds_write_b16 v133, v144 offset:4608
	ds_write_b16_d16_hi v133, v144 offset:4864
	v_mul_f32_e32 v146, v110, v140
	v_mul_f32_e32 v147, v111, v140
	v_cvt_pk_bf16_f32 v146, v146, v147
	ds_write_b16 v133, v146 offset:6144
	ds_write_b16_d16_hi v133, v146 offset:6400
	v_mul_f32_e32 v148, v112, v140
	v_mul_f32_e32 v149, v113, v140
	v_cvt_pk_bf16_f32 v148, v148, v149
	ds_write_b16 v133, v148 offset:6656
	ds_write_b16_d16_hi v133, v148 offset:6912
	v_mul_f32_e32 v142, v114, v140
	v_mul_f32_e32 v143, v115, v140
	v_cvt_pk_bf16_f32 v142, v142, v143
	ds_write_b16 v133, v142 offset:8192
	ds_write_b16_d16_hi v133, v142 offset:8448
	v_mul_f32_e32 v144, v116, v140
	v_mul_f32_e32 v145, v117, v140
	v_cvt_pk_bf16_f32 v144, v144, v145
	ds_write_b16 v133, v144 offset:8704
	ds_write_b16_d16_hi v133, v144 offset:8960
	v_mul_f32_e32 v146, v118, v140
	v_mul_f32_e32 v147, v119, v140
	v_cvt_pk_bf16_f32 v146, v146, v147
	ds_write_b16 v133, v146 offset:10240
	ds_write_b16_d16_hi v133, v146 offset:10496
	v_mul_f32_e32 v148, v120, v140
	v_mul_f32_e32 v149, v121, v140
	v_cvt_pk_bf16_f32 v148, v148, v149
	ds_write_b16 v133, v148 offset:10752
	ds_write_b16_d16_hi v133, v148 offset:11008
	v_mul_f32_e32 v142, v122, v140
	v_mul_f32_e32 v143, v123, v140
	v_cvt_pk_bf16_f32 v142, v142, v143
	ds_write_b16 v133, v142 offset:12288
	ds_write_b16_d16_hi v133, v142 offset:12544
	v_mul_f32_e32 v144, v124, v140
	v_mul_f32_e32 v145, v125, v140
	v_cvt_pk_bf16_f32 v144, v144, v145
	ds_write_b16 v133, v144 offset:12800
	ds_write_b16_d16_hi v133, v144 offset:13056
	v_mul_f32_e32 v146, v126, v140
	v_mul_f32_e32 v147, v127, v140
	v_cvt_pk_bf16_f32 v146, v146, v147
	ds_write_b16 v133, v146 offset:14336
	ds_write_b16_d16_hi v133, v146 offset:14592
	v_mul_f32_e32 v148, v128, v140
	v_mul_f32_e32 v149, v129, v140
	v_cvt_pk_bf16_f32 v148, v148, v149
	ds_write_b16 v133, v148 offset:14848
	ds_write_b16_d16_hi v133, v148 offset:15104
	v_mul_f32_e32 v142, v82, v141
	v_mul_f32_e32 v143, v83, v141
	v_cvt_pk_bf16_f32 v142, v142, v143
	ds_write_b16 v133, v142 offset:64
	ds_write_b16_d16_hi v133, v142 offset:320
	v_mul_f32_e32 v144, v84, v141
	v_mul_f32_e32 v145, v85, v141
	v_cvt_pk_bf16_f32 v144, v144, v145
	ds_write_b16 v133, v144 offset:576
	ds_write_b16_d16_hi v133, v144 offset:832
	v_mul_f32_e32 v146, v86, v141
	v_mul_f32_e32 v147, v87, v141
	v_cvt_pk_bf16_f32 v146, v146, v147
	ds_write_b16 v133, v146 offset:2112
	ds_write_b16_d16_hi v133, v146 offset:2368
	v_mul_f32_e32 v148, v88, v141
	v_mul_f32_e32 v149, v89, v141
	v_cvt_pk_bf16_f32 v148, v148, v149
	ds_write_b16 v133, v148 offset:2624
	ds_write_b16_d16_hi v133, v148 offset:2880
	v_mul_f32_e32 v142, v90, v141
	v_mul_f32_e32 v143, v91, v141
	v_cvt_pk_bf16_f32 v142, v142, v143
	ds_write_b16 v133, v142 offset:4160
	ds_write_b16_d16_hi v133, v142 offset:4416
	v_mul_f32_e32 v144, v92, v141
	v_mul_f32_e32 v145, v93, v141
	v_cvt_pk_bf16_f32 v144, v144, v145
	ds_write_b16 v133, v144 offset:4672
	ds_write_b16_d16_hi v133, v144 offset:4928
	v_mul_f32_e32 v146, v94, v141
	v_mul_f32_e32 v147, v95, v141
	v_cvt_pk_bf16_f32 v146, v146, v147
	ds_write_b16 v133, v146 offset:6208
	ds_write_b16_d16_hi v133, v146 offset:6464
	v_mul_f32_e32 v148, v96, v141
	v_mul_f32_e32 v149, v97, v141
	v_cvt_pk_bf16_f32 v148, v148, v149
	ds_write_b16 v133, v148 offset:6720
	ds_write_b16_d16_hi v133, v148 offset:6976
	v_mul_f32_e32 v142, v66, v141
	v_mul_f32_e32 v143, v67, v141
	v_cvt_pk_bf16_f32 v142, v142, v143
	ds_write_b16 v133, v142 offset:8256
	ds_write_b16_d16_hi v133, v142 offset:8512
	v_mul_f32_e32 v144, v68, v141
	v_mul_f32_e32 v145, v69, v141
	v_cvt_pk_bf16_f32 v144, v144, v145
	ds_write_b16 v133, v144 offset:8768
	ds_write_b16_d16_hi v133, v144 offset:9024
	v_mul_f32_e32 v146, v70, v141
	v_mul_f32_e32 v147, v71, v141
	v_cvt_pk_bf16_f32 v146, v146, v147
	ds_write_b16 v133, v146 offset:10304
	ds_write_b16_d16_hi v133, v146 offset:10560
	v_mul_f32_e32 v148, v72, v141
	v_mul_f32_e32 v149, v73, v141
	v_cvt_pk_bf16_f32 v148, v148, v149
	ds_write_b16 v133, v148 offset:10816
	ds_write_b16_d16_hi v133, v148 offset:11072
	v_mul_f32_e32 v142, v74, v141
	v_mul_f32_e32 v143, v75, v141
	v_cvt_pk_bf16_f32 v142, v142, v143
	ds_write_b16 v133, v142 offset:12352
	ds_write_b16_d16_hi v133, v142 offset:12608
	v_mul_f32_e32 v144, v76, v141
	v_mul_f32_e32 v145, v77, v141
	v_cvt_pk_bf16_f32 v144, v144, v145
	ds_write_b16 v133, v144 offset:12864
	ds_write_b16_d16_hi v133, v144 offset:13120
	v_mul_f32_e32 v146, v78, v141
	v_mul_f32_e32 v147, v79, v141
	v_cvt_pk_bf16_f32 v146, v146, v147
	ds_write_b16 v133, v146 offset:14400
	ds_write_b16_d16_hi v133, v146 offset:14656
	v_mul_f32_e32 v148, v80, v141
	v_mul_f32_e32 v149, v81, v141
	v_cvt_pk_bf16_f32 v148, v148, v149
	ds_write_b16 v133, v148 offset:14912
	ds_write_b16_d16_hi v133, v148 offset:15168
	v_mul_f32_e32 v142, v34, v136
	v_mul_f32_e32 v143, v35, v136
	v_cvt_pk_bf16_f32 v142, v142, v143
	ds_write_b16 v133, v142 offset:128
	ds_write_b16_d16_hi v133, v142 offset:384
	v_mul_f32_e32 v144, v36, v136
	v_mul_f32_e32 v145, v37, v136
	v_cvt_pk_bf16_f32 v144, v144, v145
	ds_write_b16 v133, v144 offset:640
	ds_write_b16_d16_hi v133, v144 offset:896
	v_mul_f32_e32 v146, v38, v136
	v_mul_f32_e32 v147, v39, v136
	v_cvt_pk_bf16_f32 v146, v146, v147
	ds_write_b16 v133, v146 offset:2176
	ds_write_b16_d16_hi v133, v146 offset:2432
	v_mul_f32_e32 v148, v40, v136
	v_mul_f32_e32 v149, v41, v136
	v_cvt_pk_bf16_f32 v148, v148, v149
	ds_write_b16 v133, v148 offset:2688
	ds_write_b16_d16_hi v133, v148 offset:2944
	v_mul_f32_e32 v142, v42, v136
	v_mul_f32_e32 v143, v43, v136
	v_cvt_pk_bf16_f32 v142, v142, v143
	ds_write_b16 v133, v142 offset:4224
	ds_write_b16_d16_hi v133, v142 offset:4480
	v_mul_f32_e32 v144, v44, v136
	v_mul_f32_e32 v145, v45, v136
	v_cvt_pk_bf16_f32 v144, v144, v145
	ds_write_b16 v133, v144 offset:4736
	ds_write_b16_d16_hi v133, v144 offset:4992
	v_mul_f32_e32 v146, v46, v136
	v_mul_f32_e32 v147, v47, v136
	v_cvt_pk_bf16_f32 v146, v146, v147
	ds_write_b16 v133, v146 offset:6272
	ds_write_b16_d16_hi v133, v146 offset:6528
	v_mul_f32_e32 v148, v48, v136
	v_mul_f32_e32 v149, v49, v136
	v_cvt_pk_bf16_f32 v148, v148, v149
	ds_write_b16 v133, v148 offset:6784
	ds_write_b16_d16_hi v133, v148 offset:7040
	v_mul_f32_e32 v142, v50, v136
	v_mul_f32_e32 v143, v51, v136
	v_cvt_pk_bf16_f32 v142, v142, v143
	ds_write_b16 v133, v142 offset:8320
	ds_write_b16_d16_hi v133, v142 offset:8576
	v_mul_f32_e32 v144, v52, v136
	v_mul_f32_e32 v145, v53, v136
	v_cvt_pk_bf16_f32 v144, v144, v145
	ds_write_b16 v133, v144 offset:8832
	ds_write_b16_d16_hi v133, v144 offset:9088
	v_mul_f32_e32 v146, v54, v136
	v_mul_f32_e32 v147, v55, v136
	v_cvt_pk_bf16_f32 v146, v146, v147
	ds_write_b16 v133, v146 offset:10368
	ds_write_b16_d16_hi v133, v146 offset:10624
	v_mul_f32_e32 v148, v56, v136
	v_mul_f32_e32 v149, v57, v136
	v_cvt_pk_bf16_f32 v148, v148, v149
	ds_write_b16 v133, v148 offset:10880
	ds_write_b16_d16_hi v133, v148 offset:11136
	v_mul_f32_e32 v142, v58, v136
	v_mul_f32_e32 v143, v59, v136
	v_cvt_pk_bf16_f32 v142, v142, v143
	ds_write_b16 v133, v142 offset:12416
	ds_write_b16_d16_hi v133, v142 offset:12672
	v_mul_f32_e32 v144, v60, v136
	v_mul_f32_e32 v145, v61, v136
	v_cvt_pk_bf16_f32 v144, v144, v145
	ds_write_b16 v133, v144 offset:12928
	ds_write_b16_d16_hi v133, v144 offset:13184
	v_mul_f32_e32 v146, v62, v136
	v_mul_f32_e32 v147, v63, v136
	v_cvt_pk_bf16_f32 v146, v146, v147
	ds_write_b16 v133, v146 offset:14464
	ds_write_b16_d16_hi v133, v146 offset:14720
	v_mul_f32_e32 v148, v64, v136
	v_mul_f32_e32 v149, v65, v136
	v_cvt_pk_bf16_f32 v148, v148, v149
	ds_write_b16 v133, v148 offset:14976
	ds_write_b16_d16_hi v133, v148 offset:15232
	v_mul_f32_e32 v142, v18, v137
	v_mul_f32_e32 v143, v19, v137
	v_cvt_pk_bf16_f32 v142, v142, v143
	ds_write_b16 v133, v142 offset:192
	ds_write_b16_d16_hi v133, v142 offset:448
	v_mul_f32_e32 v144, v20, v137
	v_mul_f32_e32 v145, v21, v137
	v_cvt_pk_bf16_f32 v144, v144, v145
	ds_write_b16 v133, v144 offset:704
	ds_write_b16_d16_hi v133, v144 offset:960
	v_mul_f32_e32 v146, v22, v137
	v_mul_f32_e32 v147, v23, v137
	v_cvt_pk_bf16_f32 v146, v146, v147
	ds_write_b16 v133, v146 offset:2240
	ds_write_b16_d16_hi v133, v146 offset:2496
	v_mul_f32_e32 v148, v24, v137
	v_mul_f32_e32 v149, v25, v137
	v_cvt_pk_bf16_f32 v148, v148, v149
	ds_write_b16 v133, v148 offset:2752
	ds_write_b16_d16_hi v133, v148 offset:3008
	v_mul_f32_e32 v142, v26, v137
	v_mul_f32_e32 v143, v27, v137
	v_cvt_pk_bf16_f32 v142, v142, v143
	ds_write_b16 v133, v142 offset:4288
	ds_write_b16_d16_hi v133, v142 offset:4544
	v_mul_f32_e32 v144, v28, v137
	v_mul_f32_e32 v145, v29, v137
	v_cvt_pk_bf16_f32 v144, v144, v145
	ds_write_b16 v133, v144 offset:4800
	ds_write_b16_d16_hi v133, v144 offset:5056
	v_mul_f32_e32 v146, v30, v137
	v_mul_f32_e32 v147, v31, v137
	v_cvt_pk_bf16_f32 v146, v146, v147
	ds_write_b16 v133, v146 offset:6336
	ds_write_b16_d16_hi v133, v146 offset:6592
	v_mul_f32_e32 v148, v32, v137
	v_mul_f32_e32 v149, v33, v137
	v_cvt_pk_bf16_f32 v148, v148, v149
	ds_write_b16 v133, v148 offset:6848
	ds_write_b16_d16_hi v133, v148 offset:7104
	v_mul_f32_e32 v142, v2, v137
	v_mul_f32_e32 v143, v3, v137
	v_cvt_pk_bf16_f32 v142, v142, v143
	ds_write_b16 v133, v142 offset:8384
	ds_write_b16_d16_hi v133, v142 offset:8640
	v_mul_f32_e32 v144, v4, v137
	v_mul_f32_e32 v145, v5, v137
	v_cvt_pk_bf16_f32 v144, v144, v145
	ds_write_b16 v133, v144 offset:8896
	ds_write_b16_d16_hi v133, v144 offset:9152
	v_mul_f32_e32 v146, v6, v137
	v_mul_f32_e32 v147, v7, v137
	v_cvt_pk_bf16_f32 v146, v146, v147
	ds_write_b16 v133, v146 offset:10432
	ds_write_b16_d16_hi v133, v146 offset:10688
	v_mul_f32_e32 v148, v8, v137
	v_mul_f32_e32 v149, v9, v137
	v_cvt_pk_bf16_f32 v148, v148, v149
	ds_write_b16 v133, v148 offset:10944
	ds_write_b16_d16_hi v133, v148 offset:11200
	v_mul_f32_e32 v142, v10, v137
	v_mul_f32_e32 v143, v11, v137
	v_cvt_pk_bf16_f32 v142, v142, v143
	ds_write_b16 v133, v142 offset:12480
	ds_write_b16_d16_hi v133, v142 offset:12736
	v_mul_f32_e32 v144, v12, v137
	v_mul_f32_e32 v145, v13, v137
	v_cvt_pk_bf16_f32 v144, v144, v145
	ds_write_b16 v133, v144 offset:12992
	ds_write_b16_d16_hi v133, v144 offset:13248
	v_mul_f32_e32 v146, v14, v137
	v_mul_f32_e32 v147, v15, v137
	v_cvt_pk_bf16_f32 v146, v146, v147
	ds_write_b16 v133, v146 offset:14528
	ds_write_b16_d16_hi v133, v146 offset:14784
	v_mul_f32_e32 v148, v16, v137
	v_mul_f32_e32 v149, v17, v137
	v_cvt_pk_bf16_f32 v148, v148, v149
	ds_write_b16 v133, v148 offset:15040
	ds_write_b16_d16_hi v133, v148 offset:15296
	s_waitcnt lgkmcnt(0)
	ds_read_b128 v[144:147], v138 offset:0
	ds_read_b128 v[148:151], v138 offset:1024
	ds_read_b128 v[152:155], v138 offset:2048
	ds_read_b128 v[156:159], v138 offset:3072
	s_waitcnt lgkmcnt(3)
	global_store_dwordx4 v139, v[144:147], s[14:15]
	s_waitcnt lgkmcnt(2)
	v_add_u32_e32 v161, 0x8000, v139
	global_store_dwordx4 v161, v[148:151], s[14:15]
	s_waitcnt lgkmcnt(1)
	v_add_u32_e32 v162, 0x10000, v139
	global_store_dwordx4 v162, v[152:155], s[14:15]
	s_waitcnt lgkmcnt(0)
	v_add_u32_e32 v163, 0x18000, v139
	global_store_dwordx4 v163, v[156:159], s[14:15]
	s_nop 1
	ds_read_b128 v[144:147], v138 offset:4096
	ds_read_b128 v[148:151], v138 offset:5120
	ds_read_b128 v[152:155], v138 offset:6144
	ds_read_b128 v[156:159], v138 offset:7168
	s_waitcnt lgkmcnt(3)
	v_add_u32_e32 v160, 0x20000, v139
	global_store_dwordx4 v160, v[144:147], s[14:15]
	s_waitcnt lgkmcnt(2)
	v_add_u32_e32 v161, 0x28000, v139
	global_store_dwordx4 v161, v[148:151], s[14:15]
	s_waitcnt lgkmcnt(1)
	v_add_u32_e32 v162, 0x30000, v139
	global_store_dwordx4 v162, v[152:155], s[14:15]
	s_waitcnt lgkmcnt(0)
	v_add_u32_e32 v163, 0x38000, v139
	global_store_dwordx4 v163, v[156:159], s[14:15]
	s_nop 1
	ds_read_b128 v[144:147], v138 offset:8192
	ds_read_b128 v[148:151], v138 offset:9216
	ds_read_b128 v[152:155], v138 offset:10240
	ds_read_b128 v[156:159], v138 offset:11264
	s_waitcnt lgkmcnt(3)
	v_add_u32_e32 v160, 0x40000, v139
	global_store_dwordx4 v160, v[144:147], s[14:15]
	s_waitcnt lgkmcnt(2)
	v_add_u32_e32 v161, 0x48000, v139
	global_store_dwordx4 v161, v[148:151], s[14:15]
	s_waitcnt lgkmcnt(1)
	v_add_u32_e32 v162, 0x50000, v139
	global_store_dwordx4 v162, v[152:155], s[14:15]
	s_waitcnt lgkmcnt(0)
	v_add_u32_e32 v163, 0x58000, v139
	global_store_dwordx4 v163, v[156:159], s[14:15]
	s_nop 1
	ds_read_b128 v[144:147], v138 offset:12288
	ds_read_b128 v[148:151], v138 offset:13312
	ds_read_b128 v[152:155], v138 offset:14336
	ds_read_b128 v[156:159], v138 offset:15360
	s_waitcnt lgkmcnt(3)
	v_add_u32_e32 v160, 0x60000, v139
	global_store_dwordx4 v160, v[144:147], s[14:15]
	s_waitcnt lgkmcnt(2)
	v_add_u32_e32 v161, 0x68000, v139
	global_store_dwordx4 v161, v[148:151], s[14:15]
	s_waitcnt lgkmcnt(1)
	v_add_u32_e32 v162, 0x70000, v139
	global_store_dwordx4 v162, v[152:155], s[14:15]
	s_waitcnt lgkmcnt(0)
	v_add_u32_e32 v163, 0x78000, v139
	global_store_dwordx4 v163, v[156:159], s[14:15]
	s_nop 1
	s_mov_b64 s[0:1], 0
